# grid barrier: all waiters poll the cross-XCD arrival counter directly (no TOPGEN to XGEN relay hop); plus sc1 stores, no final barrier
# baseline (speedup 1.0000x reference)
.LBB0_62:
	s_waitcnt vmcnt(0)
	s_waitcnt vmcnt(0)
	s_barrier
	s_mov_b64 s[4:5], exec
	v_readlane_b32 s6, v254, 36
	v_readlane_b32 s7, v254, 37
	s_and_b64 s[6:7], s[4:5], s[6:7]
	s_mov_b64 exec, s[6:7]
	s_cbranch_execz .LBB0_114
	s_add_u32 s100, s94, 0x7400
	s_addc_u32 s101, s95, 0
	s_add_u32 s6, s94, 0x4200
	s_addc_u32 s7, s95, 0
	s_add_i32 s8, 0, 0x20160
	v_mov_b32_e32 v1, s8
	s_waitcnt vmcnt(0) expcnt(0) lgkmcnt(0)
	ds_read_b32 v3, v1
	s_add_i32 s8, 0, 0x20164
	v_mov_b32_e32 v1, s8
	ds_read_b32 v1, v1
	s_waitcnt lgkmcnt(1)
	v_cmp_ne_u32_e32 vcc, 0, v3
	s_cbranch_vccnz .LBB0_78
	s_add_u32 s8, s94, 0x4400
	s_addc_u32 s9, s95, 0
	s_add_u32 s10, s94, 0x4500
	s_addc_u32 s11, s95, 0
	s_add_u32 s12, s94, 0x4600
	s_addc_u32 s13, s95, 0
	s_add_u32 s14, s94, 0x4700
	s_addc_u32 s15, s95, 0
	s_add_u32 s16, s94, 0x4800
	s_addc_u32 s17, s95, 0
	s_add_u32 s18, s94, 0x4900
	s_addc_u32 s19, s95, 0
	s_add_u32 s20, s94, 0x4a00
	s_addc_u32 s21, s95, 0
	s_add_u32 s22, s94, 0x4b00
	s_addc_u32 s23, s95, 0
	s_add_u32 s24, s94, 0x4c00
	s_addc_u32 s25, s95, 0
	s_add_u32 s26, s94, 0x4d00
	s_addc_u32 s27, s95, 0
	s_add_u32 s28, s94, 0x4e00
	s_addc_u32 s29, s95, 0
	s_add_u32 s30, s94, 0x4f00
	s_addc_u32 s31, s95, 0
	v_readlane_b32 s38, v254, 0
	s_add_u32 s34, s94, 0x5000
	v_readlane_b32 s39, v254, 1
	s_addc_u32 s35, s95, 0
	s_load_dwordx2 s[42:43], s[38:39], 0x4
	s_add_u32 s36, s94, 0x5100
	s_addc_u32 s37, s95, 0
	s_add_u32 s38, s94, 0x5200
	s_addc_u32 s39, s95, 0
	s_add_u32 s40, s94, 0x5300
	s_waitcnt lgkmcnt(0)
	s_mul_i32 s60, s42, s90
	s_addc_u32 s41, s95, 0
	s_mul_i32 s60, s60, s43
	s_mov_b32 s61, 1
	v_mov_b32_e32 v17, 0
	s_branch .LBB0_66

.LBB0_80:
	s_or_b64 exec, exec, s[12:13]
	v_cvt_f32_u32_e32 v5, v3
	s_waitcnt vmcnt(0)
	v_readfirstlane_b32 s10, v4
	s_add_u32 s8, s8, 0x2400
	s_addc_u32 s9, s9, 0
	v_rcp_iflag_f32_e32 v5, v5
	v_add_u32_e32 v6, s10, v2
	v_mul_f32_e32 v4, 0x4f7ffffe, v5
	v_cvt_u32_f32_e32 v4, v4
	v_sub_u32_e32 v5, 0, v3
	v_mul_lo_u32 v2, v5, v4
	v_mul_hi_u32 v2, v4, v2
	v_add_u32_e32 v2, v4, v2
	v_mul_hi_u32 v2, v6, v2
	v_mul_lo_u32 v4, v2, v3
	v_sub_u32_e32 v4, v6, v4
	v_add_u32_e32 v5, 1, v2
	v_cmp_ge_u32_e32 vcc, v4, v3
	s_nop 1
	v_cndmask_b32_e32 v2, v2, v5, vcc
	v_sub_u32_e32 v5, v4, v3
	v_cndmask_b32_e32 v4, v4, v5, vcc
	v_add_u32_e32 v5, 1, v2
	v_cmp_ge_u32_e32 vcc, v4, v3
	v_add_u32_e32 v4, 1, v6
	s_nop 0
	v_cndmask_b32_e32 v2, v2, v5, vcc
	v_mul_lo_u32 v5, v3, v2
	v_add_u32_e32 v3, v5, v3
	v_cmp_ne_u32_e32 vcc, v4, v3
	s_and_saveexec_b64 s[10:11], vcc
	s_xor_b64 s[10:11], exec, s[10:11]
	s_cbranch_execz .LBB0_94
	s_waitcnt lgkmcnt(0)
	v_mul_u32_u24_e32 v18, 1, v1
	v_mov_b32_e32 v1, 0
	global_load_dword v3, v1, s[100:101] sc1
	s_waitcnt vmcnt(0)
	v_cmp_lt_u32_e32 vcc, v3, v18
	s_and_saveexec_b64 s[12:13], vcc
	s_cbranch_execz .LBB0_93
	s_mov_b32 s24, 1
	s_mov_b64 s[14:15], 0
	s_branch .LBB0_84

.LBB0_86:
	global_load_dword v3, v1, s[100:101] sc1
	s_add_i32 s24, s24, 1
	s_mov_b64 s[20:21], -1
	s_waitcnt vmcnt(0)
	v_cmp_ge_u32_e32 vcc, v3, v18
	s_orn2_b64 s[18:19], vcc, exec
	s_branch .LBB0_83

.LBB0_94:
	s_andn2_saveexec_b64 s[10:11], s[10:11]
	s_cbranch_execz .LBB0_114
	s_mov_b64 s[10:11], exec
	buffer_wbl2 sc1
	s_waitcnt lgkmcnt(0)
	v_mul_u32_u24_e32 v18, 1, v1
	s_waitcnt vmcnt(0)
	v_mbcnt_lo_u32_b32 v2, s10, 0
	v_mbcnt_hi_u32_b32 v2, s11, v2
	v_cmp_eq_u32_e32 vcc, 0, v2
	s_and_saveexec_b64 s[12:13], vcc
	s_cbranch_execz .LBB0_97
	s_bcnt1_i32_b64 s10, s[10:11]
	v_mov_b32_e32 v3, 0x7000
	v_mov_b32_e32 v4, s10
	global_atomic_add v3, v3, v4, s[94:95] offset:1024 sc0
.LBB0_97:
	s_or_b64 exec, exec, s[12:13]
	v_cvt_f32_u32_e32 v4, v1
	s_waitcnt vmcnt(0)
	v_readfirstlane_b32 s12, v3
	s_add_u32 s10, s94, 0x7500
	s_addc_u32 s11, s95, 0
	v_rcp_iflag_f32_e32 v4, v4
	v_add_u32_e32 v2, s12, v2
	s_mov_b64 s[14:15], -1
	v_mul_f32_e32 v3, 0x4f7ffffe, v4
	v_cvt_u32_f32_e32 v3, v3
	v_sub_u32_e32 v4, 0, v1
	v_mul_lo_u32 v4, v4, v3
	v_mul_hi_u32 v4, v3, v4
	v_add_u32_e32 v3, v3, v4
	v_mul_hi_u32 v3, v2, v3
	v_mul_lo_u32 v4, v3, v1
	v_sub_u32_e32 v4, v2, v4
	v_add_u32_e32 v5, 1, v3
	v_cmp_ge_u32_e32 vcc, v4, v1
	v_add_u32_e32 v2, 1, v2
	s_nop 0
	v_cndmask_b32_e32 v3, v3, v5, vcc
	v_sub_u32_e32 v5, v4, v1
	v_cndmask_b32_e32 v4, v4, v5, vcc
	v_add_u32_e32 v5, 1, v3
	v_cmp_ge_u32_e32 vcc, v4, v1
	s_nop 1
	v_cndmask_b32_e32 v4, v3, v5, vcc
	v_mul_lo_u32 v3, v1, v4
	v_add_u32_e32 v1, v3, v1
	v_cmp_ne_u32_e32 vcc, v2, v1
	v_mov_b64_e32 v[2:3], s[10:11]
	s_and_saveexec_b64 s[12:13], vcc
	s_cbranch_execz .LBB0_109
	v_mov_b32_e32 v1, 0
	global_load_dword v2, v1, s[100:101] sc1
	s_mov_b64 s[16:17], 0
	s_waitcnt vmcnt(0)
	v_cmp_lt_u32_e32 vcc, v2, v18
	s_and_saveexec_b64 s[14:15], vcc
	s_cbranch_execz .LBB0_108
	s_mov_b32 s26, 1
	s_branch .LBB0_101

.LBB0_103:
	global_load_dword v2, v1, s[100:101] sc1
	s_add_i32 s26, s26, 1
	s_mov_b64 s[20:21], -1
	s_waitcnt vmcnt(0)
	v_cmp_ge_u32_e32 vcc, v2, v18
	s_orn2_b64 s[24:25], vcc, exec
	s_branch .LBB0_100

.LBB0_156:
	s_waitcnt vmcnt(0)
	s_waitcnt vmcnt(0) lgkmcnt(0)
	s_barrier
	s_mov_b64 s[4:5], exec
	v_readlane_b32 s6, v254, 36
	v_readlane_b32 s7, v254, 37
	s_and_b64 s[6:7], s[4:5], s[6:7]
	s_mov_b64 exec, s[6:7]
	s_cbranch_execz .LBB0_208
	s_add_u32 s100, s94, 0x7400
	s_addc_u32 s101, s95, 0
	s_add_u32 s6, s94, 0x4200
	s_addc_u32 s7, s95, 0
	s_add_i32 s8, 0, 0x20160
	v_mov_b32_e32 v1, s8
	s_waitcnt vmcnt(0) expcnt(0) lgkmcnt(0)
	ds_read_b32 v3, v1
	s_add_i32 s8, 0, 0x20164
	v_mov_b32_e32 v1, s8
	ds_read_b32 v1, v1
	s_waitcnt lgkmcnt(1)
	v_cmp_ne_u32_e32 vcc, 0, v3
	s_cbranch_vccnz .LBB0_172
	s_add_u32 s8, s94, 0x4400
	s_addc_u32 s9, s95, 0
	s_add_u32 s10, s94, 0x4500
	s_addc_u32 s11, s95, 0
	s_add_u32 s12, s94, 0x4600
	s_addc_u32 s13, s95, 0
	s_add_u32 s14, s94, 0x4700
	s_addc_u32 s15, s95, 0
	s_add_u32 s16, s94, 0x4800
	s_addc_u32 s17, s95, 0
	s_add_u32 s18, s94, 0x4900
	s_addc_u32 s19, s95, 0
	s_add_u32 s20, s94, 0x4a00
	s_addc_u32 s21, s95, 0
	s_add_u32 s22, s94, 0x4b00
	s_addc_u32 s23, s95, 0
	s_add_u32 s24, s94, 0x4c00
	s_addc_u32 s25, s95, 0
	s_add_u32 s26, s94, 0x4d00
	s_addc_u32 s27, s95, 0
	s_add_u32 s28, s94, 0x4e00
	s_addc_u32 s29, s95, 0
	s_add_u32 s30, s94, 0x4f00
	s_addc_u32 s31, s95, 0
	v_readlane_b32 s38, v254, 0
	s_add_u32 s34, s94, 0x5000
	v_readlane_b32 s39, v254, 1
	s_addc_u32 s35, s95, 0
	s_load_dwordx2 s[42:43], s[38:39], 0x4
	s_add_u32 s36, s94, 0x5100
	s_addc_u32 s37, s95, 0
	s_add_u32 s38, s94, 0x5200
	s_addc_u32 s39, s95, 0
	s_add_u32 s40, s94, 0x5300
	s_waitcnt lgkmcnt(0)
	s_mul_i32 s63, s42, s90
	s_addc_u32 s41, s95, 0
	s_mul_i32 s63, s63, s43
	s_mov_b32 s64, 1
	v_mov_b32_e32 v17, 0
	s_branch .LBB0_160

.LBB0_174:
	s_or_b64 exec, exec, s[12:13]
	v_cvt_f32_u32_e32 v5, v3
	s_waitcnt vmcnt(0)
	v_readfirstlane_b32 s10, v4
	s_add_u32 s8, s8, 0x2400
	s_addc_u32 s9, s9, 0
	v_rcp_iflag_f32_e32 v5, v5
	v_add_u32_e32 v6, s10, v2
	v_mul_f32_e32 v4, 0x4f7ffffe, v5
	v_cvt_u32_f32_e32 v4, v4
	v_sub_u32_e32 v5, 0, v3
	v_mul_lo_u32 v2, v5, v4
	v_mul_hi_u32 v2, v4, v2
	v_add_u32_e32 v2, v4, v2
	v_mul_hi_u32 v2, v6, v2
	v_mul_lo_u32 v4, v2, v3
	v_sub_u32_e32 v4, v6, v4
	v_add_u32_e32 v5, 1, v2
	v_cmp_ge_u32_e32 vcc, v4, v3
	s_nop 1
	v_cndmask_b32_e32 v2, v2, v5, vcc
	v_sub_u32_e32 v5, v4, v3
	v_cndmask_b32_e32 v4, v4, v5, vcc
	v_add_u32_e32 v5, 1, v2
	v_cmp_ge_u32_e32 vcc, v4, v3
	v_add_u32_e32 v4, 1, v6
	s_nop 0
	v_cndmask_b32_e32 v2, v2, v5, vcc
	v_mul_lo_u32 v5, v3, v2
	v_add_u32_e32 v3, v5, v3
	v_cmp_ne_u32_e32 vcc, v4, v3
	s_and_saveexec_b64 s[10:11], vcc
	s_xor_b64 s[10:11], exec, s[10:11]
	s_cbranch_execz .LBB0_188
	s_waitcnt lgkmcnt(0)
	v_mul_u32_u24_e32 v18, 2, v1
	v_mov_b32_e32 v1, 0
	global_load_dword v3, v1, s[100:101] sc1
	s_waitcnt vmcnt(0)
	v_cmp_lt_u32_e32 vcc, v3, v18
	s_and_saveexec_b64 s[12:13], vcc
	s_cbranch_execz .LBB0_187
	s_mov_b32 s24, 1
	s_mov_b64 s[14:15], 0
	s_branch .LBB0_178

.LBB0_188:
	s_andn2_saveexec_b64 s[10:11], s[10:11]
	s_cbranch_execz .LBB0_208
	s_mov_b64 s[10:11], exec
	buffer_wbl2 sc1
	s_waitcnt lgkmcnt(0)
	v_mul_u32_u24_e32 v18, 2, v1
	s_waitcnt vmcnt(0)
	v_mbcnt_lo_u32_b32 v2, s10, 0
	v_mbcnt_hi_u32_b32 v2, s11, v2
	v_cmp_eq_u32_e32 vcc, 0, v2
	s_and_saveexec_b64 s[12:13], vcc
	s_cbranch_execz .LBB0_191
	s_bcnt1_i32_b64 s10, s[10:11]
	v_mov_b32_e32 v3, 0x7000
	v_mov_b32_e32 v4, s10
	global_atomic_add v3, v3, v4, s[94:95] offset:1024 sc0

.LBB0_253:
	s_waitcnt vmcnt(0)
	s_waitcnt vmcnt(0) lgkmcnt(0)
	s_barrier
	s_mov_b64 s[4:5], exec
	v_readlane_b32 s6, v254, 36
	v_readlane_b32 s7, v254, 37
	s_and_b64 s[6:7], s[4:5], s[6:7]
	s_mov_b64 exec, s[6:7]
	s_cbranch_execz .LBB0_305
	s_add_u32 s100, s94, 0x7400
	s_addc_u32 s101, s95, 0
	s_add_u32 s6, s94, 0x4200
	s_addc_u32 s7, s95, 0
	s_add_i32 s8, 0, 0x20160
	v_mov_b32_e32 v1, s8
	s_waitcnt vmcnt(0) expcnt(0) lgkmcnt(0)
	ds_read_b32 v3, v1
	s_add_i32 s8, 0, 0x20164
	v_mov_b32_e32 v1, s8
	ds_read_b32 v1, v1
	s_waitcnt lgkmcnt(1)
	v_cmp_ne_u32_e32 vcc, 0, v3
	s_cbranch_vccnz .LBB0_269
	s_add_u32 s8, s94, 0x4400
	s_addc_u32 s9, s95, 0
	s_add_u32 s10, s94, 0x4500
	s_addc_u32 s11, s95, 0
	s_add_u32 s12, s94, 0x4600
	s_addc_u32 s13, s95, 0
	s_add_u32 s14, s94, 0x4700
	s_addc_u32 s15, s95, 0
	s_add_u32 s16, s94, 0x4800
	s_addc_u32 s17, s95, 0
	s_add_u32 s18, s94, 0x4900
	s_addc_u32 s19, s95, 0
	s_add_u32 s20, s94, 0x4a00
	s_addc_u32 s21, s95, 0
	s_add_u32 s22, s94, 0x4b00
	s_addc_u32 s23, s95, 0
	s_add_u32 s24, s94, 0x4c00
	s_addc_u32 s25, s95, 0
	s_add_u32 s26, s94, 0x4d00
	s_addc_u32 s27, s95, 0
	s_add_u32 s28, s94, 0x4e00
	s_addc_u32 s29, s95, 0
	s_add_u32 s30, s94, 0x4f00
	s_addc_u32 s31, s95, 0
	v_readlane_b32 s38, v254, 0
	s_add_u32 s34, s94, 0x5000
	v_readlane_b32 s39, v254, 1
	s_addc_u32 s35, s95, 0
	s_load_dwordx2 s[42:43], s[38:39], 0x4
	s_add_u32 s36, s94, 0x5100
	s_addc_u32 s37, s95, 0
	s_add_u32 s38, s94, 0x5200
	s_addc_u32 s39, s95, 0
	s_add_u32 s40, s94, 0x5300
	s_waitcnt lgkmcnt(0)
	s_mul_i32 s63, s42, s90
	s_addc_u32 s41, s95, 0
	s_mul_i32 s63, s63, s43
	s_mov_b32 s66, 1
	v_mov_b32_e32 v17, 0
	s_branch .LBB0_257

.LBB0_271:
	s_or_b64 exec, exec, s[12:13]
	v_cvt_f32_u32_e32 v5, v3
	s_waitcnt vmcnt(0)
	v_readfirstlane_b32 s10, v4
	s_add_u32 s8, s8, 0x2400
	s_addc_u32 s9, s9, 0
	v_rcp_iflag_f32_e32 v5, v5
	v_add_u32_e32 v6, s10, v2
	v_mul_f32_e32 v4, 0x4f7ffffe, v5
	v_cvt_u32_f32_e32 v4, v4
	v_sub_u32_e32 v5, 0, v3
	v_mul_lo_u32 v2, v5, v4
	v_mul_hi_u32 v2, v4, v2
	v_add_u32_e32 v2, v4, v2
	v_mul_hi_u32 v2, v6, v2
	v_mul_lo_u32 v4, v2, v3
	v_sub_u32_e32 v4, v6, v4
	v_add_u32_e32 v5, 1, v2
	v_cmp_ge_u32_e32 vcc, v4, v3
	s_nop 1
	v_cndmask_b32_e32 v2, v2, v5, vcc
	v_sub_u32_e32 v5, v4, v3
	v_cndmask_b32_e32 v4, v4, v5, vcc
	v_add_u32_e32 v5, 1, v2
	v_cmp_ge_u32_e32 vcc, v4, v3
	v_add_u32_e32 v4, 1, v6
	s_nop 0
	v_cndmask_b32_e32 v2, v2, v5, vcc
	v_mul_lo_u32 v5, v3, v2
	v_add_u32_e32 v3, v5, v3
	v_cmp_ne_u32_e32 vcc, v4, v3
	s_and_saveexec_b64 s[10:11], vcc
	s_xor_b64 s[10:11], exec, s[10:11]
	s_cbranch_execz .LBB0_285
	s_waitcnt lgkmcnt(0)
	v_mul_u32_u24_e32 v18, 3, v1
	v_mov_b32_e32 v1, 0
	global_load_dword v3, v1, s[100:101] sc1
	s_waitcnt vmcnt(0)
	v_cmp_lt_u32_e32 vcc, v3, v18
	s_and_saveexec_b64 s[12:13], vcc
	s_cbranch_execz .LBB0_284
	s_mov_b32 s24, 1
	s_mov_b64 s[14:15], 0
	s_branch .LBB0_275

.LBB0_285:
	s_andn2_saveexec_b64 s[10:11], s[10:11]
	s_cbranch_execz .LBB0_305
	s_mov_b64 s[10:11], exec
	buffer_wbl2 sc1
	s_waitcnt lgkmcnt(0)
	v_mul_u32_u24_e32 v18, 3, v1
	s_waitcnt vmcnt(0)
	v_mbcnt_lo_u32_b32 v2, s10, 0
	v_mbcnt_hi_u32_b32 v2, s11, v2
	v_cmp_eq_u32_e32 vcc, 0, v2
	s_and_saveexec_b64 s[12:13], vcc
	s_cbranch_execz .LBB0_288
	s_bcnt1_i32_b64 s10, s[10:11]
	v_mov_b32_e32 v3, 0x7000
	v_mov_b32_e32 v4, s10
	global_atomic_add v3, v3, v4, s[94:95] offset:1024 sc0

.LBB0_325:
	s_waitcnt vmcnt(0)
	s_waitcnt vmcnt(0)
	s_barrier
	s_mov_b64 s[4:5], exec
	v_readlane_b32 s6, v254, 36
	v_readlane_b32 s7, v254, 37
	s_and_b64 s[6:7], s[4:5], s[6:7]
	s_mov_b64 exec, s[6:7]
	s_cbranch_execz .LBB0_377
	s_add_u32 s100, s94, 0x7400
	s_addc_u32 s101, s95, 0
	s_add_u32 s6, s94, 0x4200
	s_addc_u32 s7, s95, 0
	s_add_i32 s8, 0, 0x20160
	v_mov_b32_e32 v1, s8
	s_waitcnt vmcnt(0) expcnt(0) lgkmcnt(0)
	ds_read_b32 v3, v1
	s_add_i32 s8, 0, 0x20164
	v_mov_b32_e32 v1, s8
	ds_read_b32 v1, v1
	s_waitcnt lgkmcnt(1)
	v_cmp_ne_u32_e32 vcc, 0, v3
	s_cbranch_vccnz .LBB0_341
	s_add_u32 s8, s94, 0x4400
	s_addc_u32 s9, s95, 0
	s_add_u32 s10, s94, 0x4500
	s_addc_u32 s11, s95, 0
	s_add_u32 s12, s94, 0x4600
	s_addc_u32 s13, s95, 0
	s_add_u32 s14, s94, 0x4700
	s_addc_u32 s15, s95, 0
	s_add_u32 s16, s94, 0x4800
	s_addc_u32 s17, s95, 0
	s_add_u32 s18, s94, 0x4900
	s_addc_u32 s19, s95, 0
	s_add_u32 s20, s94, 0x4a00
	s_addc_u32 s21, s95, 0
	s_add_u32 s22, s94, 0x4b00
	s_addc_u32 s23, s95, 0
	s_add_u32 s24, s94, 0x4c00
	s_addc_u32 s25, s95, 0
	s_add_u32 s26, s94, 0x4d00
	s_addc_u32 s27, s95, 0
	s_add_u32 s28, s94, 0x4e00
	s_addc_u32 s29, s95, 0
	s_add_u32 s30, s94, 0x4f00
	s_addc_u32 s31, s95, 0
	v_readlane_b32 s38, v254, 0
	s_add_u32 s34, s94, 0x5000
	v_readlane_b32 s39, v254, 1
	s_addc_u32 s35, s95, 0
	s_load_dwordx2 s[42:43], s[38:39], 0x4
	s_add_u32 s36, s94, 0x5100
	s_addc_u32 s37, s95, 0
	s_add_u32 s38, s94, 0x5200
	s_addc_u32 s39, s95, 0
	s_add_u32 s40, s94, 0x5300
	s_waitcnt lgkmcnt(0)
	s_mul_i32 s63, s42, s90
	s_addc_u32 s41, s95, 0
	s_mul_i32 s63, s63, s43
	s_mov_b32 s66, 1
	v_mov_b32_e32 v17, 0
	s_branch .LBB0_329

.LBB0_343:
	s_or_b64 exec, exec, s[12:13]
	v_cvt_f32_u32_e32 v5, v3
	s_waitcnt vmcnt(0)
	v_readfirstlane_b32 s10, v4
	s_add_u32 s8, s8, 0x2400
	s_addc_u32 s9, s9, 0
	v_rcp_iflag_f32_e32 v5, v5
	v_add_u32_e32 v6, s10, v2
	v_mul_f32_e32 v4, 0x4f7ffffe, v5
	v_cvt_u32_f32_e32 v4, v4
	v_sub_u32_e32 v5, 0, v3
	v_mul_lo_u32 v2, v5, v4
	v_mul_hi_u32 v2, v4, v2
	v_add_u32_e32 v2, v4, v2
	v_mul_hi_u32 v2, v6, v2
	v_mul_lo_u32 v4, v2, v3
	v_sub_u32_e32 v4, v6, v4
	v_add_u32_e32 v5, 1, v2
	v_cmp_ge_u32_e32 vcc, v4, v3
	s_nop 1
	v_cndmask_b32_e32 v2, v2, v5, vcc
	v_sub_u32_e32 v5, v4, v3
	v_cndmask_b32_e32 v4, v4, v5, vcc
	v_add_u32_e32 v5, 1, v2
	v_cmp_ge_u32_e32 vcc, v4, v3
	v_add_u32_e32 v4, 1, v6
	s_nop 0
	v_cndmask_b32_e32 v2, v2, v5, vcc
	v_mul_lo_u32 v5, v3, v2
	v_add_u32_e32 v3, v5, v3
	v_cmp_ne_u32_e32 vcc, v4, v3
	s_and_saveexec_b64 s[10:11], vcc
	s_xor_b64 s[10:11], exec, s[10:11]
	s_cbranch_execz .LBB0_357
	s_waitcnt lgkmcnt(0)
	v_mul_u32_u24_e32 v18, 4, v1
	v_mov_b32_e32 v1, 0
	global_load_dword v3, v1, s[100:101] sc1
	s_waitcnt vmcnt(0)
	v_cmp_lt_u32_e32 vcc, v3, v18
	s_and_saveexec_b64 s[12:13], vcc
	s_cbranch_execz .LBB0_356
	s_mov_b32 s24, 1
	s_mov_b64 s[14:15], 0
	s_branch .LBB0_347

.LBB0_357:
	s_andn2_saveexec_b64 s[10:11], s[10:11]
	s_cbranch_execz .LBB0_377
	s_mov_b64 s[10:11], exec
	buffer_wbl2 sc1
	s_waitcnt lgkmcnt(0)
	v_mul_u32_u24_e32 v18, 4, v1
	s_waitcnt vmcnt(0)
	v_mbcnt_lo_u32_b32 v2, s10, 0
	v_mbcnt_hi_u32_b32 v2, s11, v2
	v_cmp_eq_u32_e32 vcc, 0, v2
	s_and_saveexec_b64 s[12:13], vcc
	s_cbranch_execz .LBB0_360
	s_bcnt1_i32_b64 s10, s[10:11]
	v_mov_b32_e32 v3, 0x7000
	v_mov_b32_e32 v4, s10
	global_atomic_add v3, v3, v4, s[94:95] offset:1024 sc0

.LBB0_424:
	s_waitcnt vmcnt(0)
	s_waitcnt vmcnt(0)
	s_barrier
	s_mov_b64 s[4:5], exec
	v_readlane_b32 s6, v254, 36
	v_readlane_b32 s7, v254, 37
	s_and_b64 s[6:7], s[4:5], s[6:7]
	s_mov_b64 exec, s[6:7]
	s_cbranch_execz .LBB0_476
	s_add_u32 s100, s94, 0x7400
	s_addc_u32 s101, s95, 0
	s_add_u32 s6, s94, 0x4200
	s_addc_u32 s7, s95, 0
	s_add_i32 s8, 0, 0x20160
	v_mov_b32_e32 v1, s8
	s_waitcnt vmcnt(0) expcnt(0) lgkmcnt(0)
	ds_read_b32 v3, v1
	s_add_i32 s8, 0, 0x20164
	v_mov_b32_e32 v1, s8
	ds_read_b32 v1, v1
	s_waitcnt lgkmcnt(1)
	v_cmp_ne_u32_e32 vcc, 0, v3
	s_cbranch_vccnz .LBB0_440
	s_add_u32 s8, s94, 0x4400
	s_addc_u32 s9, s95, 0
	s_add_u32 s10, s94, 0x4500
	s_addc_u32 s11, s95, 0
	s_add_u32 s12, s94, 0x4600
	s_addc_u32 s13, s95, 0
	s_add_u32 s14, s94, 0x4700
	s_addc_u32 s15, s95, 0
	s_add_u32 s16, s94, 0x4800
	s_addc_u32 s17, s95, 0
	s_add_u32 s18, s94, 0x4900
	s_addc_u32 s19, s95, 0
	s_add_u32 s20, s94, 0x4a00
	s_addc_u32 s21, s95, 0
	s_add_u32 s22, s94, 0x4b00
	s_addc_u32 s23, s95, 0
	s_add_u32 s24, s94, 0x4c00
	s_addc_u32 s25, s95, 0
	s_add_u32 s26, s94, 0x4d00
	s_addc_u32 s27, s95, 0
	s_add_u32 s28, s94, 0x4e00
	s_addc_u32 s29, s95, 0
	s_add_u32 s30, s94, 0x4f00
	s_addc_u32 s31, s95, 0
	v_readlane_b32 s38, v254, 0
	s_add_u32 s34, s94, 0x5000
	v_readlane_b32 s39, v254, 1
	s_addc_u32 s35, s95, 0
	s_load_dwordx2 s[46:47], s[38:39], 0x4
	s_add_u32 s36, s94, 0x5100
	s_addc_u32 s37, s95, 0
	s_add_u32 s38, s94, 0x5200
	s_addc_u32 s39, s95, 0
	s_add_u32 s40, s94, 0x5300
	s_waitcnt lgkmcnt(0)
	s_mul_i32 s63, s46, s90
	s_addc_u32 s41, s95, 0
	s_mul_i32 s63, s63, s47
	s_mov_b32 s68, 1
	v_mov_b32_e32 v17, 0
	s_branch .LBB0_428

.LBB0_442:
	s_or_b64 exec, exec, s[12:13]
	v_cvt_f32_u32_e32 v5, v3
	s_waitcnt vmcnt(0)
	v_readfirstlane_b32 s10, v4
	s_add_u32 s8, s8, 0x2400
	s_addc_u32 s9, s9, 0
	v_rcp_iflag_f32_e32 v5, v5
	v_add_u32_e32 v6, s10, v2
	v_mul_f32_e32 v4, 0x4f7ffffe, v5
	v_cvt_u32_f32_e32 v4, v4
	v_sub_u32_e32 v5, 0, v3
	v_mul_lo_u32 v2, v5, v4
	v_mul_hi_u32 v2, v4, v2
	v_add_u32_e32 v2, v4, v2
	v_mul_hi_u32 v2, v6, v2
	v_mul_lo_u32 v4, v2, v3
	v_sub_u32_e32 v4, v6, v4
	v_add_u32_e32 v5, 1, v2
	v_cmp_ge_u32_e32 vcc, v4, v3
	s_nop 1
	v_cndmask_b32_e32 v2, v2, v5, vcc
	v_sub_u32_e32 v5, v4, v3
	v_cndmask_b32_e32 v4, v4, v5, vcc
	v_add_u32_e32 v5, 1, v2
	v_cmp_ge_u32_e32 vcc, v4, v3
	v_add_u32_e32 v4, 1, v6
	s_nop 0
	v_cndmask_b32_e32 v2, v2, v5, vcc
	v_mul_lo_u32 v5, v3, v2
	v_add_u32_e32 v3, v5, v3
	v_cmp_ne_u32_e32 vcc, v4, v3
	s_and_saveexec_b64 s[10:11], vcc
	s_xor_b64 s[10:11], exec, s[10:11]
	s_cbranch_execz .LBB0_456
	s_waitcnt lgkmcnt(0)
	v_mul_u32_u24_e32 v18, 5, v1
	v_mov_b32_e32 v1, 0
	global_load_dword v3, v1, s[100:101] sc1
	s_waitcnt vmcnt(0)
	v_cmp_lt_u32_e32 vcc, v3, v18
	s_and_saveexec_b64 s[12:13], vcc
	s_cbranch_execz .LBB0_455
	s_mov_b32 s24, 1
	s_mov_b64 s[14:15], 0
	s_branch .LBB0_446

.LBB0_456:
	s_andn2_saveexec_b64 s[10:11], s[10:11]
	s_cbranch_execz .LBB0_476
	s_mov_b64 s[10:11], exec
	buffer_wbl2 sc1
	s_waitcnt lgkmcnt(0)
	v_mul_u32_u24_e32 v18, 5, v1
	s_waitcnt vmcnt(0)
	v_mbcnt_lo_u32_b32 v2, s10, 0
	v_mbcnt_hi_u32_b32 v2, s11, v2
	v_cmp_eq_u32_e32 vcc, 0, v2
	s_and_saveexec_b64 s[12:13], vcc
	s_cbranch_execz .LBB0_459
	s_bcnt1_i32_b64 s10, s[10:11]
	v_mov_b32_e32 v3, 0x7000
	v_mov_b32_e32 v4, s10
	global_atomic_add v3, v3, v4, s[94:95] offset:1024 sc0

.LBB0_501:
	s_waitcnt vmcnt(0)
	s_waitcnt vmcnt(0)
	s_barrier
	s_mov_b64 s[4:5], exec
	v_readlane_b32 s6, v254, 36
	v_readlane_b32 s7, v254, 37
	s_and_b64 s[6:7], s[4:5], s[6:7]
	s_mov_b32 s86, s54
	s_mov_b32 s87, s55
	s_mov_b64 exec, s[6:7]
	s_cbranch_execz .LBB0_553
	s_add_u32 s100, s94, 0x7400
	s_addc_u32 s101, s95, 0
	s_add_u32 s6, s94, 0x4200
	s_addc_u32 s7, s95, 0
	s_add_i32 s8, 0, 0x20160
	v_mov_b32_e32 v1, s8
	s_waitcnt vmcnt(0) expcnt(0) lgkmcnt(0)
	ds_read_b32 v3, v1
	s_add_i32 s8, 0, 0x20164
	v_mov_b32_e32 v1, s8
	ds_read_b32 v1, v1
	s_waitcnt lgkmcnt(1)
	v_cmp_ne_u32_e32 vcc, 0, v3
	s_cbranch_vccnz .LBB0_517
	s_add_u32 s8, s94, 0x4400
	s_addc_u32 s9, s95, 0
	s_add_u32 s10, s94, 0x4500
	s_addc_u32 s11, s95, 0
	s_add_u32 s12, s94, 0x4600
	s_addc_u32 s13, s95, 0
	s_add_u32 s14, s94, 0x4700
	s_addc_u32 s15, s95, 0
	s_add_u32 s16, s94, 0x4800
	s_addc_u32 s17, s95, 0
	s_add_u32 s18, s94, 0x4900
	s_addc_u32 s19, s95, 0
	s_add_u32 s20, s94, 0x4a00
	s_addc_u32 s21, s95, 0
	s_add_u32 s22, s94, 0x4b00
	s_addc_u32 s23, s95, 0
	s_add_u32 s24, s94, 0x4c00
	s_addc_u32 s25, s95, 0
	s_add_u32 s26, s94, 0x4d00
	s_addc_u32 s27, s95, 0
	s_add_u32 s28, s94, 0x4e00
	s_addc_u32 s29, s95, 0
	s_add_u32 s30, s94, 0x4f00
	s_addc_u32 s31, s95, 0
	v_readlane_b32 s38, v254, 0
	s_add_u32 s34, s94, 0x5000
	v_readlane_b32 s39, v254, 1
	s_addc_u32 s35, s95, 0
	s_load_dwordx2 s[42:43], s[38:39], 0x4
	s_add_u32 s36, s94, 0x5100
	s_addc_u32 s37, s95, 0
	s_add_u32 s38, s94, 0x5200
	s_addc_u32 s39, s95, 0
	s_add_u32 s40, s94, 0x5300
	s_waitcnt lgkmcnt(0)
	s_mul_i32 s48, s42, s90
	s_addc_u32 s41, s95, 0
	s_mul_i32 s48, s48, s43
	s_mov_b32 s49, 1
	v_mov_b32_e32 v17, 0
	s_branch .LBB0_505

.LBB0_519:
	s_or_b64 exec, exec, s[12:13]
	v_cvt_f32_u32_e32 v5, v3
	s_waitcnt vmcnt(0)
	v_readfirstlane_b32 s10, v4
	s_add_u32 s8, s8, 0x2400
	s_addc_u32 s9, s9, 0
	v_rcp_iflag_f32_e32 v5, v5
	v_add_u32_e32 v6, s10, v2
	v_mul_f32_e32 v4, 0x4f7ffffe, v5
	v_cvt_u32_f32_e32 v4, v4
	v_sub_u32_e32 v5, 0, v3
	v_mul_lo_u32 v2, v5, v4
	v_mul_hi_u32 v2, v4, v2
	v_add_u32_e32 v2, v4, v2
	v_mul_hi_u32 v2, v6, v2
	v_mul_lo_u32 v4, v2, v3
	v_sub_u32_e32 v4, v6, v4
	v_add_u32_e32 v5, 1, v2
	v_cmp_ge_u32_e32 vcc, v4, v3
	s_nop 1
	v_cndmask_b32_e32 v2, v2, v5, vcc
	v_sub_u32_e32 v5, v4, v3
	v_cndmask_b32_e32 v4, v4, v5, vcc
	v_add_u32_e32 v5, 1, v2
	v_cmp_ge_u32_e32 vcc, v4, v3
	v_add_u32_e32 v4, 1, v6
	s_nop 0
	v_cndmask_b32_e32 v2, v2, v5, vcc
	v_mul_lo_u32 v5, v3, v2
	v_add_u32_e32 v3, v5, v3
	v_cmp_ne_u32_e32 vcc, v4, v3
	s_and_saveexec_b64 s[10:11], vcc
	s_xor_b64 s[10:11], exec, s[10:11]
	s_cbranch_execz .LBB0_533
	s_waitcnt lgkmcnt(0)
	v_mul_u32_u24_e32 v18, 6, v1
	v_mov_b32_e32 v1, 0
	global_load_dword v3, v1, s[100:101] sc1
	s_waitcnt vmcnt(0)
	v_cmp_lt_u32_e32 vcc, v3, v18
	s_and_saveexec_b64 s[12:13], vcc
	s_cbranch_execz .LBB0_532
	s_mov_b32 s24, 1
	s_mov_b64 s[14:15], 0
	s_branch .LBB0_523

.LBB0_533:
	s_andn2_saveexec_b64 s[10:11], s[10:11]
	s_cbranch_execz .LBB0_553
	s_mov_b64 s[10:11], exec
	buffer_wbl2 sc1
	s_waitcnt lgkmcnt(0)
	v_mul_u32_u24_e32 v18, 6, v1
	s_waitcnt vmcnt(0)
	v_mbcnt_lo_u32_b32 v2, s10, 0
	v_mbcnt_hi_u32_b32 v2, s11, v2
	v_cmp_eq_u32_e32 vcc, 0, v2
	s_and_saveexec_b64 s[12:13], vcc
	s_cbranch_execz .LBB0_536
	s_bcnt1_i32_b64 s10, s[10:11]
	v_mov_b32_e32 v3, 0x7000
	v_mov_b32_e32 v4, s10
	global_atomic_add v3, v3, v4, s[94:95] offset:1024 sc0

.LBB0_582:
	s_waitcnt vmcnt(0)
	s_waitcnt vmcnt(0) lgkmcnt(0)
	s_barrier
	s_mov_b64 s[4:5], exec
	v_readlane_b32 s6, v254, 36
	v_readlane_b32 s7, v254, 37
	s_and_b64 s[6:7], s[4:5], s[6:7]
	s_mov_b64 exec, s[6:7]
	s_cbranch_execz .LBB0_634
	s_add_u32 s100, s94, 0x7400
	s_addc_u32 s101, s95, 0
	s_add_u32 s6, s94, 0x4200
	s_addc_u32 s7, s95, 0
	s_add_i32 s8, 0, 0x20160
	v_mov_b32_e32 v1, s8
	s_waitcnt vmcnt(0) expcnt(0) lgkmcnt(0)
	ds_read_b32 v3, v1
	s_add_i32 s8, 0, 0x20164
	v_mov_b32_e32 v1, s8
	ds_read_b32 v1, v1
	s_waitcnt lgkmcnt(1)
	v_cmp_ne_u32_e32 vcc, 0, v3
	s_cbranch_vccnz .LBB0_598
	s_add_u32 s8, s94, 0x4400
	s_addc_u32 s9, s95, 0
	s_add_u32 s10, s94, 0x4500
	s_addc_u32 s11, s95, 0
	s_add_u32 s12, s94, 0x4600
	s_addc_u32 s13, s95, 0
	s_add_u32 s14, s94, 0x4700
	s_addc_u32 s15, s95, 0
	s_add_u32 s16, s94, 0x4800
	s_addc_u32 s17, s95, 0
	s_add_u32 s18, s94, 0x4900
	s_addc_u32 s19, s95, 0
	s_add_u32 s20, s94, 0x4a00
	s_addc_u32 s21, s95, 0
	s_add_u32 s22, s94, 0x4b00
	s_addc_u32 s23, s95, 0
	s_add_u32 s24, s94, 0x4c00
	s_addc_u32 s25, s95, 0
	s_add_u32 s26, s94, 0x4d00
	s_addc_u32 s27, s95, 0
	s_add_u32 s28, s94, 0x4e00
	s_addc_u32 s29, s95, 0
	s_add_u32 s30, s94, 0x4f00
	s_addc_u32 s31, s95, 0
	v_readlane_b32 s38, v254, 0
	s_add_u32 s34, s94, 0x5000
	v_readlane_b32 s39, v254, 1
	s_addc_u32 s35, s95, 0
	s_load_dwordx2 s[42:43], s[38:39], 0x4
	s_add_u32 s36, s94, 0x5100
	s_addc_u32 s37, s95, 0
	s_add_u32 s38, s94, 0x5200
	s_addc_u32 s39, s95, 0
	s_add_u32 s40, s94, 0x5300
	s_waitcnt lgkmcnt(0)
	s_mul_i32 s48, s42, s90
	s_addc_u32 s41, s95, 0
	s_mul_i32 s48, s48, s43
	s_mov_b32 s49, 1
	v_mov_b32_e32 v17, 0
	s_branch .LBB0_586

.LBB0_600:
	s_or_b64 exec, exec, s[12:13]
	v_cvt_f32_u32_e32 v5, v3
	s_waitcnt vmcnt(0)
	v_readfirstlane_b32 s10, v4
	s_add_u32 s8, s8, 0x2400
	s_addc_u32 s9, s9, 0
	v_rcp_iflag_f32_e32 v5, v5
	v_add_u32_e32 v6, s10, v2
	v_mul_f32_e32 v4, 0x4f7ffffe, v5
	v_cvt_u32_f32_e32 v4, v4
	v_sub_u32_e32 v5, 0, v3
	v_mul_lo_u32 v2, v5, v4
	v_mul_hi_u32 v2, v4, v2
	v_add_u32_e32 v2, v4, v2
	v_mul_hi_u32 v2, v6, v2
	v_mul_lo_u32 v4, v2, v3
	v_sub_u32_e32 v4, v6, v4
	v_add_u32_e32 v5, 1, v2
	v_cmp_ge_u32_e32 vcc, v4, v3
	s_nop 1
	v_cndmask_b32_e32 v2, v2, v5, vcc
	v_sub_u32_e32 v5, v4, v3
	v_cndmask_b32_e32 v4, v4, v5, vcc
	v_add_u32_e32 v5, 1, v2
	v_cmp_ge_u32_e32 vcc, v4, v3
	v_add_u32_e32 v4, 1, v6
	s_nop 0
	v_cndmask_b32_e32 v2, v2, v5, vcc
	v_mul_lo_u32 v5, v3, v2
	v_add_u32_e32 v3, v5, v3
	v_cmp_ne_u32_e32 vcc, v4, v3
	s_and_saveexec_b64 s[10:11], vcc
	s_xor_b64 s[10:11], exec, s[10:11]
	s_cbranch_execz .LBB0_614
	s_waitcnt lgkmcnt(0)
	v_mul_u32_u24_e32 v18, 7, v1
	v_mov_b32_e32 v1, 0
	global_load_dword v3, v1, s[100:101] sc1
	s_waitcnt vmcnt(0)
	v_cmp_lt_u32_e32 vcc, v3, v18
	s_and_saveexec_b64 s[12:13], vcc
	s_cbranch_execz .LBB0_613
	s_mov_b32 s24, 1
	s_mov_b64 s[14:15], 0
	s_branch .LBB0_604

.LBB0_614:
	s_andn2_saveexec_b64 s[10:11], s[10:11]
	s_cbranch_execz .LBB0_634
	s_mov_b64 s[10:11], exec
	buffer_wbl2 sc1
	s_waitcnt lgkmcnt(0)
	v_mul_u32_u24_e32 v18, 7, v1
	s_waitcnt vmcnt(0)
	v_mbcnt_lo_u32_b32 v2, s10, 0
	v_mbcnt_hi_u32_b32 v2, s11, v2
	v_cmp_eq_u32_e32 vcc, 0, v2
	s_and_saveexec_b64 s[12:13], vcc
	s_cbranch_execz .LBB0_617
	s_bcnt1_i32_b64 s10, s[10:11]
	v_mov_b32_e32 v3, 0x7000
	v_mov_b32_e32 v4, s10
	global_atomic_add v3, v3, v4, s[94:95] offset:1024 sc0

.LBB0_662:
	s_waitcnt vmcnt(0)
	s_waitcnt vmcnt(0)
	s_barrier
	s_mov_b64 s[4:5], exec
	v_readlane_b32 s6, v254, 36
	v_readlane_b32 s7, v254, 37
	s_and_b64 s[6:7], s[4:5], s[6:7]
	s_mov_b64 exec, s[6:7]
	s_cbranch_execz .LBB0_714
	s_add_u32 s100, s94, 0x7400
	s_addc_u32 s101, s95, 0
	s_add_u32 s6, s94, 0x4200
	s_addc_u32 s7, s95, 0
	s_add_i32 s8, 0, 0x20160
	v_mov_b32_e32 v1, s8
	s_waitcnt vmcnt(0) expcnt(0) lgkmcnt(0)
	ds_read_b32 v3, v1
	s_add_i32 s8, 0, 0x20164
	v_mov_b32_e32 v1, s8
	ds_read_b32 v1, v1
	s_waitcnt lgkmcnt(1)
	v_cmp_ne_u32_e32 vcc, 0, v3
	s_cbranch_vccnz .LBB0_678
	s_add_u32 s8, s94, 0x4400
	s_addc_u32 s9, s95, 0
	s_add_u32 s10, s94, 0x4500
	s_addc_u32 s11, s95, 0
	s_add_u32 s12, s94, 0x4600
	s_addc_u32 s13, s95, 0
	s_add_u32 s14, s94, 0x4700
	s_addc_u32 s15, s95, 0
	s_add_u32 s16, s94, 0x4800
	s_addc_u32 s17, s95, 0
	s_add_u32 s18, s94, 0x4900
	s_addc_u32 s19, s95, 0
	s_add_u32 s20, s94, 0x4a00
	s_addc_u32 s21, s95, 0
	s_add_u32 s22, s94, 0x4b00
	s_addc_u32 s23, s95, 0
	s_add_u32 s24, s94, 0x4c00
	s_addc_u32 s25, s95, 0
	s_add_u32 s26, s94, 0x4d00
	s_addc_u32 s27, s95, 0
	s_add_u32 s28, s94, 0x4e00
	s_addc_u32 s29, s95, 0
	s_add_u32 s30, s94, 0x4f00
	s_addc_u32 s31, s95, 0
	v_readlane_b32 s38, v254, 0
	s_add_u32 s34, s94, 0x5000
	v_readlane_b32 s39, v254, 1
	s_addc_u32 s35, s95, 0
	s_load_dwordx2 s[42:43], s[38:39], 0x4
	s_add_u32 s36, s94, 0x5100
	s_addc_u32 s37, s95, 0
	s_add_u32 s38, s94, 0x5200
	s_addc_u32 s39, s95, 0
	s_add_u32 s40, s94, 0x5300
	s_waitcnt lgkmcnt(0)
	s_mul_i32 s48, s42, s90
	s_addc_u32 s41, s95, 0
	s_mul_i32 s48, s48, s43
	s_mov_b32 s49, 1
	v_mov_b32_e32 v17, 0
	s_branch .LBB0_666

.LBB0_680:
	s_or_b64 exec, exec, s[12:13]
	v_cvt_f32_u32_e32 v5, v3
	s_waitcnt vmcnt(0)
	v_readfirstlane_b32 s10, v4
	s_add_u32 s8, s8, 0x2400
	s_addc_u32 s9, s9, 0
	v_rcp_iflag_f32_e32 v5, v5
	v_add_u32_e32 v6, s10, v2
	v_mul_f32_e32 v4, 0x4f7ffffe, v5
	v_cvt_u32_f32_e32 v4, v4
	v_sub_u32_e32 v5, 0, v3
	v_mul_lo_u32 v2, v5, v4
	v_mul_hi_u32 v2, v4, v2
	v_add_u32_e32 v2, v4, v2
	v_mul_hi_u32 v2, v6, v2
	v_mul_lo_u32 v4, v2, v3
	v_sub_u32_e32 v4, v6, v4
	v_add_u32_e32 v5, 1, v2
	v_cmp_ge_u32_e32 vcc, v4, v3
	s_nop 1
	v_cndmask_b32_e32 v2, v2, v5, vcc
	v_sub_u32_e32 v5, v4, v3
	v_cndmask_b32_e32 v4, v4, v5, vcc
	v_add_u32_e32 v5, 1, v2
	v_cmp_ge_u32_e32 vcc, v4, v3
	v_add_u32_e32 v4, 1, v6
	s_nop 0
	v_cndmask_b32_e32 v2, v2, v5, vcc
	v_mul_lo_u32 v5, v3, v2
	v_add_u32_e32 v3, v5, v3
	v_cmp_ne_u32_e32 vcc, v4, v3
	s_and_saveexec_b64 s[10:11], vcc
	s_xor_b64 s[10:11], exec, s[10:11]
	s_cbranch_execz .LBB0_694
	s_waitcnt lgkmcnt(0)
	v_mul_u32_u24_e32 v18, 8, v1
	v_mov_b32_e32 v1, 0
	global_load_dword v3, v1, s[100:101] sc1
	s_waitcnt vmcnt(0)
	v_cmp_lt_u32_e32 vcc, v3, v18
	s_and_saveexec_b64 s[12:13], vcc
	s_cbranch_execz .LBB0_693
	s_mov_b32 s24, 1
	s_mov_b64 s[14:15], 0
	s_branch .LBB0_684

.LBB0_694:
	s_andn2_saveexec_b64 s[10:11], s[10:11]
	s_cbranch_execz .LBB0_714
	s_mov_b64 s[10:11], exec
	buffer_wbl2 sc1
	s_waitcnt lgkmcnt(0)
	v_mul_u32_u24_e32 v18, 8, v1
	s_waitcnt vmcnt(0)
	v_mbcnt_lo_u32_b32 v2, s10, 0
	v_mbcnt_hi_u32_b32 v2, s11, v2
	v_cmp_eq_u32_e32 vcc, 0, v2
	s_and_saveexec_b64 s[12:13], vcc
	s_cbranch_execz .LBB0_697
	s_bcnt1_i32_b64 s10, s[10:11]
	v_mov_b32_e32 v3, 0x7000
	v_mov_b32_e32 v4, s10
	global_atomic_add v3, v3, v4, s[94:95] offset:1024 sc0

.LBB0_774:
	s_or_b64 exec, exec, s[12:13]
	v_cvt_f32_u32_e32 v5, v3
	s_waitcnt vmcnt(0)
	v_readfirstlane_b32 s10, v4
	s_add_u32 s8, s8, 0x2400
	s_addc_u32 s9, s9, 0
	v_rcp_iflag_f32_e32 v5, v5
	v_add_u32_e32 v6, s10, v2
	v_mul_f32_e32 v4, 0x4f7ffffe, v5
	v_cvt_u32_f32_e32 v4, v4
	v_sub_u32_e32 v5, 0, v3
	v_mul_lo_u32 v2, v5, v4
	v_mul_hi_u32 v2, v4, v2
	v_add_u32_e32 v2, v4, v2
	v_mul_hi_u32 v2, v6, v2
	v_mul_lo_u32 v4, v2, v3
	v_sub_u32_e32 v4, v6, v4
	v_add_u32_e32 v5, 1, v2
	v_cmp_ge_u32_e32 vcc, v4, v3
	s_nop 1
	v_cndmask_b32_e32 v2, v2, v5, vcc
	v_sub_u32_e32 v5, v4, v3
	v_cndmask_b32_e32 v4, v4, v5, vcc
	v_add_u32_e32 v5, 1, v2
	v_cmp_ge_u32_e32 vcc, v4, v3
	v_add_u32_e32 v4, 1, v6
	s_nop 0
	v_cndmask_b32_e32 v2, v2, v5, vcc
	v_mul_lo_u32 v5, v3, v2
	v_add_u32_e32 v3, v5, v3
	v_cmp_ne_u32_e32 vcc, v4, v3
	s_and_saveexec_b64 s[10:11], vcc
	s_xor_b64 s[10:11], exec, s[10:11]
	s_cbranch_execz .LBB0_788
	s_waitcnt lgkmcnt(0)
	v_mul_u32_u24_e32 v18, 9, v1
	v_mov_b32_e32 v1, 0
	global_load_dword v3, v1, s[100:101] sc1
	s_waitcnt vmcnt(0)
	v_cmp_lt_u32_e32 vcc, v3, v18
	s_and_saveexec_b64 s[12:13], vcc
	s_cbranch_execz .LBB0_787
	s_mov_b32 s24, 1
	s_mov_b64 s[14:15], 0
	s_branch .LBB0_778

.LBB0_788:
	s_andn2_saveexec_b64 s[10:11], s[10:11]
	s_cbranch_execz .LBB0_808
	s_mov_b64 s[10:11], exec
	buffer_wbl2 sc1
	s_waitcnt lgkmcnt(0)
	v_mul_u32_u24_e32 v18, 9, v1
	s_waitcnt vmcnt(0)
	v_mbcnt_lo_u32_b32 v2, s10, 0
	v_mbcnt_hi_u32_b32 v2, s11, v2
	v_cmp_eq_u32_e32 vcc, 0, v2
	s_and_saveexec_b64 s[12:13], vcc
	s_cbranch_execz .LBB0_791
	s_bcnt1_i32_b64 s10, s[10:11]
	v_mov_b32_e32 v3, 0x7000
	v_mov_b32_e32 v4, s10
	global_atomic_add v3, v3, v4, s[94:95] offset:1024 sc0

.LBB0_871:
	s_or_b64 exec, exec, s[12:13]
	v_cvt_f32_u32_e32 v5, v3
	s_waitcnt vmcnt(0)
	v_readfirstlane_b32 s10, v4
	s_add_u32 s8, s8, 0x2400
	s_addc_u32 s9, s9, 0
	v_rcp_iflag_f32_e32 v5, v5
	v_add_u32_e32 v6, s10, v2
	v_mul_f32_e32 v4, 0x4f7ffffe, v5
	v_cvt_u32_f32_e32 v4, v4
	v_sub_u32_e32 v5, 0, v3
	v_mul_lo_u32 v2, v5, v4
	v_mul_hi_u32 v2, v4, v2
	v_add_u32_e32 v2, v4, v2
	v_mul_hi_u32 v2, v6, v2
	v_mul_lo_u32 v4, v2, v3
	v_sub_u32_e32 v4, v6, v4
	v_add_u32_e32 v5, 1, v2
	v_cmp_ge_u32_e32 vcc, v4, v3
	s_nop 1
	v_cndmask_b32_e32 v2, v2, v5, vcc
	v_sub_u32_e32 v5, v4, v3
	v_cndmask_b32_e32 v4, v4, v5, vcc
	v_add_u32_e32 v5, 1, v2
	v_cmp_ge_u32_e32 vcc, v4, v3
	v_add_u32_e32 v4, 1, v6
	s_nop 0
	v_cndmask_b32_e32 v2, v2, v5, vcc
	v_mul_lo_u32 v5, v3, v2
	v_add_u32_e32 v3, v5, v3
	v_cmp_ne_u32_e32 vcc, v4, v3
	s_and_saveexec_b64 s[10:11], vcc
	s_xor_b64 s[10:11], exec, s[10:11]
	s_cbranch_execz .LBB0_885
	s_waitcnt lgkmcnt(0)
	v_mul_u32_u24_e32 v18, 10, v1
	v_mov_b32_e32 v1, 0
	global_load_dword v3, v1, s[100:101] sc1
	s_waitcnt vmcnt(0)
	v_cmp_lt_u32_e32 vcc, v3, v18
	s_and_saveexec_b64 s[12:13], vcc
	s_cbranch_execz .LBB0_884
	s_mov_b32 s24, 1
	s_mov_b64 s[14:15], 0
	s_branch .LBB0_875

.LBB0_885:
	s_andn2_saveexec_b64 s[10:11], s[10:11]
	s_cbranch_execz .LBB0_905
	s_mov_b64 s[10:11], exec
	buffer_wbl2 sc1
	s_waitcnt lgkmcnt(0)
	v_mul_u32_u24_e32 v18, 10, v1
	s_waitcnt vmcnt(0)
	v_mbcnt_lo_u32_b32 v2, s10, 0
	v_mbcnt_hi_u32_b32 v2, s11, v2
	v_cmp_eq_u32_e32 vcc, 0, v2
	s_and_saveexec_b64 s[12:13], vcc
	s_cbranch_execz .LBB0_888
	s_bcnt1_i32_b64 s10, s[10:11]
	v_mov_b32_e32 v3, 0x7000
	v_mov_b32_e32 v4, s10
	global_atomic_add v3, v3, v4, s[94:95] offset:1024 sc0

.LBB0_951:
	s_or_b64 exec, exec, s[12:13]
	v_cvt_f32_u32_e32 v5, v3
	s_waitcnt vmcnt(0)
	v_readfirstlane_b32 s10, v4
	s_add_u32 s8, s8, 0x2400
	s_addc_u32 s9, s9, 0
	v_rcp_iflag_f32_e32 v5, v5
	v_add_u32_e32 v6, s10, v2
	v_mul_f32_e32 v4, 0x4f7ffffe, v5
	v_cvt_u32_f32_e32 v4, v4
	v_sub_u32_e32 v5, 0, v3
	v_mul_lo_u32 v2, v5, v4
	v_mul_hi_u32 v2, v4, v2
	v_add_u32_e32 v2, v4, v2
	v_mul_hi_u32 v2, v6, v2
	v_mul_lo_u32 v4, v2, v3
	v_sub_u32_e32 v4, v6, v4
	v_add_u32_e32 v5, 1, v2
	v_cmp_ge_u32_e32 vcc, v4, v3
	s_nop 1
	v_cndmask_b32_e32 v2, v2, v5, vcc
	v_sub_u32_e32 v5, v4, v3
	v_cndmask_b32_e32 v4, v4, v5, vcc
	v_add_u32_e32 v5, 1, v2
	v_cmp_ge_u32_e32 vcc, v4, v3
	v_add_u32_e32 v4, 1, v6
	s_nop 0
	v_cndmask_b32_e32 v2, v2, v5, vcc
	v_mul_lo_u32 v5, v3, v2
	v_add_u32_e32 v3, v5, v3
	v_cmp_ne_u32_e32 vcc, v4, v3
	s_and_saveexec_b64 s[10:11], vcc
	s_xor_b64 s[10:11], exec, s[10:11]
	s_cbranch_execz .LBB0_965
	s_waitcnt lgkmcnt(0)
	v_mul_u32_u24_e32 v18, 11, v1
	v_mov_b32_e32 v1, 0
	global_load_dword v3, v1, s[100:101] sc1
	s_waitcnt vmcnt(0)
	v_cmp_lt_u32_e32 vcc, v3, v18
	s_and_saveexec_b64 s[12:13], vcc
	s_cbranch_execz .LBB0_964
	s_mov_b32 s24, 1
	s_mov_b64 s[14:15], 0
	s_branch .LBB0_955

.LBB0_965:
	s_andn2_saveexec_b64 s[10:11], s[10:11]
	s_cbranch_execz .LBB0_985
	s_mov_b64 s[10:11], exec
	buffer_wbl2 sc1
	s_waitcnt lgkmcnt(0)
	v_mul_u32_u24_e32 v18, 11, v1
	s_waitcnt vmcnt(0)
	v_mbcnt_lo_u32_b32 v2, s10, 0
	v_mbcnt_hi_u32_b32 v2, s11, v2
	v_cmp_eq_u32_e32 vcc, 0, v2
	s_and_saveexec_b64 s[12:13], vcc
	s_cbranch_execz .LBB0_968
	s_bcnt1_i32_b64 s10, s[10:11]
	v_mov_b32_e32 v3, 0x7000
	v_mov_b32_e32 v4, s10
	global_atomic_add v3, v3, v4, s[94:95] offset:1024 sc0

.LBB0_1045:
	s_or_b64 exec, exec, s[12:13]
	v_cvt_f32_u32_e32 v5, v3
	s_waitcnt vmcnt(0)
	v_readfirstlane_b32 s10, v4
	s_add_u32 s8, s8, 0x2400
	s_addc_u32 s9, s9, 0
	v_rcp_iflag_f32_e32 v5, v5
	v_add_u32_e32 v6, s10, v2
	v_mul_f32_e32 v4, 0x4f7ffffe, v5
	v_cvt_u32_f32_e32 v4, v4
	v_sub_u32_e32 v5, 0, v3
	v_mul_lo_u32 v2, v5, v4
	v_mul_hi_u32 v2, v4, v2
	v_add_u32_e32 v2, v4, v2
	v_mul_hi_u32 v2, v6, v2
	v_mul_lo_u32 v4, v2, v3
	v_sub_u32_e32 v4, v6, v4
	v_add_u32_e32 v5, 1, v2
	v_cmp_ge_u32_e32 vcc, v4, v3
	s_nop 1
	v_cndmask_b32_e32 v2, v2, v5, vcc
	v_sub_u32_e32 v5, v4, v3
	v_cndmask_b32_e32 v4, v4, v5, vcc
	v_add_u32_e32 v5, 1, v2
	v_cmp_ge_u32_e32 vcc, v4, v3
	v_add_u32_e32 v4, 1, v6
	s_nop 0
	v_cndmask_b32_e32 v2, v2, v5, vcc
	v_mul_lo_u32 v5, v3, v2
	v_add_u32_e32 v3, v5, v3
	v_cmp_ne_u32_e32 vcc, v4, v3
	s_and_saveexec_b64 s[10:11], vcc
	s_xor_b64 s[10:11], exec, s[10:11]
	s_cbranch_execz .LBB0_1059
	s_waitcnt lgkmcnt(0)
	v_mul_u32_u24_e32 v18, 12, v1
	v_mov_b32_e32 v1, 0
	global_load_dword v3, v1, s[100:101] sc1
	s_waitcnt vmcnt(0)
	v_cmp_lt_u32_e32 vcc, v3, v18
	s_and_saveexec_b64 s[12:13], vcc
	s_cbranch_execz .LBB0_1058
	s_mov_b32 s24, 1
	s_mov_b64 s[14:15], 0
	s_branch .LBB0_1049

.LBB0_1059:
	s_andn2_saveexec_b64 s[10:11], s[10:11]
	s_cbranch_execz .LBB0_1079
	s_mov_b64 s[10:11], exec
	buffer_wbl2 sc1
	s_waitcnt lgkmcnt(0)
	v_mul_u32_u24_e32 v18, 12, v1
	s_waitcnt vmcnt(0)
	v_mbcnt_lo_u32_b32 v2, s10, 0
	v_mbcnt_hi_u32_b32 v2, s11, v2
	v_cmp_eq_u32_e32 vcc, 0, v2
	s_and_saveexec_b64 s[12:13], vcc
	s_cbranch_execz .LBB0_1062
	s_bcnt1_i32_b64 s10, s[10:11]
	v_mov_b32_e32 v3, 0x7000
	v_mov_b32_e32 v4, s10
	global_atomic_add v3, v3, v4, s[94:95] offset:1024 sc0

.LBB0_1142:
	s_or_b64 exec, exec, s[12:13]
	v_cvt_f32_u32_e32 v5, v3
	s_waitcnt vmcnt(0)
	v_readfirstlane_b32 s10, v4
	s_add_u32 s8, s8, 0x2400
	s_addc_u32 s9, s9, 0
	v_rcp_iflag_f32_e32 v5, v5
	v_add_u32_e32 v6, s10, v2
	v_mul_f32_e32 v4, 0x4f7ffffe, v5
	v_cvt_u32_f32_e32 v4, v4
	v_sub_u32_e32 v5, 0, v3
	v_mul_lo_u32 v2, v5, v4
	v_mul_hi_u32 v2, v4, v2
	v_add_u32_e32 v2, v4, v2
	v_mul_hi_u32 v2, v6, v2
	v_mul_lo_u32 v4, v2, v3
	v_sub_u32_e32 v4, v6, v4
	v_add_u32_e32 v5, 1, v2
	v_cmp_ge_u32_e32 vcc, v4, v3
	s_nop 1
	v_cndmask_b32_e32 v2, v2, v5, vcc
	v_sub_u32_e32 v5, v4, v3
	v_cndmask_b32_e32 v4, v4, v5, vcc
	v_add_u32_e32 v5, 1, v2
	v_cmp_ge_u32_e32 vcc, v4, v3
	v_add_u32_e32 v4, 1, v6
	s_nop 0
	v_cndmask_b32_e32 v2, v2, v5, vcc
	v_mul_lo_u32 v5, v3, v2
	v_add_u32_e32 v3, v5, v3
	v_cmp_ne_u32_e32 vcc, v4, v3
	s_and_saveexec_b64 s[10:11], vcc
	s_xor_b64 s[10:11], exec, s[10:11]
	s_cbranch_execz .LBB0_1156
	s_waitcnt lgkmcnt(0)
	v_mul_u32_u24_e32 v18, 13, v1
	v_mov_b32_e32 v1, 0
	global_load_dword v3, v1, s[100:101] sc1
	s_waitcnt vmcnt(0)
	v_cmp_lt_u32_e32 vcc, v3, v18
	s_and_saveexec_b64 s[12:13], vcc
	s_cbranch_execz .LBB0_1155
	s_mov_b32 s24, 1
	s_mov_b64 s[14:15], 0
	s_branch .LBB0_1146

.LBB0_1156:
	s_andn2_saveexec_b64 s[10:11], s[10:11]
	s_cbranch_execz .LBB0_1176
	s_mov_b64 s[10:11], exec
	buffer_wbl2 sc1
	s_waitcnt lgkmcnt(0)
	v_mul_u32_u24_e32 v18, 13, v1
	s_waitcnt vmcnt(0)
	v_mbcnt_lo_u32_b32 v2, s10, 0
	v_mbcnt_hi_u32_b32 v2, s11, v2
	v_cmp_eq_u32_e32 vcc, 0, v2
	s_and_saveexec_b64 s[12:13], vcc
	s_cbranch_execz .LBB0_1159
	s_bcnt1_i32_b64 s10, s[10:11]
	v_mov_b32_e32 v3, 0x7000
	v_mov_b32_e32 v4, s10
	global_atomic_add v3, v3, v4, s[94:95] offset:1024 sc0

.LBB0_1214:
	s_or_b64 exec, exec, s[12:13]
	v_cvt_f32_u32_e32 v5, v3
	s_waitcnt vmcnt(0)
	v_readfirstlane_b32 s10, v4
	s_add_u32 s8, s8, 0x2400
	s_addc_u32 s9, s9, 0
	v_rcp_iflag_f32_e32 v5, v5
	v_add_u32_e32 v6, s10, v2
	v_mul_f32_e32 v4, 0x4f7ffffe, v5
	v_cvt_u32_f32_e32 v4, v4
	v_sub_u32_e32 v5, 0, v3
	v_mul_lo_u32 v2, v5, v4
	v_mul_hi_u32 v2, v4, v2
	v_add_u32_e32 v2, v4, v2
	v_mul_hi_u32 v2, v6, v2
	v_mul_lo_u32 v4, v2, v3
	v_sub_u32_e32 v4, v6, v4
	v_add_u32_e32 v5, 1, v2
	v_cmp_ge_u32_e32 vcc, v4, v3
	s_nop 1
	v_cndmask_b32_e32 v2, v2, v5, vcc
	v_sub_u32_e32 v5, v4, v3
	v_cndmask_b32_e32 v4, v4, v5, vcc
	v_add_u32_e32 v5, 1, v2
	v_cmp_ge_u32_e32 vcc, v4, v3
	v_add_u32_e32 v4, 1, v6
	s_nop 0
	v_cndmask_b32_e32 v2, v2, v5, vcc
	v_mul_lo_u32 v5, v3, v2
	v_add_u32_e32 v3, v5, v3
	v_cmp_ne_u32_e32 vcc, v4, v3
	s_and_saveexec_b64 s[10:11], vcc
	s_xor_b64 s[10:11], exec, s[10:11]
	s_cbranch_execz .LBB0_1228
	s_waitcnt lgkmcnt(0)
	v_mul_u32_u24_e32 v18, 14, v1
	v_mov_b32_e32 v1, 0
	global_load_dword v3, v1, s[100:101] sc1
	s_waitcnt vmcnt(0)
	v_cmp_lt_u32_e32 vcc, v3, v18
	s_and_saveexec_b64 s[12:13], vcc
	s_cbranch_execz .LBB0_1227
	s_mov_b32 s24, 1
	s_mov_b64 s[14:15], 0
	s_branch .LBB0_1218

.LBB0_1228:
	s_andn2_saveexec_b64 s[10:11], s[10:11]
	s_cbranch_execz .LBB0_1248
	s_mov_b64 s[10:11], exec
	buffer_wbl2 sc1
	s_waitcnt lgkmcnt(0)
	v_mul_u32_u24_e32 v18, 14, v1
	s_waitcnt vmcnt(0)
	v_mbcnt_lo_u32_b32 v2, s10, 0
	v_mbcnt_hi_u32_b32 v2, s11, v2
	v_cmp_eq_u32_e32 vcc, 0, v2
	s_and_saveexec_b64 s[12:13], vcc
	s_cbranch_execz .LBB0_1231
	s_bcnt1_i32_b64 s10, s[10:11]
	v_mov_b32_e32 v3, 0x7000
	v_mov_b32_e32 v4, s10
	global_atomic_add v3, v3, v4, s[94:95] offset:1024 sc0

.LBB0_1291:
	s_or_b64 exec, exec, s[12:13]
	v_cvt_f32_u32_e32 v5, v3
	s_waitcnt vmcnt(0)
	v_readfirstlane_b32 s10, v4
	s_add_u32 s8, s8, 0x2400
	s_addc_u32 s9, s9, 0
	v_rcp_iflag_f32_e32 v5, v5
	v_add_u32_e32 v6, s10, v2
	v_mul_f32_e32 v4, 0x4f7ffffe, v5
	v_cvt_u32_f32_e32 v4, v4
	v_sub_u32_e32 v5, 0, v3
	v_mul_lo_u32 v2, v5, v4
	v_mul_hi_u32 v2, v4, v2
	v_add_u32_e32 v2, v4, v2
	v_mul_hi_u32 v2, v6, v2
	v_mul_lo_u32 v4, v2, v3
	v_sub_u32_e32 v4, v6, v4
	v_add_u32_e32 v5, 1, v2
	v_cmp_ge_u32_e32 vcc, v4, v3
	s_nop 1
	v_cndmask_b32_e32 v2, v2, v5, vcc
	v_sub_u32_e32 v5, v4, v3
	v_cndmask_b32_e32 v4, v4, v5, vcc
	v_add_u32_e32 v5, 1, v2
	v_cmp_ge_u32_e32 vcc, v4, v3
	v_add_u32_e32 v4, 1, v6
	s_nop 0
	v_cndmask_b32_e32 v2, v2, v5, vcc
	v_mul_lo_u32 v5, v3, v2
	v_add_u32_e32 v3, v5, v3
	v_cmp_ne_u32_e32 vcc, v4, v3
	s_and_saveexec_b64 s[10:11], vcc
	s_xor_b64 s[10:11], exec, s[10:11]
	s_cbranch_execz .LBB0_1305
	s_waitcnt lgkmcnt(0)
	v_mul_u32_u24_e32 v18, 15, v1
	v_mov_b32_e32 v1, 0
	global_load_dword v3, v1, s[100:101] sc1
	s_waitcnt vmcnt(0)
	v_cmp_lt_u32_e32 vcc, v3, v18
	s_and_saveexec_b64 s[12:13], vcc
	s_cbranch_execz .LBB0_1304
	s_mov_b32 s24, 1
	s_mov_b64 s[14:15], 0
	s_branch .LBB0_1295

.LBB0_1305:
	s_andn2_saveexec_b64 s[10:11], s[10:11]
	s_cbranch_execz .LBB0_1325
	s_mov_b64 s[10:11], exec
	buffer_wbl2 sc1
	s_waitcnt lgkmcnt(0)
	v_mul_u32_u24_e32 v18, 15, v1
	s_waitcnt vmcnt(0)
	v_mbcnt_lo_u32_b32 v2, s10, 0
	v_mbcnt_hi_u32_b32 v2, s11, v2
	v_cmp_eq_u32_e32 vcc, 0, v2
	s_and_saveexec_b64 s[12:13], vcc
	s_cbranch_execz .LBB0_1308
	s_bcnt1_i32_b64 s10, s[10:11]
	v_mov_b32_e32 v3, 0x7000
	v_mov_b32_e32 v4, s10
	global_atomic_add v3, v3, v4, s[94:95] offset:1024 sc0

.LBB0_1358:
	s_waitcnt vmcnt(0)
	s_waitcnt vmcnt(0)
	s_barrier
	s_mov_b64 s[4:5], exec
	s_load_dwordx2 s[42:43], s[0:1], 0x110
	v_readlane_b32 s6, v254, 36
	v_readlane_b32 s7, v254, 37
	s_and_b64 s[6:7], s[4:5], s[6:7]
	s_mov_b64 exec, s[6:7]
	s_cbranch_execz .LBB0_1411
	s_add_u32 s100, s94, 0x7400
	s_addc_u32 s101, s95, 0
	s_add_u32 s6, s94, 0x4200
	s_addc_u32 s7, s95, 0
	s_add_i32 s8, 0, 0x20160
	v_mov_b32_e32 v1, s8
	s_waitcnt vmcnt(0) expcnt(0) lgkmcnt(0)
	ds_read_b32 v3, v1
	s_add_i32 s8, 0, 0x20164
	v_mov_b32_e32 v1, s8
	ds_read_b32 v1, v1
	s_waitcnt lgkmcnt(1)
	v_cmp_ne_u32_e32 vcc, 0, v3
	s_cbranch_vccnz .LBB0_1375
	s_add_u32 s8, s94, 0x4400
	s_addc_u32 s9, s95, 0
	s_add_u32 s10, s94, 0x4500
	s_addc_u32 s11, s95, 0
	s_add_u32 s12, s94, 0x4600
	s_addc_u32 s13, s95, 0
	s_add_u32 s14, s94, 0x4700
	s_addc_u32 s15, s95, 0
	s_add_u32 s16, s94, 0x4800
	s_addc_u32 s17, s95, 0
	s_add_u32 s20, s94, 0x4900
	s_addc_u32 s21, s95, 0
	s_add_u32 s22, s94, 0x4a00
	s_addc_u32 s23, s95, 0
	s_add_u32 s24, s94, 0x4b00
	s_addc_u32 s25, s95, 0
	s_add_u32 s26, s94, 0x4c00
	s_addc_u32 s27, s95, 0
	s_add_u32 s28, s94, 0x4d00
	s_addc_u32 s29, s95, 0
	s_add_u32 s30, s94, 0x4e00
	s_addc_u32 s31, s95, 0
	s_add_u32 s34, s94, 0x4f00
	s_addc_u32 s35, s95, 0
	v_readlane_b32 s40, v254, 0
	s_add_u32 s36, s94, 0x5000
	v_readlane_b32 s41, v254, 1
	s_addc_u32 s37, s95, 0
	s_load_dwordx2 s[44:45], s[40:41], 0x4
	s_add_u32 s38, s94, 0x5100
	s_addc_u32 s39, s95, 0
	s_add_u32 s40, s94, 0x5200
	s_addc_u32 s41, s95, 0
	s_add_u32 s42, s94, 0x5300
	s_waitcnt lgkmcnt(0)
	s_mul_i32 s50, s44, s90
	s_addc_u32 s43, s95, 0
	s_mul_i32 s50, s50, s45
	s_mov_b32 s51, 1
	v_mov_b32_e32 v17, 0
	s_branch .LBB0_1362

.LBB0_1377:
	s_or_b64 exec, exec, s[12:13]
	v_cvt_f32_u32_e32 v5, v3
	s_waitcnt vmcnt(0)
	v_readfirstlane_b32 s10, v4
	s_add_u32 s8, s8, 0x2400
	s_addc_u32 s9, s9, 0
	v_rcp_iflag_f32_e32 v5, v5
	v_add_u32_e32 v6, s10, v2
	v_mul_f32_e32 v4, 0x4f7ffffe, v5
	v_cvt_u32_f32_e32 v4, v4
	v_sub_u32_e32 v5, 0, v3
	v_mul_lo_u32 v2, v5, v4
	v_mul_hi_u32 v2, v4, v2
	v_add_u32_e32 v2, v4, v2
	v_mul_hi_u32 v2, v6, v2
	v_mul_lo_u32 v4, v2, v3
	v_sub_u32_e32 v4, v6, v4
	v_add_u32_e32 v5, 1, v2
	v_cmp_ge_u32_e32 vcc, v4, v3
	s_nop 1
	v_cndmask_b32_e32 v2, v2, v5, vcc
	v_sub_u32_e32 v5, v4, v3
	v_cndmask_b32_e32 v4, v4, v5, vcc
	v_add_u32_e32 v5, 1, v2
	v_cmp_ge_u32_e32 vcc, v4, v3
	v_add_u32_e32 v4, 1, v6
	s_nop 0
	v_cndmask_b32_e32 v2, v2, v5, vcc
	v_mul_lo_u32 v5, v3, v2
	v_add_u32_e32 v3, v5, v3
	v_cmp_ne_u32_e32 vcc, v4, v3
	s_and_saveexec_b64 s[10:11], vcc
	s_xor_b64 s[10:11], exec, s[10:11]
	s_cbranch_execz .LBB0_1391
	s_waitcnt lgkmcnt(0)
	v_mul_u32_u24_e32 v18, 16, v1
	v_mov_b32_e32 v1, 0
	global_load_dword v3, v1, s[100:101] sc1
	s_waitcnt vmcnt(0)
	v_cmp_lt_u32_e32 vcc, v3, v18
	s_and_saveexec_b64 s[12:13], vcc
	s_cbranch_execz .LBB0_1390
	s_mov_b32 s26, 1
	s_mov_b64 s[14:15], 0
	s_branch .LBB0_1381

.LBB0_1383:
	global_load_dword v3, v1, s[100:101] sc1
	s_add_i32 s26, s26, 1
	s_mov_b64 s[22:23], -1
	s_waitcnt vmcnt(0)
	v_cmp_ge_u32_e32 vcc, v3, v18
	s_orn2_b64 s[20:21], vcc, exec
	s_branch .LBB0_1380

.LBB0_1391:
	s_andn2_saveexec_b64 s[10:11], s[10:11]
	s_cbranch_execz .LBB0_1411
	s_mov_b64 s[10:11], exec
	buffer_wbl2 sc1
	s_waitcnt lgkmcnt(0)
	v_mul_u32_u24_e32 v18, 16, v1
	s_waitcnt vmcnt(0)
	v_mbcnt_lo_u32_b32 v2, s10, 0
	v_mbcnt_hi_u32_b32 v2, s11, v2
	v_cmp_eq_u32_e32 vcc, 0, v2
	s_and_saveexec_b64 s[12:13], vcc
	s_cbranch_execz .LBB0_1394
	s_bcnt1_i32_b64 s10, s[10:11]
	v_mov_b32_e32 v3, 0x7000
	v_mov_b32_e32 v4, s10
	global_atomic_add v3, v3, v4, s[94:95] offset:1024 sc0
.LBB0_1394:
	s_or_b64 exec, exec, s[12:13]
	v_cvt_f32_u32_e32 v4, v1
	s_waitcnt vmcnt(0)
	v_readfirstlane_b32 s12, v3
	s_add_u32 s10, s94, 0x7500
	s_addc_u32 s11, s95, 0
	v_rcp_iflag_f32_e32 v4, v4
	v_add_u32_e32 v2, s12, v2
	s_mov_b64 s[14:15], -1
	v_mul_f32_e32 v3, 0x4f7ffffe, v4
	v_cvt_u32_f32_e32 v3, v3
	v_sub_u32_e32 v4, 0, v1
	v_mul_lo_u32 v4, v4, v3
	v_mul_hi_u32 v4, v3, v4
	v_add_u32_e32 v3, v3, v4
	v_mul_hi_u32 v3, v2, v3
	v_mul_lo_u32 v4, v3, v1
	v_sub_u32_e32 v4, v2, v4
	v_add_u32_e32 v5, 1, v3
	v_cmp_ge_u32_e32 vcc, v4, v1
	v_add_u32_e32 v2, 1, v2
	s_nop 0
	v_cndmask_b32_e32 v3, v3, v5, vcc
	v_sub_u32_e32 v5, v4, v1
	v_cndmask_b32_e32 v4, v4, v5, vcc
	v_add_u32_e32 v5, 1, v3
	v_cmp_ge_u32_e32 vcc, v4, v1
	s_nop 1
	v_cndmask_b32_e32 v4, v3, v5, vcc
	v_mul_lo_u32 v3, v1, v4
	v_add_u32_e32 v1, v3, v1
	v_cmp_ne_u32_e32 vcc, v2, v1
	v_mov_b64_e32 v[2:3], s[10:11]
	s_and_saveexec_b64 s[12:13], vcc
	s_cbranch_execz .LBB0_1406
	v_mov_b32_e32 v1, 0
	global_load_dword v2, v1, s[100:101] sc1
	s_mov_b64 s[16:17], 0
	s_waitcnt vmcnt(0)
	v_cmp_lt_u32_e32 vcc, v2, v18
	s_and_saveexec_b64 s[14:15], vcc
	s_cbranch_execz .LBB0_1405
	s_mov_b32 s28, 1
	s_branch .LBB0_1398

.LBB0_1400:
	global_load_dword v2, v1, s[100:101] sc1
	s_add_i32 s28, s28, 1
	s_mov_b64 s[22:23], -1
	s_waitcnt vmcnt(0)
	v_cmp_ge_u32_e32 vcc, v2, v18
	s_orn2_b64 s[26:27], vcc, exec
	s_branch .LBB0_1397

.LBB0_1440:
	s_waitcnt vmcnt(0)
	s_waitcnt vmcnt(0) lgkmcnt(0)
	s_barrier
	s_mov_b64 s[4:5], exec
	v_readlane_b32 s6, v254, 36
	v_readlane_b32 s7, v254, 37
	s_and_b64 s[6:7], s[4:5], s[6:7]
	s_mov_b64 exec, s[6:7]
	s_cbranch_execz .LBB0_1492
	s_add_u32 s100, s94, 0x7400
	s_addc_u32 s101, s95, 0
	s_add_u32 s6, s94, 0x4200
	s_addc_u32 s7, s95, 0
	s_add_i32 s8, 0, 0x20160
	v_mov_b32_e32 v1, s8
	s_waitcnt vmcnt(0) expcnt(0) lgkmcnt(0)
	ds_read_b32 v3, v1
	s_add_i32 s8, 0, 0x20164
	v_mov_b32_e32 v1, s8
	ds_read_b32 v1, v1
	s_waitcnt lgkmcnt(1)
	v_cmp_ne_u32_e32 vcc, 0, v3
	s_cbranch_vccnz .LBB0_1456
	s_add_u32 s8, s94, 0x4400
	s_addc_u32 s9, s95, 0
	s_add_u32 s10, s94, 0x4500
	s_addc_u32 s11, s95, 0
	s_add_u32 s12, s94, 0x4600
	s_addc_u32 s13, s95, 0
	s_add_u32 s14, s94, 0x4700
	s_addc_u32 s15, s95, 0
	s_add_u32 s16, s94, 0x4800
	s_addc_u32 s17, s95, 0
	s_add_u32 s20, s94, 0x4900
	s_addc_u32 s21, s95, 0
	s_add_u32 s22, s94, 0x4a00
	s_addc_u32 s23, s95, 0
	s_add_u32 s24, s94, 0x4b00
	s_addc_u32 s25, s95, 0
	s_add_u32 s26, s94, 0x4c00
	s_addc_u32 s27, s95, 0
	s_add_u32 s28, s94, 0x4d00
	s_addc_u32 s29, s95, 0
	s_add_u32 s30, s94, 0x4e00
	s_addc_u32 s31, s95, 0
	s_add_u32 s34, s94, 0x4f00
	s_addc_u32 s35, s95, 0
	v_readlane_b32 s40, v254, 0
	s_add_u32 s36, s94, 0x5000
	v_readlane_b32 s41, v254, 1
	s_addc_u32 s37, s95, 0
	s_load_dwordx2 s[44:45], s[40:41], 0x4
	s_add_u32 s38, s94, 0x5100
	s_addc_u32 s39, s95, 0
	s_add_u32 s40, s94, 0x5200
	s_addc_u32 s41, s95, 0
	s_add_u32 s42, s94, 0x5300
	s_waitcnt lgkmcnt(0)
	s_mul_i32 s50, s44, s90
	s_addc_u32 s43, s95, 0
	s_mul_i32 s50, s50, s45
	s_mov_b32 s51, 1
	v_mov_b32_e32 v17, 0
	s_branch .LBB0_1444

.LBB0_1458:
	s_or_b64 exec, exec, s[12:13]
	v_cvt_f32_u32_e32 v5, v3
	s_waitcnt vmcnt(0)
	v_readfirstlane_b32 s10, v4
	s_add_u32 s8, s8, 0x2400
	s_addc_u32 s9, s9, 0
	v_rcp_iflag_f32_e32 v5, v5
	v_add_u32_e32 v6, s10, v2
	v_mul_f32_e32 v4, 0x4f7ffffe, v5
	v_cvt_u32_f32_e32 v4, v4
	v_sub_u32_e32 v5, 0, v3
	v_mul_lo_u32 v2, v5, v4
	v_mul_hi_u32 v2, v4, v2
	v_add_u32_e32 v2, v4, v2
	v_mul_hi_u32 v2, v6, v2
	v_mul_lo_u32 v4, v2, v3
	v_sub_u32_e32 v4, v6, v4
	v_add_u32_e32 v5, 1, v2
	v_cmp_ge_u32_e32 vcc, v4, v3
	s_nop 1
	v_cndmask_b32_e32 v2, v2, v5, vcc
	v_sub_u32_e32 v5, v4, v3
	v_cndmask_b32_e32 v4, v4, v5, vcc
	v_add_u32_e32 v5, 1, v2
	v_cmp_ge_u32_e32 vcc, v4, v3
	v_add_u32_e32 v4, 1, v6
	s_nop 0
	v_cndmask_b32_e32 v2, v2, v5, vcc
	v_mul_lo_u32 v5, v3, v2
	v_add_u32_e32 v3, v5, v3
	v_cmp_ne_u32_e32 vcc, v4, v3
	s_and_saveexec_b64 s[10:11], vcc
	s_xor_b64 s[10:11], exec, s[10:11]
	s_cbranch_execz .LBB0_1472
	s_waitcnt lgkmcnt(0)
	v_mul_u32_u24_e32 v18, 17, v1
	v_mov_b32_e32 v1, 0
	global_load_dword v3, v1, s[100:101] sc1
	s_waitcnt vmcnt(0)
	v_cmp_lt_u32_e32 vcc, v3, v18
	s_and_saveexec_b64 s[12:13], vcc
	s_cbranch_execz .LBB0_1471
	s_mov_b32 s26, 1
	s_mov_b64 s[14:15], 0
	s_branch .LBB0_1462

.LBB0_1472:
	s_andn2_saveexec_b64 s[10:11], s[10:11]
	s_cbranch_execz .LBB0_1492
	s_mov_b64 s[10:11], exec
	buffer_wbl2 sc1
	s_waitcnt lgkmcnt(0)
	v_mul_u32_u24_e32 v18, 17, v1
	s_waitcnt vmcnt(0)
	v_mbcnt_lo_u32_b32 v2, s10, 0
	v_mbcnt_hi_u32_b32 v2, s11, v2
	v_cmp_eq_u32_e32 vcc, 0, v2
	s_and_saveexec_b64 s[12:13], vcc
	s_cbranch_execz .LBB0_1475
	s_bcnt1_i32_b64 s10, s[10:11]
	v_mov_b32_e32 v3, 0x7000
	v_mov_b32_e32 v4, s10
	global_atomic_add v3, v3, v4, s[94:95] offset:1024 sc0

.LBB0_1520:
	s_waitcnt vmcnt(0)
	s_waitcnt vmcnt(0)
	s_barrier
	s_mov_b64 s[4:5], exec
	v_readlane_b32 s6, v254, 36
	v_readlane_b32 s7, v254, 37
	s_and_b64 s[6:7], s[4:5], s[6:7]
	s_mov_b64 exec, s[6:7]
	s_cbranch_execz .LBB0_1572
	s_add_u32 s100, s94, 0x7400
	s_addc_u32 s101, s95, 0
	s_add_u32 s6, s94, 0x4200
	s_addc_u32 s7, s95, 0
	s_add_i32 s8, 0, 0x20160
	v_mov_b32_e32 v1, s8
	s_waitcnt vmcnt(0) expcnt(0) lgkmcnt(0)
	ds_read_b32 v3, v1
	s_add_i32 s8, 0, 0x20164
	v_mov_b32_e32 v1, s8
	ds_read_b32 v1, v1
	s_waitcnt lgkmcnt(1)
	v_cmp_ne_u32_e32 vcc, 0, v3
	s_cbranch_vccnz .LBB0_1536
	s_add_u32 s8, s94, 0x4400
	s_addc_u32 s9, s95, 0
	s_add_u32 s10, s94, 0x4500
	s_addc_u32 s11, s95, 0
	s_add_u32 s12, s94, 0x4600
	s_addc_u32 s13, s95, 0
	s_add_u32 s14, s94, 0x4700
	s_addc_u32 s15, s95, 0
	s_add_u32 s16, s94, 0x4800
	s_addc_u32 s17, s95, 0
	s_add_u32 s20, s94, 0x4900
	s_addc_u32 s21, s95, 0
	s_add_u32 s22, s94, 0x4a00
	s_addc_u32 s23, s95, 0
	s_add_u32 s24, s94, 0x4b00
	s_addc_u32 s25, s95, 0
	s_add_u32 s26, s94, 0x4c00
	s_addc_u32 s27, s95, 0
	s_add_u32 s28, s94, 0x4d00
	s_addc_u32 s29, s95, 0
	s_add_u32 s30, s94, 0x4e00
	s_addc_u32 s31, s95, 0
	s_add_u32 s34, s94, 0x4f00
	s_addc_u32 s35, s95, 0
	v_readlane_b32 s40, v254, 0
	s_add_u32 s36, s94, 0x5000
	v_readlane_b32 s41, v254, 1
	s_addc_u32 s37, s95, 0
	s_load_dwordx2 s[44:45], s[40:41], 0x4
	s_add_u32 s38, s94, 0x5100
	s_addc_u32 s39, s95, 0
	s_add_u32 s40, s94, 0x5200
	s_addc_u32 s41, s95, 0
	s_add_u32 s42, s94, 0x5300
	s_waitcnt lgkmcnt(0)
	s_mul_i32 s50, s44, s90
	s_addc_u32 s43, s95, 0
	s_mul_i32 s50, s50, s45
	s_mov_b32 s51, 1
	v_mov_b32_e32 v17, 0
	s_branch .LBB0_1524

.LBB0_1538:
	s_or_b64 exec, exec, s[12:13]
	v_cvt_f32_u32_e32 v5, v3
	s_waitcnt vmcnt(0)
	v_readfirstlane_b32 s10, v4
	s_add_u32 s8, s8, 0x2400
	s_addc_u32 s9, s9, 0
	v_rcp_iflag_f32_e32 v5, v5
	v_add_u32_e32 v6, s10, v2
	v_mul_f32_e32 v4, 0x4f7ffffe, v5
	v_cvt_u32_f32_e32 v4, v4
	v_sub_u32_e32 v5, 0, v3
	v_mul_lo_u32 v2, v5, v4
	v_mul_hi_u32 v2, v4, v2
	v_add_u32_e32 v2, v4, v2
	v_mul_hi_u32 v2, v6, v2
	v_mul_lo_u32 v4, v2, v3
	v_sub_u32_e32 v4, v6, v4
	v_add_u32_e32 v5, 1, v2
	v_cmp_ge_u32_e32 vcc, v4, v3
	s_nop 1
	v_cndmask_b32_e32 v2, v2, v5, vcc
	v_sub_u32_e32 v5, v4, v3
	v_cndmask_b32_e32 v4, v4, v5, vcc
	v_add_u32_e32 v5, 1, v2
	v_cmp_ge_u32_e32 vcc, v4, v3
	v_add_u32_e32 v4, 1, v6
	s_nop 0
	v_cndmask_b32_e32 v2, v2, v5, vcc
	v_mul_lo_u32 v5, v3, v2
	v_add_u32_e32 v3, v5, v3
	v_cmp_ne_u32_e32 vcc, v4, v3
	s_and_saveexec_b64 s[10:11], vcc
	s_xor_b64 s[10:11], exec, s[10:11]
	s_cbranch_execz .LBB0_1552
	s_waitcnt lgkmcnt(0)
	v_mul_u32_u24_e32 v18, 18, v1
	v_mov_b32_e32 v1, 0
	global_load_dword v3, v1, s[100:101] sc1
	s_waitcnt vmcnt(0)
	v_cmp_lt_u32_e32 vcc, v3, v18
	s_and_saveexec_b64 s[12:13], vcc
	s_cbranch_execz .LBB0_1551
	s_mov_b32 s26, 1
	s_mov_b64 s[14:15], 0
	s_branch .LBB0_1542

.LBB0_1552:
	s_andn2_saveexec_b64 s[10:11], s[10:11]
	s_cbranch_execz .LBB0_1572
	s_mov_b64 s[10:11], exec
	buffer_wbl2 sc1
	s_waitcnt lgkmcnt(0)
	v_mul_u32_u24_e32 v18, 18, v1
	s_waitcnt vmcnt(0)
	v_mbcnt_lo_u32_b32 v2, s10, 0
	v_mbcnt_hi_u32_b32 v2, s11, v2
	v_cmp_eq_u32_e32 vcc, 0, v2
	s_and_saveexec_b64 s[12:13], vcc
	s_cbranch_execz .LBB0_1555
	s_bcnt1_i32_b64 s10, s[10:11]
	v_mov_b32_e32 v3, 0x7000
	v_mov_b32_e32 v4, s10
	global_atomic_add v3, v3, v4, s[94:95] offset:1024 sc0

.LBB0_1632:
	s_or_b64 exec, exec, s[12:13]
	v_cvt_f32_u32_e32 v5, v3
	s_waitcnt vmcnt(0)
	v_readfirstlane_b32 s10, v4
	s_add_u32 s8, s8, 0x2400
	s_addc_u32 s9, s9, 0
	v_rcp_iflag_f32_e32 v5, v5
	v_add_u32_e32 v6, s10, v2
	v_mul_f32_e32 v4, 0x4f7ffffe, v5
	v_cvt_u32_f32_e32 v4, v4
	v_sub_u32_e32 v5, 0, v3
	v_mul_lo_u32 v2, v5, v4
	v_mul_hi_u32 v2, v4, v2
	v_add_u32_e32 v2, v4, v2
	v_mul_hi_u32 v2, v6, v2
	v_mul_lo_u32 v4, v2, v3
	v_sub_u32_e32 v4, v6, v4
	v_add_u32_e32 v5, 1, v2
	v_cmp_ge_u32_e32 vcc, v4, v3
	s_nop 1
	v_cndmask_b32_e32 v2, v2, v5, vcc
	v_sub_u32_e32 v5, v4, v3
	v_cndmask_b32_e32 v4, v4, v5, vcc
	v_add_u32_e32 v5, 1, v2
	v_cmp_ge_u32_e32 vcc, v4, v3
	v_add_u32_e32 v4, 1, v6
	s_nop 0
	v_cndmask_b32_e32 v2, v2, v5, vcc
	v_mul_lo_u32 v5, v3, v2
	v_add_u32_e32 v3, v5, v3
	v_cmp_ne_u32_e32 vcc, v4, v3
	s_and_saveexec_b64 s[10:11], vcc
	s_xor_b64 s[10:11], exec, s[10:11]
	s_cbranch_execz .LBB0_1646
	s_waitcnt lgkmcnt(0)
	v_mul_u32_u24_e32 v18, 19, v1
	v_mov_b32_e32 v1, 0
	global_load_dword v3, v1, s[100:101] sc1
	s_waitcnt vmcnt(0)
	v_cmp_lt_u32_e32 vcc, v3, v18
	s_and_saveexec_b64 s[12:13], vcc
	s_cbranch_execz .LBB0_1645
	s_mov_b32 s26, 1
	s_mov_b64 s[14:15], 0
	s_branch .LBB0_1636

.LBB0_1646:
	s_andn2_saveexec_b64 s[10:11], s[10:11]
	s_cbranch_execz .LBB0_1666
	s_mov_b64 s[10:11], exec
	buffer_wbl2 sc1
	s_waitcnt lgkmcnt(0)
	v_mul_u32_u24_e32 v18, 19, v1
	s_waitcnt vmcnt(0)
	v_mbcnt_lo_u32_b32 v2, s10, 0
	v_mbcnt_hi_u32_b32 v2, s11, v2
	v_cmp_eq_u32_e32 vcc, 0, v2
	s_and_saveexec_b64 s[12:13], vcc
	s_cbranch_execz .LBB0_1649
	s_bcnt1_i32_b64 s10, s[10:11]
	v_mov_b32_e32 v3, 0x7000
	v_mov_b32_e32 v4, s10
	global_atomic_add v3, v3, v4, s[94:95] offset:1024 sc0

.LBB0_1729:
	s_or_b64 exec, exec, s[12:13]
	v_cvt_f32_u32_e32 v5, v3
	s_waitcnt vmcnt(0)
	v_readfirstlane_b32 s10, v4
	s_add_u32 s8, s8, 0x2400
	s_addc_u32 s9, s9, 0
	v_rcp_iflag_f32_e32 v5, v5
	v_add_u32_e32 v6, s10, v2
	v_mul_f32_e32 v4, 0x4f7ffffe, v5
	v_cvt_u32_f32_e32 v4, v4
	v_sub_u32_e32 v5, 0, v3
	v_mul_lo_u32 v2, v5, v4
	v_mul_hi_u32 v2, v4, v2
	v_add_u32_e32 v2, v4, v2
	v_mul_hi_u32 v2, v6, v2
	v_mul_lo_u32 v4, v2, v3
	v_sub_u32_e32 v4, v6, v4
	v_add_u32_e32 v5, 1, v2
	v_cmp_ge_u32_e32 vcc, v4, v3
	s_nop 1
	v_cndmask_b32_e32 v2, v2, v5, vcc
	v_sub_u32_e32 v5, v4, v3
	v_cndmask_b32_e32 v4, v4, v5, vcc
	v_add_u32_e32 v5, 1, v2
	v_cmp_ge_u32_e32 vcc, v4, v3
	v_add_u32_e32 v4, 1, v6
	s_nop 0
	v_cndmask_b32_e32 v2, v2, v5, vcc
	v_mul_lo_u32 v5, v3, v2
	v_add_u32_e32 v3, v5, v3
	v_cmp_ne_u32_e32 vcc, v4, v3
	s_and_saveexec_b64 s[10:11], vcc
	s_xor_b64 s[10:11], exec, s[10:11]
	s_cbranch_execz .LBB0_1743
	s_waitcnt lgkmcnt(0)
	v_mul_u32_u24_e32 v18, 20, v1
	v_mov_b32_e32 v1, 0
	global_load_dword v3, v1, s[100:101] sc1
	s_waitcnt vmcnt(0)
	v_cmp_lt_u32_e32 vcc, v3, v18
	s_and_saveexec_b64 s[12:13], vcc
	s_cbranch_execz .LBB0_1742
	s_mov_b32 s26, 1
	s_mov_b64 s[14:15], 0
	s_branch .LBB0_1733

.LBB0_1743:
	s_andn2_saveexec_b64 s[10:11], s[10:11]
	s_cbranch_execz .LBB0_1763
	s_mov_b64 s[10:11], exec
	buffer_wbl2 sc1
	s_waitcnt lgkmcnt(0)
	v_mul_u32_u24_e32 v18, 20, v1
	s_waitcnt vmcnt(0)
	v_mbcnt_lo_u32_b32 v2, s10, 0
	v_mbcnt_hi_u32_b32 v2, s11, v2
	v_cmp_eq_u32_e32 vcc, 0, v2
	s_and_saveexec_b64 s[12:13], vcc
	s_cbranch_execz .LBB0_1746
	s_bcnt1_i32_b64 s10, s[10:11]
	v_mov_b32_e32 v3, 0x7000
	v_mov_b32_e32 v4, s10
	global_atomic_add v3, v3, v4, s[94:95] offset:1024 sc0

.LBB0_1809:
	s_or_b64 exec, exec, s[12:13]
	v_cvt_f32_u32_e32 v5, v3
	s_waitcnt vmcnt(0)
	v_readfirstlane_b32 s10, v4
	s_add_u32 s8, s8, 0x2400
	s_addc_u32 s9, s9, 0
	v_rcp_iflag_f32_e32 v5, v5
	v_add_u32_e32 v6, s10, v2
	v_mul_f32_e32 v4, 0x4f7ffffe, v5
	v_cvt_u32_f32_e32 v4, v4
	v_sub_u32_e32 v5, 0, v3
	v_mul_lo_u32 v2, v5, v4
	v_mul_hi_u32 v2, v4, v2
	v_add_u32_e32 v2, v4, v2
	v_mul_hi_u32 v2, v6, v2
	v_mul_lo_u32 v4, v2, v3
	v_sub_u32_e32 v4, v6, v4
	v_add_u32_e32 v5, 1, v2
	v_cmp_ge_u32_e32 vcc, v4, v3
	s_nop 1
	v_cndmask_b32_e32 v2, v2, v5, vcc
	v_sub_u32_e32 v5, v4, v3
	v_cndmask_b32_e32 v4, v4, v5, vcc
	v_add_u32_e32 v5, 1, v2
	v_cmp_ge_u32_e32 vcc, v4, v3
	v_add_u32_e32 v4, 1, v6
	s_nop 0
	v_cndmask_b32_e32 v2, v2, v5, vcc
	v_mul_lo_u32 v5, v3, v2
	v_add_u32_e32 v3, v5, v3
	v_cmp_ne_u32_e32 vcc, v4, v3
	s_and_saveexec_b64 s[10:11], vcc
	s_xor_b64 s[10:11], exec, s[10:11]
	s_cbranch_execz .LBB0_1823
	s_waitcnt lgkmcnt(0)
	v_mul_u32_u24_e32 v18, 21, v1
	v_mov_b32_e32 v1, 0
	global_load_dword v3, v1, s[100:101] sc1
	s_waitcnt vmcnt(0)
	v_cmp_lt_u32_e32 vcc, v3, v18
	s_and_saveexec_b64 s[12:13], vcc
	s_cbranch_execz .LBB0_1822
	s_mov_b32 s26, 1
	s_mov_b64 s[14:15], 0
	s_branch .LBB0_1813

.LBB0_1823:
	s_andn2_saveexec_b64 s[10:11], s[10:11]
	s_cbranch_execz .LBB0_1843
	s_mov_b64 s[10:11], exec
	buffer_wbl2 sc1
	s_waitcnt lgkmcnt(0)
	v_mul_u32_u24_e32 v18, 21, v1
	s_waitcnt vmcnt(0)
	v_mbcnt_lo_u32_b32 v2, s10, 0
	v_mbcnt_hi_u32_b32 v2, s11, v2
	v_cmp_eq_u32_e32 vcc, 0, v2
	s_and_saveexec_b64 s[12:13], vcc
	s_cbranch_execz .LBB0_1826
	s_bcnt1_i32_b64 s10, s[10:11]
	v_mov_b32_e32 v3, 0x7000
	v_mov_b32_e32 v4, s10
	global_atomic_add v3, v3, v4, s[94:95] offset:1024 sc0

.LBB0_1903:
	s_or_b64 exec, exec, s[12:13]
	v_cvt_f32_u32_e32 v5, v3
	s_waitcnt vmcnt(0)
	v_readfirstlane_b32 s10, v4
	s_add_u32 s8, s8, 0x2400
	s_addc_u32 s9, s9, 0
	v_rcp_iflag_f32_e32 v5, v5
	v_add_u32_e32 v6, s10, v2
	v_mul_f32_e32 v4, 0x4f7ffffe, v5
	v_cvt_u32_f32_e32 v4, v4
	v_sub_u32_e32 v5, 0, v3
	v_mul_lo_u32 v2, v5, v4
	v_mul_hi_u32 v2, v4, v2
	v_add_u32_e32 v2, v4, v2
	v_mul_hi_u32 v2, v6, v2
	v_mul_lo_u32 v4, v2, v3
	v_sub_u32_e32 v4, v6, v4
	v_add_u32_e32 v5, 1, v2
	v_cmp_ge_u32_e32 vcc, v4, v3
	s_nop 1
	v_cndmask_b32_e32 v2, v2, v5, vcc
	v_sub_u32_e32 v5, v4, v3
	v_cndmask_b32_e32 v4, v4, v5, vcc
	v_add_u32_e32 v5, 1, v2
	v_cmp_ge_u32_e32 vcc, v4, v3
	v_add_u32_e32 v4, 1, v6
	s_nop 0
	v_cndmask_b32_e32 v2, v2, v5, vcc
	v_mul_lo_u32 v5, v3, v2
	v_add_u32_e32 v3, v5, v3
	v_cmp_ne_u32_e32 vcc, v4, v3
	s_and_saveexec_b64 s[10:11], vcc
	s_xor_b64 s[10:11], exec, s[10:11]
	s_cbranch_execz .LBB0_1917
	s_waitcnt lgkmcnt(0)
	v_mul_u32_u24_e32 v18, 22, v1
	v_mov_b32_e32 v1, 0
	global_load_dword v3, v1, s[100:101] sc1
	s_waitcnt vmcnt(0)
	v_cmp_lt_u32_e32 vcc, v3, v18
	s_and_saveexec_b64 s[12:13], vcc
	s_cbranch_execz .LBB0_1916
	s_mov_b32 s26, 1
	s_mov_b64 s[14:15], 0
	s_branch .LBB0_1907

.LBB0_1917:
	s_andn2_saveexec_b64 s[10:11], s[10:11]
	s_cbranch_execz .LBB0_1937
	s_mov_b64 s[10:11], exec
	buffer_wbl2 sc1
	s_waitcnt lgkmcnt(0)
	v_mul_u32_u24_e32 v18, 22, v1
	s_waitcnt vmcnt(0)
	v_mbcnt_lo_u32_b32 v2, s10, 0
	v_mbcnt_hi_u32_b32 v2, s11, v2
	v_cmp_eq_u32_e32 vcc, 0, v2
	s_and_saveexec_b64 s[12:13], vcc
	s_cbranch_execz .LBB0_1920
	s_bcnt1_i32_b64 s10, s[10:11]
	v_mov_b32_e32 v3, 0x7000
	v_mov_b32_e32 v4, s10
	global_atomic_add v3, v3, v4, s[94:95] offset:1024 sc0

.LBB0_2000:
	s_or_b64 exec, exec, s[12:13]
	v_cvt_f32_u32_e32 v5, v3
	s_waitcnt vmcnt(0)
	v_readfirstlane_b32 s10, v4
	s_add_u32 s8, s8, 0x2400
	s_addc_u32 s9, s9, 0
	v_rcp_iflag_f32_e32 v5, v5
	v_add_u32_e32 v6, s10, v2
	v_mul_f32_e32 v4, 0x4f7ffffe, v5
	v_cvt_u32_f32_e32 v4, v4
	v_sub_u32_e32 v5, 0, v3
	v_mul_lo_u32 v2, v5, v4
	v_mul_hi_u32 v2, v4, v2
	v_add_u32_e32 v2, v4, v2
	v_mul_hi_u32 v2, v6, v2
	v_mul_lo_u32 v4, v2, v3
	v_sub_u32_e32 v4, v6, v4
	v_add_u32_e32 v5, 1, v2
	v_cmp_ge_u32_e32 vcc, v4, v3
	s_nop 1
	v_cndmask_b32_e32 v2, v2, v5, vcc
	v_sub_u32_e32 v5, v4, v3
	v_cndmask_b32_e32 v4, v4, v5, vcc
	v_add_u32_e32 v5, 1, v2
	v_cmp_ge_u32_e32 vcc, v4, v3
	v_add_u32_e32 v4, 1, v6
	s_nop 0
	v_cndmask_b32_e32 v2, v2, v5, vcc
	v_mul_lo_u32 v5, v3, v2
	v_add_u32_e32 v3, v5, v3
	v_cmp_ne_u32_e32 vcc, v4, v3
	s_and_saveexec_b64 s[10:11], vcc
	s_xor_b64 s[10:11], exec, s[10:11]
	s_cbranch_execz .LBB0_2014
	s_waitcnt lgkmcnt(0)
	v_mul_u32_u24_e32 v18, 23, v1
	v_mov_b32_e32 v1, 0
	global_load_dword v3, v1, s[100:101] sc1
	s_waitcnt vmcnt(0)
	v_cmp_lt_u32_e32 vcc, v3, v18
	s_and_saveexec_b64 s[12:13], vcc
	s_cbranch_execz .LBB0_2013
	s_mov_b32 s26, 1
	s_mov_b64 s[14:15], 0
	s_branch .LBB0_2004

.LBB0_2014:
	s_andn2_saveexec_b64 s[10:11], s[10:11]
	s_cbranch_execz .LBB0_2034
	s_mov_b64 s[10:11], exec
	buffer_wbl2 sc1
	s_waitcnt lgkmcnt(0)
	v_mul_u32_u24_e32 v18, 23, v1
	s_waitcnt vmcnt(0)
	v_mbcnt_lo_u32_b32 v2, s10, 0
	v_mbcnt_hi_u32_b32 v2, s11, v2
	v_cmp_eq_u32_e32 vcc, 0, v2
	s_and_saveexec_b64 s[12:13], vcc
	s_cbranch_execz .LBB0_2017
	s_bcnt1_i32_b64 s10, s[10:11]
	v_mov_b32_e32 v3, 0x7000
	v_mov_b32_e32 v4, s10
	global_atomic_add v3, v3, v4, s[94:95] offset:1024 sc0

.LBB0_2072:
	s_or_b64 exec, exec, s[12:13]
	v_cvt_f32_u32_e32 v5, v3
	s_waitcnt vmcnt(0)
	v_readfirstlane_b32 s10, v4
	s_add_u32 s8, s8, 0x2400
	s_addc_u32 s9, s9, 0
	v_rcp_iflag_f32_e32 v5, v5
	v_add_u32_e32 v6, s10, v2
	v_mul_f32_e32 v4, 0x4f7ffffe, v5
	v_cvt_u32_f32_e32 v4, v4
	v_sub_u32_e32 v5, 0, v3
	v_mul_lo_u32 v2, v5, v4
	v_mul_hi_u32 v2, v4, v2
	v_add_u32_e32 v2, v4, v2
	v_mul_hi_u32 v2, v6, v2
	v_mul_lo_u32 v4, v2, v3
	v_sub_u32_e32 v4, v6, v4
	v_add_u32_e32 v5, 1, v2
	v_cmp_ge_u32_e32 vcc, v4, v3
	s_nop 1
	v_cndmask_b32_e32 v2, v2, v5, vcc
	v_sub_u32_e32 v5, v4, v3
	v_cndmask_b32_e32 v4, v4, v5, vcc
	v_add_u32_e32 v5, 1, v2
	v_cmp_ge_u32_e32 vcc, v4, v3
	v_add_u32_e32 v4, 1, v6
	s_nop 0
	v_cndmask_b32_e32 v2, v2, v5, vcc
	v_mul_lo_u32 v5, v3, v2
	v_add_u32_e32 v3, v5, v3
	v_cmp_ne_u32_e32 vcc, v4, v3
	s_and_saveexec_b64 s[10:11], vcc
	s_xor_b64 s[10:11], exec, s[10:11]
	s_cbranch_execz .LBB0_2086
	s_waitcnt lgkmcnt(0)
	v_mul_u32_u24_e32 v18, 24, v1
	v_mov_b32_e32 v1, 0
	global_load_dword v3, v1, s[100:101] sc1
	s_waitcnt vmcnt(0)
	v_cmp_lt_u32_e32 vcc, v3, v18
	s_and_saveexec_b64 s[12:13], vcc
	s_cbranch_execz .LBB0_2085
	s_mov_b32 s26, 1
	s_mov_b64 s[14:15], 0
	s_branch .LBB0_2076

.LBB0_2086:
	s_andn2_saveexec_b64 s[10:11], s[10:11]
	s_cbranch_execz .LBB0_2106
	s_mov_b64 s[10:11], exec
	buffer_wbl2 sc1
	s_waitcnt lgkmcnt(0)
	v_mul_u32_u24_e32 v18, 24, v1
	s_waitcnt vmcnt(0)
	v_mbcnt_lo_u32_b32 v2, s10, 0
	v_mbcnt_hi_u32_b32 v2, s11, v2
	v_cmp_eq_u32_e32 vcc, 0, v2
	s_and_saveexec_b64 s[12:13], vcc
	s_cbranch_execz .LBB0_2089
	s_bcnt1_i32_b64 s10, s[10:11]
	v_mov_b32_e32 v3, 0x7000
	v_mov_b32_e32 v4, s10
	global_atomic_add v3, v3, v4, s[94:95] offset:1024 sc0

.LBB0_2234:
	s_waitcnt lgkmcnt(0)
	s_barrier
	s_waitcnt vmcnt(0)
	s_waitcnt vmcnt(0)
	s_barrier
	s_mov_b64 s[0:1], exec
	v_readlane_b32 s4, v254, 36
	v_readlane_b32 s5, v254, 37
	s_and_b64 s[4:5], s[0:1], s[4:5]
	s_mov_b64 exec, s[4:5]
	s_cbranch_execz .LBB0_2286
	s_add_u32 s100, s94, 0x7400
	s_addc_u32 s101, s95, 0
	s_add_u32 s4, s94, 0x4200
	s_addc_u32 s5, s95, 0
	s_add_i32 s6, 0, 0x20160
	v_mov_b32_e32 v1, s6
	s_waitcnt vmcnt(0) expcnt(0) lgkmcnt(0)
	ds_read_b32 v3, v1
	s_add_i32 s6, 0, 0x20164
	v_mov_b32_e32 v1, s6
	ds_read_b32 v1, v1
	s_waitcnt lgkmcnt(1)
	v_cmp_ne_u32_e32 vcc, 0, v3
	s_cbranch_vccnz .LBB0_2250
	s_add_u32 s6, s94, 0x4400
	s_addc_u32 s7, s95, 0
	s_add_u32 s8, s94, 0x4500
	s_addc_u32 s9, s95, 0
	s_add_u32 s10, s94, 0x4600
	s_addc_u32 s11, s95, 0
	s_add_u32 s12, s94, 0x4700
	s_addc_u32 s13, s95, 0
	s_add_u32 s14, s94, 0x4800
	s_addc_u32 s15, s95, 0
	s_add_u32 s16, s94, 0x4900
	s_addc_u32 s17, s95, 0
	s_add_u32 s20, s94, 0x4a00
	s_addc_u32 s21, s95, 0
	s_add_u32 s22, s94, 0x4b00
	s_addc_u32 s23, s95, 0
	s_add_u32 s24, s94, 0x4c00
	s_addc_u32 s25, s95, 0
	s_add_u32 s26, s94, 0x4d00
	s_addc_u32 s27, s95, 0
	s_add_u32 s28, s94, 0x4e00
	s_addc_u32 s29, s95, 0
	s_add_u32 s30, s94, 0x4f00
	s_addc_u32 s31, s95, 0
	v_readlane_b32 s38, v254, 0
	s_add_u32 s34, s94, 0x5000
	v_readlane_b32 s39, v254, 1
	s_addc_u32 s35, s95, 0
	s_load_dwordx2 s[42:43], s[38:39], 0x4
	s_add_u32 s36, s94, 0x5100
	s_addc_u32 s37, s95, 0
	s_add_u32 s38, s94, 0x5200
	s_addc_u32 s39, s95, 0
	s_add_u32 s40, s94, 0x5300
	s_waitcnt lgkmcnt(0)
	s_mul_i32 s48, s42, s90
	s_addc_u32 s41, s95, 0
	s_mul_i32 s48, s48, s43
	s_mov_b32 s49, 1
	v_mov_b32_e32 v17, 0
	s_branch .LBB0_2238

.LBB0_2252:
	s_or_b64 exec, exec, s[10:11]
	v_cvt_f32_u32_e32 v5, v3
	s_waitcnt vmcnt(0)
	v_readfirstlane_b32 s8, v4
	s_add_u32 s6, s6, 0x2400
	s_addc_u32 s7, s7, 0
	v_rcp_iflag_f32_e32 v5, v5
	v_add_u32_e32 v6, s8, v2
	v_mul_f32_e32 v4, 0x4f7ffffe, v5
	v_cvt_u32_f32_e32 v4, v4
	v_sub_u32_e32 v5, 0, v3
	v_mul_lo_u32 v2, v5, v4
	v_mul_hi_u32 v2, v4, v2
	v_add_u32_e32 v2, v4, v2
	v_mul_hi_u32 v2, v6, v2
	v_mul_lo_u32 v4, v2, v3
	v_sub_u32_e32 v4, v6, v4
	v_add_u32_e32 v5, 1, v2
	v_cmp_ge_u32_e32 vcc, v4, v3
	s_nop 1
	v_cndmask_b32_e32 v2, v2, v5, vcc
	v_sub_u32_e32 v5, v4, v3
	v_cndmask_b32_e32 v4, v4, v5, vcc
	v_add_u32_e32 v5, 1, v2
	v_cmp_ge_u32_e32 vcc, v4, v3
	v_add_u32_e32 v4, 1, v6
	s_nop 0
	v_cndmask_b32_e32 v2, v2, v5, vcc
	v_mul_lo_u32 v5, v3, v2
	v_add_u32_e32 v3, v5, v3
	v_cmp_ne_u32_e32 vcc, v4, v3
	s_and_saveexec_b64 s[8:9], vcc
	s_xor_b64 s[8:9], exec, s[8:9]
	s_cbranch_execz .LBB0_2266
	s_waitcnt lgkmcnt(0)
	v_mul_u32_u24_e32 v18, 25, v1
	v_mov_b32_e32 v1, 0
	global_load_dword v3, v1, s[100:101] sc1
	s_waitcnt vmcnt(0)
	v_cmp_lt_u32_e32 vcc, v3, v18
	s_and_saveexec_b64 s[10:11], vcc
	s_cbranch_execz .LBB0_2265
	s_mov_b32 s24, 1
	s_mov_b64 s[12:13], 0
	s_branch .LBB0_2256

.LBB0_2258:
	global_load_dword v3, v1, s[100:101] sc1
	s_add_i32 s24, s24, 1
	s_mov_b64 s[20:21], -1
	s_waitcnt vmcnt(0)
	v_cmp_ge_u32_e32 vcc, v3, v18
	s_orn2_b64 s[16:17], vcc, exec
	s_branch .LBB0_2255

.LBB0_2266:
	s_andn2_saveexec_b64 s[8:9], s[8:9]
	s_cbranch_execz .LBB0_2286
	s_mov_b64 s[8:9], exec
	buffer_wbl2 sc1
	s_waitcnt lgkmcnt(0)
	v_mul_u32_u24_e32 v18, 25, v1
	s_waitcnt vmcnt(0)
	v_mbcnt_lo_u32_b32 v2, s8, 0
	v_mbcnt_hi_u32_b32 v2, s9, v2
	v_cmp_eq_u32_e32 vcc, 0, v2
	s_and_saveexec_b64 s[10:11], vcc
	s_cbranch_execz .LBB0_2269
	s_bcnt1_i32_b64 s8, s[8:9]
	v_mov_b32_e32 v3, 0x7000
	v_mov_b32_e32 v4, s8
	global_atomic_add v3, v3, v4, s[94:95] offset:1024 sc0
.LBB0_2269:
	s_or_b64 exec, exec, s[10:11]
	v_cvt_f32_u32_e32 v4, v1
	s_waitcnt vmcnt(0)
	v_readfirstlane_b32 s10, v3
	s_add_u32 s8, s94, 0x7500
	s_addc_u32 s9, s95, 0
	v_rcp_iflag_f32_e32 v4, v4
	v_add_u32_e32 v2, s10, v2
	s_mov_b64 s[12:13], -1
	v_mul_f32_e32 v3, 0x4f7ffffe, v4
	v_cvt_u32_f32_e32 v3, v3
	v_sub_u32_e32 v4, 0, v1
	v_mul_lo_u32 v4, v4, v3
	v_mul_hi_u32 v4, v3, v4
	v_add_u32_e32 v3, v3, v4
	v_mul_hi_u32 v3, v2, v3
	v_mul_lo_u32 v4, v3, v1
	v_sub_u32_e32 v4, v2, v4
	v_add_u32_e32 v5, 1, v3
	v_cmp_ge_u32_e32 vcc, v4, v1
	v_add_u32_e32 v2, 1, v2
	s_nop 0
	v_cndmask_b32_e32 v3, v3, v5, vcc
	v_sub_u32_e32 v5, v4, v1
	v_cndmask_b32_e32 v4, v4, v5, vcc
	v_add_u32_e32 v5, 1, v3
	v_cmp_ge_u32_e32 vcc, v4, v1
	s_nop 1
	v_cndmask_b32_e32 v4, v3, v5, vcc
	v_mul_lo_u32 v3, v1, v4
	v_add_u32_e32 v1, v3, v1
	v_cmp_ne_u32_e32 vcc, v2, v1
	v_mov_b64_e32 v[2:3], s[8:9]
	s_and_saveexec_b64 s[10:11], vcc
	s_cbranch_execz .LBB0_2281
	v_mov_b32_e32 v1, 0
	global_load_dword v2, v1, s[100:101] sc1
	s_mov_b64 s[14:15], 0
	s_waitcnt vmcnt(0)
	v_cmp_lt_u32_e32 vcc, v2, v18
	s_and_saveexec_b64 s[12:13], vcc
	s_cbranch_execz .LBB0_2280
	s_mov_b32 s26, 1
	s_branch .LBB0_2273

.LBB0_2315:
	s_waitcnt vmcnt(0)
	s_waitcnt vmcnt(0)
	s_barrier
	s_mov_b64 s[0:1], exec
	v_readlane_b32 s4, v254, 36
	v_readlane_b32 s5, v254, 37
	s_and_b64 s[4:5], s[0:1], s[4:5]
	s_mov_b64 exec, s[4:5]
	s_cbranch_execz .LBB0_2367
	s_add_u32 s100, s94, 0x7400
	s_addc_u32 s101, s95, 0
	s_add_u32 s4, s94, 0x4200
	s_addc_u32 s5, s95, 0
	s_add_i32 s6, 0, 0x20160
	v_mov_b32_e32 v1, s6
	s_waitcnt vmcnt(0) expcnt(0) lgkmcnt(0)
	ds_read_b32 v3, v1
	s_add_i32 s6, 0, 0x20164
	v_mov_b32_e32 v1, s6
	ds_read_b32 v1, v1
	s_waitcnt lgkmcnt(1)
	v_cmp_ne_u32_e32 vcc, 0, v3
	s_cbranch_vccnz .LBB0_2331
	s_add_u32 s6, s94, 0x4400
	s_addc_u32 s7, s95, 0
	s_add_u32 s8, s94, 0x4500
	s_addc_u32 s9, s95, 0
	s_add_u32 s10, s94, 0x4600
	s_addc_u32 s11, s95, 0
	s_add_u32 s12, s94, 0x4700
	s_addc_u32 s13, s95, 0
	s_add_u32 s14, s94, 0x4800
	s_addc_u32 s15, s95, 0
	s_add_u32 s16, s94, 0x4900
	s_addc_u32 s17, s95, 0
	s_add_u32 s20, s94, 0x4a00
	s_addc_u32 s21, s95, 0
	s_add_u32 s22, s94, 0x4b00
	s_addc_u32 s23, s95, 0
	s_add_u32 s24, s94, 0x4c00
	s_addc_u32 s25, s95, 0
	s_add_u32 s26, s94, 0x4d00
	s_addc_u32 s27, s95, 0
	s_add_u32 s28, s94, 0x4e00
	s_addc_u32 s29, s95, 0
	s_add_u32 s30, s94, 0x4f00
	s_addc_u32 s31, s95, 0
	v_readlane_b32 s38, v254, 0
	s_add_u32 s34, s94, 0x5000
	v_readlane_b32 s39, v254, 1
	s_addc_u32 s35, s95, 0
	s_load_dwordx2 s[42:43], s[38:39], 0x4
	s_add_u32 s36, s94, 0x5100
	s_addc_u32 s37, s95, 0
	s_add_u32 s38, s94, 0x5200
	s_addc_u32 s39, s95, 0
	s_add_u32 s40, s94, 0x5300
	s_waitcnt lgkmcnt(0)
	s_mul_i32 s48, s42, s90
	s_addc_u32 s41, s95, 0
	s_mul_i32 s48, s48, s43
	s_mov_b32 s49, 1
	v_mov_b32_e32 v17, 0
	s_branch .LBB0_2319

.LBB0_2333:
	s_or_b64 exec, exec, s[10:11]
	v_cvt_f32_u32_e32 v5, v3
	s_waitcnt vmcnt(0)
	v_readfirstlane_b32 s8, v4
	s_add_u32 s6, s6, 0x2400
	s_addc_u32 s7, s7, 0
	v_rcp_iflag_f32_e32 v5, v5
	v_add_u32_e32 v6, s8, v2
	v_mul_f32_e32 v4, 0x4f7ffffe, v5
	v_cvt_u32_f32_e32 v4, v4
	v_sub_u32_e32 v5, 0, v3
	v_mul_lo_u32 v2, v5, v4
	v_mul_hi_u32 v2, v4, v2
	v_add_u32_e32 v2, v4, v2
	v_mul_hi_u32 v2, v6, v2
	v_mul_lo_u32 v4, v2, v3
	v_sub_u32_e32 v4, v6, v4
	v_add_u32_e32 v5, 1, v2
	v_cmp_ge_u32_e32 vcc, v4, v3
	s_nop 1
	v_cndmask_b32_e32 v2, v2, v5, vcc
	v_sub_u32_e32 v5, v4, v3
	v_cndmask_b32_e32 v4, v4, v5, vcc
	v_add_u32_e32 v5, 1, v2
	v_cmp_ge_u32_e32 vcc, v4, v3
	v_add_u32_e32 v4, 1, v6
	s_nop 0
	v_cndmask_b32_e32 v2, v2, v5, vcc
	v_mul_lo_u32 v5, v3, v2
	v_add_u32_e32 v3, v5, v3
	v_cmp_ne_u32_e32 vcc, v4, v3
	s_and_saveexec_b64 s[8:9], vcc
	s_xor_b64 s[8:9], exec, s[8:9]
	s_cbranch_execz .LBB0_2347
	s_waitcnt lgkmcnt(0)
	v_mul_u32_u24_e32 v18, 26, v1
	v_mov_b32_e32 v1, 0
	global_load_dword v3, v1, s[100:101] sc1
	s_waitcnt vmcnt(0)
	v_cmp_lt_u32_e32 vcc, v3, v18
	s_and_saveexec_b64 s[10:11], vcc
	s_cbranch_execz .LBB0_2346
	s_mov_b32 s24, 1
	s_mov_b64 s[12:13], 0
	s_branch .LBB0_2337

.LBB0_2347:
	s_andn2_saveexec_b64 s[8:9], s[8:9]
	s_cbranch_execz .LBB0_2367
	s_mov_b64 s[8:9], exec
	buffer_wbl2 sc1
	s_waitcnt lgkmcnt(0)
	v_mul_u32_u24_e32 v18, 26, v1
	s_waitcnt vmcnt(0)
	v_mbcnt_lo_u32_b32 v2, s8, 0
	v_mbcnt_hi_u32_b32 v2, s9, v2
	v_cmp_eq_u32_e32 vcc, 0, v2
	s_and_saveexec_b64 s[10:11], vcc
	s_cbranch_execz .LBB0_2350
	s_bcnt1_i32_b64 s8, s[8:9]
	v_mov_b32_e32 v3, 0x7000
	v_mov_b32_e32 v4, s8
	global_atomic_add v3, v3, v4, s[94:95] offset:1024 sc0

.LBB0_2413:
	s_or_b64 exec, exec, s[10:11]
	v_cvt_f32_u32_e32 v5, v3
	s_waitcnt vmcnt(0)
	v_readfirstlane_b32 s8, v4
	s_add_u32 s6, s6, 0x2400
	s_addc_u32 s7, s7, 0
	v_rcp_iflag_f32_e32 v5, v5
	v_add_u32_e32 v6, s8, v2
	v_mul_f32_e32 v4, 0x4f7ffffe, v5
	v_cvt_u32_f32_e32 v4, v4
	v_sub_u32_e32 v5, 0, v3
	v_mul_lo_u32 v2, v5, v4
	v_mul_hi_u32 v2, v4, v2
	v_add_u32_e32 v2, v4, v2
	v_mul_hi_u32 v2, v6, v2
	v_mul_lo_u32 v4, v2, v3
	v_sub_u32_e32 v4, v6, v4
	v_add_u32_e32 v5, 1, v2
	v_cmp_ge_u32_e32 vcc, v4, v3
	s_nop 1
	v_cndmask_b32_e32 v2, v2, v5, vcc
	v_sub_u32_e32 v5, v4, v3
	v_cndmask_b32_e32 v4, v4, v5, vcc
	v_add_u32_e32 v5, 1, v2
	v_cmp_ge_u32_e32 vcc, v4, v3
	v_add_u32_e32 v4, 1, v6
	s_nop 0
	v_cndmask_b32_e32 v2, v2, v5, vcc
	v_mul_lo_u32 v5, v3, v2
	v_add_u32_e32 v3, v5, v3
	v_cmp_ne_u32_e32 vcc, v4, v3
	s_and_saveexec_b64 s[8:9], vcc
	s_xor_b64 s[8:9], exec, s[8:9]
	s_cbranch_execz .LBB0_2427
	s_waitcnt lgkmcnt(0)
	v_mul_u32_u24_e32 v18, 27, v1
	v_mov_b32_e32 v1, 0
	global_load_dword v3, v1, s[100:101] sc1
	s_waitcnt vmcnt(0)
	v_cmp_lt_u32_e32 vcc, v3, v18
	s_and_saveexec_b64 s[10:11], vcc
	s_cbranch_execz .LBB0_2426
	s_mov_b32 s24, 1
	s_mov_b64 s[12:13], 0
	s_branch .LBB0_2417

.LBB0_2427:
	s_andn2_saveexec_b64 s[8:9], s[8:9]
	s_cbranch_execz .LBB0_2447
	s_mov_b64 s[8:9], exec
	buffer_wbl2 sc1
	s_waitcnt lgkmcnt(0)
	v_mul_u32_u24_e32 v18, 27, v1
	s_waitcnt vmcnt(0)
	v_mbcnt_lo_u32_b32 v2, s8, 0
	v_mbcnt_hi_u32_b32 v2, s9, v2
	v_cmp_eq_u32_e32 vcc, 0, v2
	s_and_saveexec_b64 s[10:11], vcc
	s_cbranch_execz .LBB0_2430
	s_bcnt1_i32_b64 s8, s[8:9]
	v_mov_b32_e32 v3, 0x7000
	v_mov_b32_e32 v4, s8
	global_atomic_add v3, v3, v4, s[94:95] offset:1024 sc0

.LBB0_2489:
	s_waitcnt vmcnt(0)
	s_waitcnt vmcnt(0) lgkmcnt(0)
	s_barrier
	s_mov_b64 s[0:1], exec
	v_readlane_b32 s4, v254, 36
	v_readlane_b32 s5, v254, 37
	s_and_b64 s[4:5], s[0:1], s[4:5]
	s_mov_b64 exec, s[4:5]
	s_cbranch_execz .LBB0_2541
	s_add_u32 s100, s94, 0x7400
	s_addc_u32 s101, s95, 0
	s_add_u32 s4, s94, 0x4200
	s_addc_u32 s5, s95, 0
	s_add_i32 s6, 0, 0x20160
	v_mov_b32_e32 v1, s6
	s_waitcnt vmcnt(0) expcnt(0) lgkmcnt(0)
	ds_read_b32 v3, v1
	s_add_i32 s6, 0, 0x20164
	v_mov_b32_e32 v1, s6
	ds_read_b32 v1, v1
	s_waitcnt lgkmcnt(1)
	v_cmp_ne_u32_e32 vcc, 0, v3
	s_cbranch_vccnz .LBB0_2505
	s_add_u32 s6, s94, 0x4400
	s_addc_u32 s7, s95, 0
	s_add_u32 s8, s94, 0x4500
	s_addc_u32 s9, s95, 0
	s_add_u32 s10, s94, 0x4600
	s_addc_u32 s11, s95, 0
	s_add_u32 s12, s94, 0x4700
	s_addc_u32 s13, s95, 0
	s_add_u32 s14, s94, 0x4800
	s_addc_u32 s15, s95, 0
	s_add_u32 s16, s94, 0x4900
	s_addc_u32 s17, s95, 0
	s_add_u32 s20, s94, 0x4a00
	s_addc_u32 s21, s95, 0
	s_add_u32 s22, s94, 0x4b00
	s_addc_u32 s23, s95, 0
	s_add_u32 s24, s94, 0x4c00
	s_addc_u32 s25, s95, 0
	s_add_u32 s26, s94, 0x4d00
	s_addc_u32 s27, s95, 0
	s_add_u32 s28, s94, 0x4e00
	s_addc_u32 s29, s95, 0
	s_add_u32 s30, s94, 0x4f00
	s_addc_u32 s31, s95, 0
	v_readlane_b32 s38, v254, 0
	s_add_u32 s34, s94, 0x5000
	v_readlane_b32 s39, v254, 1
	s_addc_u32 s35, s95, 0
	s_load_dwordx2 s[42:43], s[38:39], 0x4
	s_add_u32 s36, s94, 0x5100
	s_addc_u32 s37, s95, 0
	s_add_u32 s38, s94, 0x5200
	s_addc_u32 s39, s95, 0
	s_add_u32 s40, s94, 0x5300
	s_waitcnt lgkmcnt(0)
	s_mul_i32 s48, s42, s90
	s_addc_u32 s41, s95, 0
	s_mul_i32 s48, s48, s43
	s_mov_b32 s49, 1
	v_mov_b32_e32 v17, 0
	s_branch .LBB0_2493

.LBB0_2507:
	s_or_b64 exec, exec, s[10:11]
	v_cvt_f32_u32_e32 v5, v3
	s_waitcnt vmcnt(0)
	v_readfirstlane_b32 s8, v4
	s_add_u32 s6, s6, 0x2400
	s_addc_u32 s7, s7, 0
	v_rcp_iflag_f32_e32 v5, v5
	v_add_u32_e32 v6, s8, v2
	v_mul_f32_e32 v4, 0x4f7ffffe, v5
	v_cvt_u32_f32_e32 v4, v4
	v_sub_u32_e32 v5, 0, v3
	v_mul_lo_u32 v2, v5, v4
	v_mul_hi_u32 v2, v4, v2
	v_add_u32_e32 v2, v4, v2
	v_mul_hi_u32 v2, v6, v2
	v_mul_lo_u32 v4, v2, v3
	v_sub_u32_e32 v4, v6, v4
	v_add_u32_e32 v5, 1, v2
	v_cmp_ge_u32_e32 vcc, v4, v3
	s_nop 1
	v_cndmask_b32_e32 v2, v2, v5, vcc
	v_sub_u32_e32 v5, v4, v3
	v_cndmask_b32_e32 v4, v4, v5, vcc
	v_add_u32_e32 v5, 1, v2
	v_cmp_ge_u32_e32 vcc, v4, v3
	v_add_u32_e32 v4, 1, v6
	s_nop 0
	v_cndmask_b32_e32 v2, v2, v5, vcc
	v_mul_lo_u32 v5, v3, v2
	v_add_u32_e32 v3, v5, v3
	v_cmp_ne_u32_e32 vcc, v4, v3
	s_and_saveexec_b64 s[8:9], vcc
	s_xor_b64 s[8:9], exec, s[8:9]
	s_cbranch_execz .LBB0_2521
	s_waitcnt lgkmcnt(0)
	v_mul_u32_u24_e32 v18, 28, v1
	v_mov_b32_e32 v1, 0
	global_load_dword v3, v1, s[100:101] sc1
	s_waitcnt vmcnt(0)
	v_cmp_lt_u32_e32 vcc, v3, v18
	s_and_saveexec_b64 s[10:11], vcc
	s_cbranch_execz .LBB0_2520
	s_mov_b32 s24, 1
	s_mov_b64 s[12:13], 0
	s_branch .LBB0_2511

.LBB0_2521:
	s_andn2_saveexec_b64 s[8:9], s[8:9]
	s_cbranch_execz .LBB0_2541
	s_mov_b64 s[8:9], exec
	buffer_wbl2 sc1
	s_waitcnt lgkmcnt(0)
	v_mul_u32_u24_e32 v18, 28, v1
	s_waitcnt vmcnt(0)
	v_mbcnt_lo_u32_b32 v2, s8, 0
	v_mbcnt_hi_u32_b32 v2, s9, v2
	v_cmp_eq_u32_e32 vcc, 0, v2
	s_and_saveexec_b64 s[10:11], vcc
	s_cbranch_execz .LBB0_2524
	s_bcnt1_i32_b64 s8, s[8:9]
	v_mov_b32_e32 v3, 0x7000
	v_mov_b32_e32 v4, s8
	global_atomic_add v3, v3, v4, s[94:95] offset:1024 sc0

.LBB0_2604:
	s_or_b64 exec, exec, s[10:11]
	v_cvt_f32_u32_e32 v5, v3
	s_waitcnt vmcnt(0)
	v_readfirstlane_b32 s8, v4
	s_add_u32 s6, s6, 0x2400
	s_addc_u32 s7, s7, 0
	v_rcp_iflag_f32_e32 v5, v5
	v_add_u32_e32 v6, s8, v2
	v_mul_f32_e32 v4, 0x4f7ffffe, v5
	v_cvt_u32_f32_e32 v4, v4
	v_sub_u32_e32 v5, 0, v3
	v_mul_lo_u32 v2, v5, v4
	v_mul_hi_u32 v2, v4, v2
	v_add_u32_e32 v2, v4, v2
	v_mul_hi_u32 v2, v6, v2
	v_mul_lo_u32 v4, v2, v3
	v_sub_u32_e32 v4, v6, v4
	v_add_u32_e32 v5, 1, v2
	v_cmp_ge_u32_e32 vcc, v4, v3
	s_nop 1
	v_cndmask_b32_e32 v2, v2, v5, vcc
	v_sub_u32_e32 v5, v4, v3
	v_cndmask_b32_e32 v4, v4, v5, vcc
	v_add_u32_e32 v5, 1, v2
	v_cmp_ge_u32_e32 vcc, v4, v3
	v_add_u32_e32 v4, 1, v6
	s_nop 0
	v_cndmask_b32_e32 v2, v2, v5, vcc
	v_mul_lo_u32 v5, v3, v2
	v_add_u32_e32 v3, v5, v3
	v_cmp_ne_u32_e32 vcc, v4, v3
	s_and_saveexec_b64 s[8:9], vcc
	s_xor_b64 s[8:9], exec, s[8:9]
	s_cbranch_execz .LBB0_2618
	s_waitcnt lgkmcnt(0)
	v_mul_u32_u24_e32 v18, 29, v1
	v_mov_b32_e32 v1, 0
	global_load_dword v3, v1, s[100:101] sc1
	s_waitcnt vmcnt(0)
	v_cmp_lt_u32_e32 vcc, v3, v18
	s_and_saveexec_b64 s[10:11], vcc
	s_cbranch_execz .LBB0_2617
	s_mov_b32 s24, 1
	s_mov_b64 s[12:13], 0
	s_branch .LBB0_2608

.LBB0_2618:
	s_andn2_saveexec_b64 s[8:9], s[8:9]
	s_cbranch_execz .LBB0_2638
	s_mov_b64 s[8:9], exec
	buffer_wbl2 sc1
	s_waitcnt lgkmcnt(0)
	v_mul_u32_u24_e32 v18, 29, v1
	s_waitcnt vmcnt(0)
	v_mbcnt_lo_u32_b32 v2, s8, 0
	v_mbcnt_hi_u32_b32 v2, s9, v2
	v_cmp_eq_u32_e32 vcc, 0, v2
	s_and_saveexec_b64 s[10:11], vcc
	s_cbranch_execz .LBB0_2621
	s_bcnt1_i32_b64 s8, s[8:9]
	v_mov_b32_e32 v3, 0x7000
	v_mov_b32_e32 v4, s8
	global_atomic_add v3, v3, v4, s[94:95] offset:1024 sc0

.LBB0_2684:
	s_or_b64 exec, exec, s[10:11]
	v_cvt_f32_u32_e32 v5, v3
	s_waitcnt vmcnt(0)
	v_readfirstlane_b32 s8, v4
	s_add_u32 s6, s6, 0x2400
	s_addc_u32 s7, s7, 0
	v_rcp_iflag_f32_e32 v5, v5
	v_add_u32_e32 v6, s8, v2
	v_mul_f32_e32 v4, 0x4f7ffffe, v5
	v_cvt_u32_f32_e32 v4, v4
	v_sub_u32_e32 v5, 0, v3
	v_mul_lo_u32 v2, v5, v4
	v_mul_hi_u32 v2, v4, v2
	v_add_u32_e32 v2, v4, v2
	v_mul_hi_u32 v2, v6, v2
	v_mul_lo_u32 v4, v2, v3
	v_sub_u32_e32 v4, v6, v4
	v_add_u32_e32 v5, 1, v2
	v_cmp_ge_u32_e32 vcc, v4, v3
	s_nop 1
	v_cndmask_b32_e32 v2, v2, v5, vcc
	v_sub_u32_e32 v5, v4, v3
	v_cndmask_b32_e32 v4, v4, v5, vcc
	v_add_u32_e32 v5, 1, v2
	v_cmp_ge_u32_e32 vcc, v4, v3
	v_add_u32_e32 v4, 1, v6
	s_nop 0
	v_cndmask_b32_e32 v2, v2, v5, vcc
	v_mul_lo_u32 v5, v3, v2
	v_add_u32_e32 v3, v5, v3
	v_cmp_ne_u32_e32 vcc, v4, v3
	s_and_saveexec_b64 s[8:9], vcc
	s_xor_b64 s[8:9], exec, s[8:9]
	s_cbranch_execz .LBB0_2698
	s_waitcnt lgkmcnt(0)
	v_mul_u32_u24_e32 v18, 30, v1
	v_mov_b32_e32 v1, 0
	global_load_dword v3, v1, s[100:101] sc1
	s_waitcnt vmcnt(0)
	v_cmp_lt_u32_e32 vcc, v3, v18
	s_and_saveexec_b64 s[10:11], vcc
	s_cbranch_execz .LBB0_2697
	s_mov_b32 s24, 1
	s_mov_b64 s[12:13], 0
	s_branch .LBB0_2688

.LBB0_2698:
	s_andn2_saveexec_b64 s[8:9], s[8:9]
	s_cbranch_execz .LBB0_2718
	s_mov_b64 s[8:9], exec
	buffer_wbl2 sc1
	s_waitcnt lgkmcnt(0)
	v_mul_u32_u24_e32 v18, 30, v1
	s_waitcnt vmcnt(0)
	v_mbcnt_lo_u32_b32 v2, s8, 0
	v_mbcnt_hi_u32_b32 v2, s9, v2
	v_cmp_eq_u32_e32 vcc, 0, v2
	s_and_saveexec_b64 s[10:11], vcc
	s_cbranch_execz .LBB0_2701
	s_bcnt1_i32_b64 s8, s[8:9]
	v_mov_b32_e32 v3, 0x7000
	v_mov_b32_e32 v4, s8
	global_atomic_add v3, v3, v4, s[94:95] offset:1024 sc0

.LBB0_2778:
	s_or_b64 exec, exec, s[10:11]
	v_cvt_f32_u32_e32 v5, v3
	s_waitcnt vmcnt(0)
	v_readfirstlane_b32 s8, v4
	s_add_u32 s6, s6, 0x2400
	s_addc_u32 s7, s7, 0
	v_rcp_iflag_f32_e32 v5, v5
	v_add_u32_e32 v6, s8, v2
	v_mul_f32_e32 v4, 0x4f7ffffe, v5
	v_cvt_u32_f32_e32 v4, v4
	v_sub_u32_e32 v5, 0, v3
	v_mul_lo_u32 v2, v5, v4
	v_mul_hi_u32 v2, v4, v2
	v_add_u32_e32 v2, v4, v2
	v_mul_hi_u32 v2, v6, v2
	v_mul_lo_u32 v4, v2, v3
	v_sub_u32_e32 v4, v6, v4
	v_add_u32_e32 v5, 1, v2
	v_cmp_ge_u32_e32 vcc, v4, v3
	s_nop 1
	v_cndmask_b32_e32 v2, v2, v5, vcc
	v_sub_u32_e32 v5, v4, v3
	v_cndmask_b32_e32 v4, v4, v5, vcc
	v_add_u32_e32 v5, 1, v2
	v_cmp_ge_u32_e32 vcc, v4, v3
	v_add_u32_e32 v4, 1, v6
	s_nop 0
	v_cndmask_b32_e32 v2, v2, v5, vcc
	v_mul_lo_u32 v5, v3, v2
	v_add_u32_e32 v3, v5, v3
	v_cmp_ne_u32_e32 vcc, v4, v3
	s_and_saveexec_b64 s[8:9], vcc
	s_xor_b64 s[8:9], exec, s[8:9]
	s_cbranch_execz .LBB0_2792
	s_waitcnt lgkmcnt(0)
	v_mul_u32_u24_e32 v18, 31, v1
	v_mov_b32_e32 v1, 0
	global_load_dword v3, v1, s[100:101] sc1
	s_waitcnt vmcnt(0)
	v_cmp_lt_u32_e32 vcc, v3, v18
	s_and_saveexec_b64 s[10:11], vcc
	s_cbranch_execz .LBB0_2791
	s_mov_b32 s24, 1
	s_mov_b64 s[12:13], 0
	s_branch .LBB0_2782

.LBB0_2792:
	s_andn2_saveexec_b64 s[8:9], s[8:9]
	s_cbranch_execz .LBB0_2812
	s_mov_b64 s[8:9], exec
	buffer_wbl2 sc1
	s_waitcnt lgkmcnt(0)
	v_mul_u32_u24_e32 v18, 31, v1
	s_waitcnt vmcnt(0)
	v_mbcnt_lo_u32_b32 v2, s8, 0
	v_mbcnt_hi_u32_b32 v2, s9, v2
	v_cmp_eq_u32_e32 vcc, 0, v2
	s_and_saveexec_b64 s[10:11], vcc
	s_cbranch_execz .LBB0_2795
	s_bcnt1_i32_b64 s8, s[8:9]
	v_mov_b32_e32 v3, 0x7000
	v_mov_b32_e32 v4, s8
	global_atomic_add v3, v3, v4, s[94:95] offset:1024 sc0

.LBB0_2875:
	s_or_b64 exec, exec, s[10:11]
	v_cvt_f32_u32_e32 v5, v3
	s_waitcnt vmcnt(0)
	v_readfirstlane_b32 s8, v4
	s_add_u32 s6, s6, 0x2400
	s_addc_u32 s7, s7, 0
	v_rcp_iflag_f32_e32 v5, v5
	v_add_u32_e32 v6, s8, v2
	v_mul_f32_e32 v4, 0x4f7ffffe, v5
	v_cvt_u32_f32_e32 v4, v4
	v_sub_u32_e32 v5, 0, v3
	v_mul_lo_u32 v2, v5, v4
	v_mul_hi_u32 v2, v4, v2
	v_add_u32_e32 v2, v4, v2
	v_mul_hi_u32 v2, v6, v2
	v_mul_lo_u32 v4, v2, v3
	v_sub_u32_e32 v4, v6, v4
	v_add_u32_e32 v5, 1, v2
	v_cmp_ge_u32_e32 vcc, v4, v3
	s_nop 1
	v_cndmask_b32_e32 v2, v2, v5, vcc
	v_sub_u32_e32 v5, v4, v3
	v_cndmask_b32_e32 v4, v4, v5, vcc
	v_add_u32_e32 v5, 1, v2
	v_cmp_ge_u32_e32 vcc, v4, v3
	v_add_u32_e32 v4, 1, v6
	s_nop 0
	v_cndmask_b32_e32 v2, v2, v5, vcc
	v_mul_lo_u32 v5, v3, v2
	v_add_u32_e32 v3, v5, v3
	v_cmp_ne_u32_e32 vcc, v4, v3
	s_and_saveexec_b64 s[8:9], vcc
	s_xor_b64 s[8:9], exec, s[8:9]
	s_cbranch_execz .LBB0_2889
	s_waitcnt lgkmcnt(0)
	v_mul_u32_u24_e32 v18, 32, v1
	v_mov_b32_e32 v1, 0
	global_load_dword v3, v1, s[100:101] sc1
	s_waitcnt vmcnt(0)
	v_cmp_lt_u32_e32 vcc, v3, v18
	s_and_saveexec_b64 s[10:11], vcc
	s_cbranch_execz .LBB0_2888
	s_mov_b32 s24, 1
	s_mov_b64 s[12:13], 0
	s_branch .LBB0_2879

.LBB0_2889:
	s_andn2_saveexec_b64 s[8:9], s[8:9]
	s_cbranch_execz .LBB0_2909
	s_mov_b64 s[8:9], exec
	buffer_wbl2 sc1
	s_waitcnt lgkmcnt(0)
	v_mul_u32_u24_e32 v18, 32, v1
	s_waitcnt vmcnt(0)
	v_mbcnt_lo_u32_b32 v2, s8, 0
	v_mbcnt_hi_u32_b32 v2, s9, v2
	v_cmp_eq_u32_e32 vcc, 0, v2
	s_and_saveexec_b64 s[10:11], vcc
	s_cbranch_execz .LBB0_2892
	s_bcnt1_i32_b64 s8, s[8:9]
	v_mov_b32_e32 v3, 0x7000
	v_mov_b32_e32 v4, s8
	global_atomic_add v3, v3, v4, s[94:95] offset:1024 sc0

.LBB0_2947:
	s_or_b64 exec, exec, s[10:11]
	v_cvt_f32_u32_e32 v5, v3
	s_waitcnt vmcnt(0)
	v_readfirstlane_b32 s8, v4
	s_add_u32 s6, s6, 0x2400
	s_addc_u32 s7, s7, 0
	v_rcp_iflag_f32_e32 v5, v5
	v_add_u32_e32 v6, s8, v2
	v_mul_f32_e32 v4, 0x4f7ffffe, v5
	v_cvt_u32_f32_e32 v4, v4
	v_sub_u32_e32 v5, 0, v3
	v_mul_lo_u32 v2, v5, v4
	v_mul_hi_u32 v2, v4, v2
	v_add_u32_e32 v2, v4, v2
	v_mul_hi_u32 v2, v6, v2
	v_mul_lo_u32 v4, v2, v3
	v_sub_u32_e32 v4, v6, v4
	v_add_u32_e32 v5, 1, v2
	v_cmp_ge_u32_e32 vcc, v4, v3
	s_nop 1
	v_cndmask_b32_e32 v2, v2, v5, vcc
	v_sub_u32_e32 v5, v4, v3
	v_cndmask_b32_e32 v4, v4, v5, vcc
	v_add_u32_e32 v5, 1, v2
	v_cmp_ge_u32_e32 vcc, v4, v3
	v_add_u32_e32 v4, 1, v6
	s_nop 0
	v_cndmask_b32_e32 v2, v2, v5, vcc
	v_mul_lo_u32 v5, v3, v2
	v_add_u32_e32 v3, v5, v3
	v_cmp_ne_u32_e32 vcc, v4, v3
	s_and_saveexec_b64 s[8:9], vcc
	s_xor_b64 s[8:9], exec, s[8:9]
	s_cbranch_execz .LBB0_2961
	s_waitcnt lgkmcnt(0)
	v_mul_u32_u24_e32 v18, 33, v1
	v_mov_b32_e32 v1, 0
	global_load_dword v3, v1, s[100:101] sc1
	s_waitcnt vmcnt(0)
	v_cmp_lt_u32_e32 vcc, v3, v18
	s_and_saveexec_b64 s[10:11], vcc
	s_cbranch_execz .LBB0_2960
	s_mov_b32 s24, 1
	s_mov_b64 s[12:13], 0
	s_branch .LBB0_2951

.LBB0_2961:
	s_andn2_saveexec_b64 s[8:9], s[8:9]
	s_cbranch_execz .LBB0_2981
	s_mov_b64 s[8:9], exec
	buffer_wbl2 sc1
	s_waitcnt lgkmcnt(0)
	v_mul_u32_u24_e32 v18, 33, v1
	s_waitcnt vmcnt(0)
	v_mbcnt_lo_u32_b32 v2, s8, 0
	v_mbcnt_hi_u32_b32 v2, s9, v2
	v_cmp_eq_u32_e32 vcc, 0, v2
	s_and_saveexec_b64 s[10:11], vcc
	s_cbranch_execz .LBB0_2964
	s_bcnt1_i32_b64 s8, s[8:9]
	v_mov_b32_e32 v3, 0x7000
	v_mov_b32_e32 v4, s8
	global_atomic_add v3, v3, v4, s[94:95] offset:1024 sc0

.LBB0_3045:
	s_or_b64 exec, exec, s[10:11]
	v_cvt_f32_u32_e32 v5, v3
	s_waitcnt vmcnt(0)
	v_readfirstlane_b32 s8, v4
	s_add_u32 s6, s6, 0x2400
	s_addc_u32 s7, s7, 0
	v_rcp_iflag_f32_e32 v5, v5
	v_add_u32_e32 v6, s8, v2
	v_mul_f32_e32 v4, 0x4f7ffffe, v5
	v_cvt_u32_f32_e32 v4, v4
	v_sub_u32_e32 v5, 0, v3
	v_mul_lo_u32 v2, v5, v4
	v_mul_hi_u32 v2, v4, v2
	v_add_u32_e32 v2, v4, v2
	v_mul_hi_u32 v2, v6, v2
	v_mul_lo_u32 v4, v2, v3
	v_sub_u32_e32 v4, v6, v4
	v_add_u32_e32 v5, 1, v2
	v_cmp_ge_u32_e32 vcc, v4, v3
	s_nop 1
	v_cndmask_b32_e32 v2, v2, v5, vcc
	v_sub_u32_e32 v5, v4, v3
	v_cndmask_b32_e32 v4, v4, v5, vcc
	v_add_u32_e32 v5, 1, v2
	v_cmp_ge_u32_e32 vcc, v4, v3
	v_add_u32_e32 v4, 1, v6
	s_nop 0
	v_cndmask_b32_e32 v2, v2, v5, vcc
	v_mul_lo_u32 v5, v3, v2
	v_add_u32_e32 v3, v5, v3
	v_cmp_ne_u32_e32 vcc, v4, v3
	s_and_saveexec_b64 s[8:9], vcc
	s_xor_b64 s[8:9], exec, s[8:9]
	s_cbranch_execz .LBB0_3059
	s_waitcnt lgkmcnt(0)
	v_mul_u32_u24_e32 v18, 34, v1
	v_mov_b32_e32 v1, 0
	global_load_dword v3, v1, s[100:101] sc1
	s_waitcnt vmcnt(0)
	v_cmp_lt_u32_e32 vcc, v3, v18
	s_and_saveexec_b64 s[10:11], vcc
	s_cbranch_execz .LBB0_3058
	s_mov_b32 s24, 1
	s_mov_b64 s[12:13], 0
	s_branch .LBB0_3049

.LBB0_3059:
	s_andn2_saveexec_b64 s[8:9], s[8:9]
	s_cbranch_execz .LBB0_3079
	s_mov_b64 s[8:9], exec
	buffer_wbl2 sc1
	s_waitcnt lgkmcnt(0)
	v_mul_u32_u24_e32 v18, 34, v1
	s_waitcnt vmcnt(0)
	v_mbcnt_lo_u32_b32 v2, s8, 0
	v_mbcnt_hi_u32_b32 v2, s9, v2
	v_cmp_eq_u32_e32 vcc, 0, v2
	s_and_saveexec_b64 s[10:11], vcc
	s_cbranch_execz .LBB0_3062
	s_bcnt1_i32_b64 s8, s[8:9]
	v_mov_b32_e32 v3, 0x7000
	v_mov_b32_e32 v4, s8
	global_atomic_add v3, v3, v4, s[94:95] offset:1024 sc0

.LBB0_3108:
	s_or_b64 exec, exec, s[10:11]
	v_cvt_f32_u32_e32 v5, v3
	s_waitcnt vmcnt(0)
	v_readfirstlane_b32 s8, v4
	s_add_u32 s6, s6, 0x2400
	s_addc_u32 s7, s7, 0
	v_rcp_iflag_f32_e32 v5, v5
	v_add_u32_e32 v6, s8, v2
	v_mul_f32_e32 v4, 0x4f7ffffe, v5
	v_cvt_u32_f32_e32 v4, v4
	v_sub_u32_e32 v5, 0, v3
	v_mul_lo_u32 v2, v5, v4
	v_mul_hi_u32 v2, v4, v2
	v_add_u32_e32 v2, v4, v2
	v_mul_hi_u32 v2, v6, v2
	v_mul_lo_u32 v4, v2, v3
	v_sub_u32_e32 v4, v6, v4
	v_add_u32_e32 v5, 1, v2
	v_cmp_ge_u32_e32 vcc, v4, v3
	s_nop 1
	v_cndmask_b32_e32 v2, v2, v5, vcc
	v_sub_u32_e32 v5, v4, v3
	v_cndmask_b32_e32 v4, v4, v5, vcc
	v_add_u32_e32 v5, 1, v2
	v_cmp_ge_u32_e32 vcc, v4, v3
	v_add_u32_e32 v4, 1, v6
	s_nop 0
	v_cndmask_b32_e32 v2, v2, v5, vcc
	v_mul_lo_u32 v5, v3, v2
	v_add_u32_e32 v3, v5, v3
	v_cmp_ne_u32_e32 vcc, v4, v3
	s_and_saveexec_b64 s[8:9], vcc
	s_xor_b64 s[8:9], exec, s[8:9]
	s_cbranch_execz .LBB0_3122
	s_waitcnt lgkmcnt(0)
	v_mul_u32_u24_e32 v18, 35, v1
	v_mov_b32_e32 v1, 0
	global_load_dword v3, v1, s[100:101] sc1
	s_waitcnt vmcnt(0)
	v_cmp_lt_u32_e32 vcc, v3, v18
	s_and_saveexec_b64 s[10:11], vcc
	s_cbranch_execz .LBB0_3121
	s_mov_b32 s24, 1
	s_mov_b64 s[12:13], 0
	s_branch .LBB0_3112

.LBB0_3122:
	s_andn2_saveexec_b64 s[8:9], s[8:9]
	s_cbranch_execz .LBB0_3142
	s_mov_b64 s[8:9], exec
	buffer_wbl2 sc1
	s_waitcnt lgkmcnt(0)
	v_mul_u32_u24_e32 v18, 35, v1
	s_waitcnt vmcnt(0)
	v_mbcnt_lo_u32_b32 v2, s8, 0
	v_mbcnt_hi_u32_b32 v2, s9, v2
	v_cmp_eq_u32_e32 vcc, 0, v2
	s_and_saveexec_b64 s[10:11], vcc
	s_cbranch_execz .LBB0_3125
	s_bcnt1_i32_b64 s8, s[8:9]
	v_mov_b32_e32 v3, 0x7000
	v_mov_b32_e32 v4, s8
	global_atomic_add v3, v3, v4, s[94:95] offset:1024 sc0

.LBB0_3151:
	s_barrier
	s_waitcnt vmcnt(0)
	s_waitcnt vmcnt(0)
	s_barrier
	s_mov_b64 s[0:1], exec
	v_readlane_b32 s4, v254, 36
	v_readlane_b32 s5, v254, 37
	s_and_b64 s[4:5], s[0:1], s[4:5]
	s_mov_b64 exec, s[4:5]
	s_cbranch_execz .LBB0_3203
	s_add_u32 s100, s94, 0x7400
	s_addc_u32 s101, s95, 0
	s_add_u32 s4, s94, 0x4200
	s_addc_u32 s5, s95, 0
	s_add_i32 s6, 0, 0x20160
	v_mov_b32_e32 v1, s6
	s_waitcnt vmcnt(0) expcnt(0) lgkmcnt(0)
	ds_read_b32 v3, v1
	s_add_i32 s6, 0, 0x20164
	v_mov_b32_e32 v1, s6
	ds_read_b32 v1, v1
	s_waitcnt lgkmcnt(1)
	v_cmp_ne_u32_e32 vcc, 0, v3
	s_cbranch_vccnz .LBB0_3167
	s_add_u32 s6, s94, 0x4400
	s_addc_u32 s7, s95, 0
	s_add_u32 s8, s94, 0x4500
	s_addc_u32 s9, s95, 0
	s_add_u32 s10, s94, 0x4600
	s_addc_u32 s11, s95, 0
	s_add_u32 s12, s94, 0x4700
	s_addc_u32 s13, s95, 0
	s_add_u32 s14, s94, 0x4800
	s_addc_u32 s15, s95, 0
	s_add_u32 s16, s94, 0x4900
	s_addc_u32 s17, s95, 0
	s_add_u32 s18, s94, 0x4a00
	s_addc_u32 s19, s95, 0
	s_add_u32 s20, s94, 0x4b00
	s_addc_u32 s21, s95, 0
	s_add_u32 s22, s94, 0x4c00
	s_addc_u32 s23, s95, 0
	s_add_u32 s24, s94, 0x4d00
	s_addc_u32 s25, s95, 0
	s_add_u32 s26, s94, 0x4e00
	s_addc_u32 s27, s95, 0
	s_add_u32 s28, s94, 0x4f00
	s_addc_u32 s29, s95, 0
	v_readlane_b32 s36, v254, 0
	s_add_u32 s30, s94, 0x5000
	v_readlane_b32 s37, v254, 1
	s_addc_u32 s31, s95, 0
	s_load_dwordx2 s[40:41], s[36:37], 0x4
	s_add_u32 s34, s94, 0x5100
	s_addc_u32 s35, s95, 0
	s_add_u32 s36, s94, 0x5200
	s_addc_u32 s37, s95, 0
	s_add_u32 s38, s94, 0x5300
	s_waitcnt lgkmcnt(0)
	s_mul_i32 s46, s40, s90
	s_addc_u32 s39, s95, 0
	s_mul_i32 s46, s46, s41
	s_mov_b32 s47, 1
	v_mov_b32_e32 v17, 0
	s_branch .LBB0_3155

.LBB0_3169:
	s_or_b64 exec, exec, s[10:11]
	v_cvt_f32_u32_e32 v5, v3
	s_waitcnt vmcnt(0)
	v_readfirstlane_b32 s8, v4
	s_add_u32 s6, s6, 0x2400
	s_addc_u32 s7, s7, 0
	v_rcp_iflag_f32_e32 v5, v5
	v_add_u32_e32 v6, s8, v2
	v_mul_f32_e32 v4, 0x4f7ffffe, v5
	v_cvt_u32_f32_e32 v4, v4
	v_sub_u32_e32 v5, 0, v3
	v_mul_lo_u32 v2, v5, v4
	v_mul_hi_u32 v2, v4, v2
	v_add_u32_e32 v2, v4, v2
	v_mul_hi_u32 v2, v6, v2
	v_mul_lo_u32 v4, v2, v3
	v_sub_u32_e32 v4, v6, v4
	v_add_u32_e32 v5, 1, v2
	v_cmp_ge_u32_e32 vcc, v4, v3
	s_nop 1
	v_cndmask_b32_e32 v2, v2, v5, vcc
	v_sub_u32_e32 v5, v4, v3
	v_cndmask_b32_e32 v4, v4, v5, vcc
	v_add_u32_e32 v5, 1, v2
	v_cmp_ge_u32_e32 vcc, v4, v3
	v_add_u32_e32 v4, 1, v6
	s_nop 0
	v_cndmask_b32_e32 v2, v2, v5, vcc
	v_mul_lo_u32 v5, v3, v2
	v_add_u32_e32 v3, v5, v3
	v_cmp_ne_u32_e32 vcc, v4, v3
	s_and_saveexec_b64 s[8:9], vcc
	s_xor_b64 s[8:9], exec, s[8:9]
	s_cbranch_execz .LBB0_3183
	s_waitcnt lgkmcnt(0)
	v_mul_u32_u24_e32 v18, 36, v1
	v_mov_b32_e32 v1, 0
	global_load_dword v3, v1, s[100:101] sc1
	s_waitcnt vmcnt(0)
	v_cmp_lt_u32_e32 vcc, v3, v18
	s_and_saveexec_b64 s[10:11], vcc
	s_cbranch_execz .LBB0_3182
	s_mov_b32 s22, 1
	s_mov_b64 s[12:13], 0
	s_branch .LBB0_3173

.LBB0_3175:
	global_load_dword v3, v1, s[100:101] sc1
	s_add_i32 s22, s22, 1
	s_mov_b64 s[18:19], -1
	s_waitcnt vmcnt(0)
	v_cmp_ge_u32_e32 vcc, v3, v18
	s_orn2_b64 s[16:17], vcc, exec
	s_branch .LBB0_3172

.LBB0_3183:
	s_andn2_saveexec_b64 s[8:9], s[8:9]
	s_cbranch_execz .LBB0_3203
	s_mov_b64 s[8:9], exec
	buffer_wbl2 sc1
	s_waitcnt lgkmcnt(0)
	v_mul_u32_u24_e32 v18, 36, v1
	s_waitcnt vmcnt(0)
	v_mbcnt_lo_u32_b32 v2, s8, 0
	v_mbcnt_hi_u32_b32 v2, s9, v2
	v_cmp_eq_u32_e32 vcc, 0, v2
	s_and_saveexec_b64 s[10:11], vcc
	s_cbranch_execz .LBB0_3186
	s_bcnt1_i32_b64 s8, s[8:9]
	v_mov_b32_e32 v3, 0x7000
	v_mov_b32_e32 v4, s8
	global_atomic_add v3, v3, v4, s[94:95] offset:1024 sc0
.LBB0_3186:
	s_or_b64 exec, exec, s[10:11]
	v_cvt_f32_u32_e32 v4, v1
	s_waitcnt vmcnt(0)
	v_readfirstlane_b32 s10, v3
	s_add_u32 s8, s94, 0x7500
	s_addc_u32 s9, s95, 0
	v_rcp_iflag_f32_e32 v4, v4
	v_add_u32_e32 v2, s10, v2
	s_mov_b64 s[12:13], -1
	v_mul_f32_e32 v3, 0x4f7ffffe, v4
	v_cvt_u32_f32_e32 v3, v3
	v_sub_u32_e32 v4, 0, v1
	v_mul_lo_u32 v4, v4, v3
	v_mul_hi_u32 v4, v3, v4
	v_add_u32_e32 v3, v3, v4
	v_mul_hi_u32 v3, v2, v3
	v_mul_lo_u32 v4, v3, v1
	v_sub_u32_e32 v4, v2, v4
	v_add_u32_e32 v5, 1, v3
	v_cmp_ge_u32_e32 vcc, v4, v1
	v_add_u32_e32 v2, 1, v2
	s_nop 0
	v_cndmask_b32_e32 v3, v3, v5, vcc
	v_sub_u32_e32 v5, v4, v1
	v_cndmask_b32_e32 v4, v4, v5, vcc
	v_add_u32_e32 v5, 1, v3
	v_cmp_ge_u32_e32 vcc, v4, v1
	s_nop 1
	v_cndmask_b32_e32 v4, v3, v5, vcc
	v_mul_lo_u32 v3, v1, v4
	v_add_u32_e32 v1, v3, v1
	v_cmp_ne_u32_e32 vcc, v2, v1
	v_mov_b64_e32 v[2:3], s[8:9]
	s_and_saveexec_b64 s[10:11], vcc
	s_cbranch_execz .LBB0_3198
	v_mov_b32_e32 v1, 0
	global_load_dword v2, v1, s[100:101] sc1
	s_mov_b64 s[14:15], 0
	s_waitcnt vmcnt(0)
	v_cmp_lt_u32_e32 vcc, v2, v18
	s_and_saveexec_b64 s[12:13], vcc
	s_cbranch_execz .LBB0_3197
	s_mov_b32 s24, 1
	s_branch .LBB0_3190

.LBB0_3192:
	global_load_dword v2, v1, s[100:101] sc1
	s_add_i32 s24, s24, 1
	s_mov_b64 s[18:19], -1
	s_waitcnt vmcnt(0)
	v_cmp_ge_u32_e32 vcc, v2, v18
	s_orn2_b64 s[22:23], vcc, exec
	s_branch .LBB0_3189

.LBB0_3232:
	s_waitcnt vmcnt(0)
	s_waitcnt vmcnt(0)
	s_barrier
	s_mov_b64 s[0:1], exec
	v_readlane_b32 s4, v254, 36
	v_readlane_b32 s5, v254, 37
	s_and_b64 s[4:5], s[0:1], s[4:5]
	s_mov_b64 exec, s[4:5]
	s_cbranch_execz .LBB0_3284
	s_add_u32 s100, s94, 0x7400
	s_addc_u32 s101, s95, 0
	s_add_u32 s4, s94, 0x4200
	s_addc_u32 s5, s95, 0
	s_add_i32 s6, 0, 0x20160
	v_mov_b32_e32 v1, s6
	s_waitcnt vmcnt(0) expcnt(0) lgkmcnt(0)
	ds_read_b32 v3, v1
	s_add_i32 s6, 0, 0x20164
	v_mov_b32_e32 v1, s6
	ds_read_b32 v1, v1
	s_waitcnt lgkmcnt(1)
	v_cmp_ne_u32_e32 vcc, 0, v3
	s_cbranch_vccnz .LBB0_3248
	s_add_u32 s6, s94, 0x4400
	s_addc_u32 s7, s95, 0
	s_add_u32 s8, s94, 0x4500
	s_addc_u32 s9, s95, 0
	s_add_u32 s10, s94, 0x4600
	s_addc_u32 s11, s95, 0
	s_add_u32 s12, s94, 0x4700
	s_addc_u32 s13, s95, 0
	s_add_u32 s14, s94, 0x4800
	s_addc_u32 s15, s95, 0
	s_add_u32 s16, s94, 0x4900
	s_addc_u32 s17, s95, 0
	s_add_u32 s18, s94, 0x4a00
	s_addc_u32 s19, s95, 0
	s_add_u32 s20, s94, 0x4b00
	s_addc_u32 s21, s95, 0
	s_add_u32 s22, s94, 0x4c00
	s_addc_u32 s23, s95, 0
	s_add_u32 s24, s94, 0x4d00
	s_addc_u32 s25, s95, 0
	s_add_u32 s26, s94, 0x4e00
	s_addc_u32 s27, s95, 0
	s_add_u32 s28, s94, 0x4f00
	s_addc_u32 s29, s95, 0
	v_readlane_b32 s36, v254, 0
	s_add_u32 s30, s94, 0x5000
	v_readlane_b32 s37, v254, 1
	s_addc_u32 s31, s95, 0
	s_load_dwordx2 s[40:41], s[36:37], 0x4
	s_add_u32 s34, s94, 0x5100
	s_addc_u32 s35, s95, 0
	s_add_u32 s36, s94, 0x5200
	s_addc_u32 s37, s95, 0
	s_add_u32 s38, s94, 0x5300
	s_waitcnt lgkmcnt(0)
	s_mul_i32 s46, s40, s90
	s_addc_u32 s39, s95, 0
	s_mul_i32 s46, s46, s41
	s_mov_b32 s47, 1
	v_mov_b32_e32 v17, 0
	s_branch .LBB0_3236

.LBB0_3250:
	s_or_b64 exec, exec, s[10:11]
	v_cvt_f32_u32_e32 v5, v3
	s_waitcnt vmcnt(0)
	v_readfirstlane_b32 s8, v4
	s_add_u32 s6, s6, 0x2400
	s_addc_u32 s7, s7, 0
	v_rcp_iflag_f32_e32 v5, v5
	v_add_u32_e32 v6, s8, v2
	v_mul_f32_e32 v4, 0x4f7ffffe, v5
	v_cvt_u32_f32_e32 v4, v4
	v_sub_u32_e32 v5, 0, v3
	v_mul_lo_u32 v2, v5, v4
	v_mul_hi_u32 v2, v4, v2
	v_add_u32_e32 v2, v4, v2
	v_mul_hi_u32 v2, v6, v2
	v_mul_lo_u32 v4, v2, v3
	v_sub_u32_e32 v4, v6, v4
	v_add_u32_e32 v5, 1, v2
	v_cmp_ge_u32_e32 vcc, v4, v3
	s_nop 1
	v_cndmask_b32_e32 v2, v2, v5, vcc
	v_sub_u32_e32 v5, v4, v3
	v_cndmask_b32_e32 v4, v4, v5, vcc
	v_add_u32_e32 v5, 1, v2
	v_cmp_ge_u32_e32 vcc, v4, v3
	v_add_u32_e32 v4, 1, v6
	s_nop 0
	v_cndmask_b32_e32 v2, v2, v5, vcc
	v_mul_lo_u32 v5, v3, v2
	v_add_u32_e32 v3, v5, v3
	v_cmp_ne_u32_e32 vcc, v4, v3
	s_and_saveexec_b64 s[8:9], vcc
	s_xor_b64 s[8:9], exec, s[8:9]
	s_cbranch_execz .LBB0_3264
	s_waitcnt lgkmcnt(0)
	v_mul_u32_u24_e32 v18, 37, v1
	v_mov_b32_e32 v1, 0
	global_load_dword v3, v1, s[100:101] sc1
	s_waitcnt vmcnt(0)
	v_cmp_lt_u32_e32 vcc, v3, v18
	s_and_saveexec_b64 s[10:11], vcc
	s_cbranch_execz .LBB0_3263
	s_mov_b32 s22, 1
	s_mov_b64 s[12:13], 0
	s_branch .LBB0_3254

.LBB0_3264:
	s_andn2_saveexec_b64 s[8:9], s[8:9]
	s_cbranch_execz .LBB0_3284
	s_mov_b64 s[8:9], exec
	buffer_wbl2 sc1
	s_waitcnt lgkmcnt(0)
	v_mul_u32_u24_e32 v18, 37, v1
	s_waitcnt vmcnt(0)
	v_mbcnt_lo_u32_b32 v2, s8, 0
	v_mbcnt_hi_u32_b32 v2, s9, v2
	v_cmp_eq_u32_e32 vcc, 0, v2
	s_and_saveexec_b64 s[10:11], vcc
	s_cbranch_execz .LBB0_3267
	s_bcnt1_i32_b64 s8, s[8:9]
	v_mov_b32_e32 v3, 0x7000
	v_mov_b32_e32 v4, s8
	global_atomic_add v3, v3, v4, s[94:95] offset:1024 sc0

.LBB0_3330:
	s_or_b64 exec, exec, s[10:11]
	v_cvt_f32_u32_e32 v5, v3
	s_waitcnt vmcnt(0)
	v_readfirstlane_b32 s8, v4
	s_add_u32 s6, s6, 0x2400
	s_addc_u32 s7, s7, 0
	v_rcp_iflag_f32_e32 v5, v5
	v_add_u32_e32 v6, s8, v2
	v_mul_f32_e32 v4, 0x4f7ffffe, v5
	v_cvt_u32_f32_e32 v4, v4
	v_sub_u32_e32 v5, 0, v3
	v_mul_lo_u32 v2, v5, v4
	v_mul_hi_u32 v2, v4, v2
	v_add_u32_e32 v2, v4, v2
	v_mul_hi_u32 v2, v6, v2
	v_mul_lo_u32 v4, v2, v3
	v_sub_u32_e32 v4, v6, v4
	v_add_u32_e32 v5, 1, v2
	v_cmp_ge_u32_e32 vcc, v4, v3
	s_nop 1
	v_cndmask_b32_e32 v2, v2, v5, vcc
	v_sub_u32_e32 v5, v4, v3
	v_cndmask_b32_e32 v4, v4, v5, vcc
	v_add_u32_e32 v5, 1, v2
	v_cmp_ge_u32_e32 vcc, v4, v3
	v_add_u32_e32 v4, 1, v6
	s_nop 0
	v_cndmask_b32_e32 v2, v2, v5, vcc
	v_mul_lo_u32 v5, v3, v2
	v_add_u32_e32 v3, v5, v3
	v_cmp_ne_u32_e32 vcc, v4, v3
	s_and_saveexec_b64 s[8:9], vcc
	s_xor_b64 s[8:9], exec, s[8:9]
	s_cbranch_execz .LBB0_3344
	s_waitcnt lgkmcnt(0)
	v_mul_u32_u24_e32 v18, 38, v1
	v_mov_b32_e32 v1, 0
	global_load_dword v3, v1, s[100:101] sc1
	s_waitcnt vmcnt(0)
	v_cmp_lt_u32_e32 vcc, v3, v18
	s_and_saveexec_b64 s[10:11], vcc
	s_cbranch_execz .LBB0_3343
	s_mov_b32 s22, 1
	s_mov_b64 s[12:13], 0
	s_branch .LBB0_3334

.LBB0_3344:
	s_andn2_saveexec_b64 s[8:9], s[8:9]
	s_cbranch_execz .LBB0_3364
	s_mov_b64 s[8:9], exec
	buffer_wbl2 sc1
	s_waitcnt lgkmcnt(0)
	v_mul_u32_u24_e32 v18, 38, v1
	s_waitcnt vmcnt(0)
	v_mbcnt_lo_u32_b32 v2, s8, 0
	v_mbcnt_hi_u32_b32 v2, s9, v2
	v_cmp_eq_u32_e32 vcc, 0, v2
	s_and_saveexec_b64 s[10:11], vcc
	s_cbranch_execz .LBB0_3347
	s_bcnt1_i32_b64 s8, s[8:9]
	v_mov_b32_e32 v3, 0x7000
	v_mov_b32_e32 v4, s8
	global_atomic_add v3, v3, v4, s[94:95] offset:1024 sc0

.LBB0_3406:
	s_waitcnt vmcnt(0)
	s_waitcnt vmcnt(0) lgkmcnt(0)
	s_barrier
	s_mov_b64 s[0:1], exec
	v_readlane_b32 s4, v254, 36
	v_readlane_b32 s5, v254, 37
	s_and_b64 s[4:5], s[0:1], s[4:5]
	s_mov_b64 exec, s[4:5]
	s_cbranch_execz .LBB0_3458
	s_add_u32 s100, s94, 0x7400
	s_addc_u32 s101, s95, 0
	s_add_u32 s4, s94, 0x4200
	s_addc_u32 s5, s95, 0
	s_add_i32 s3, 0, 0x20160
	v_mov_b32_e32 v1, s3
	s_waitcnt vmcnt(0) expcnt(0) lgkmcnt(0)
	ds_read_b32 v3, v1
	s_add_i32 s3, 0, 0x20164
	v_mov_b32_e32 v1, s3
	ds_read_b32 v1, v1
	s_waitcnt lgkmcnt(1)
	v_cmp_ne_u32_e32 vcc, 0, v3
	s_cbranch_vccnz .LBB0_3422
	s_add_u32 s6, s94, 0x4400
	s_addc_u32 s7, s95, 0
	s_add_u32 s8, s94, 0x4500
	s_addc_u32 s9, s95, 0
	s_add_u32 s10, s94, 0x4600
	s_addc_u32 s11, s95, 0
	s_add_u32 s12, s94, 0x4700
	s_addc_u32 s13, s95, 0
	s_add_u32 s14, s94, 0x4800
	s_addc_u32 s15, s95, 0
	s_add_u32 s16, s94, 0x4900
	s_addc_u32 s17, s95, 0
	s_add_u32 s18, s94, 0x4a00
	s_addc_u32 s19, s95, 0
	s_add_u32 s20, s94, 0x4b00
	s_addc_u32 s21, s95, 0
	s_add_u32 s22, s94, 0x4c00
	s_addc_u32 s23, s95, 0
	s_add_u32 s24, s94, 0x4d00
	s_addc_u32 s25, s95, 0
	s_add_u32 s26, s94, 0x4e00
	s_addc_u32 s27, s95, 0
	s_add_u32 s28, s94, 0x4f00
	s_addc_u32 s29, s95, 0
	v_readlane_b32 s36, v254, 0
	s_add_u32 s30, s94, 0x5000
	v_readlane_b32 s37, v254, 1
	s_addc_u32 s31, s95, 0
	s_load_dwordx2 s[40:41], s[36:37], 0x4
	s_add_u32 s34, s94, 0x5100
	s_addc_u32 s35, s95, 0
	s_add_u32 s36, s94, 0x5200
	s_addc_u32 s37, s95, 0
	s_add_u32 s38, s94, 0x5300
	s_waitcnt lgkmcnt(0)
	s_mul_i32 s3, s40, s90
	s_addc_u32 s39, s95, 0
	s_mul_i32 s3, s3, s41
	s_mov_b32 s46, 1
	v_mov_b32_e32 v17, 0
	s_branch .LBB0_3410

.LBB0_3424:
	s_or_b64 exec, exec, s[10:11]
	v_cvt_f32_u32_e32 v5, v3
	s_waitcnt vmcnt(0)
	v_readfirstlane_b32 s3, v4
	s_add_u32 s6, s6, 0x2400
	s_addc_u32 s7, s7, 0
	v_rcp_iflag_f32_e32 v5, v5
	v_add_u32_e32 v6, s3, v2
	v_mul_f32_e32 v4, 0x4f7ffffe, v5
	v_cvt_u32_f32_e32 v4, v4
	v_sub_u32_e32 v5, 0, v3
	v_mul_lo_u32 v2, v5, v4
	v_mul_hi_u32 v2, v4, v2
	v_add_u32_e32 v2, v4, v2
	v_mul_hi_u32 v2, v6, v2
	v_mul_lo_u32 v4, v2, v3
	v_sub_u32_e32 v4, v6, v4
	v_add_u32_e32 v5, 1, v2
	v_cmp_ge_u32_e32 vcc, v4, v3
	s_nop 1
	v_cndmask_b32_e32 v2, v2, v5, vcc
	v_sub_u32_e32 v5, v4, v3
	v_cndmask_b32_e32 v4, v4, v5, vcc
	v_add_u32_e32 v5, 1, v2
	v_cmp_ge_u32_e32 vcc, v4, v3
	v_add_u32_e32 v4, 1, v6
	s_nop 0
	v_cndmask_b32_e32 v2, v2, v5, vcc
	v_mul_lo_u32 v5, v3, v2
	v_add_u32_e32 v3, v5, v3
	v_cmp_ne_u32_e32 vcc, v4, v3
	s_and_saveexec_b64 s[8:9], vcc
	s_xor_b64 s[8:9], exec, s[8:9]
	s_cbranch_execz .LBB0_3438
	s_waitcnt lgkmcnt(0)
	v_mul_u32_u24_e32 v18, 39, v1
	v_mov_b32_e32 v1, 0
	global_load_dword v3, v1, s[100:101] sc1
	s_waitcnt vmcnt(0)
	v_cmp_lt_u32_e32 vcc, v3, v18
	s_and_saveexec_b64 s[10:11], vcc
	s_cbranch_execz .LBB0_3437
	s_mov_b32 s3, 1
	s_mov_b64 s[12:13], 0
	s_branch .LBB0_3428

.LBB0_3430:
	global_load_dword v3, v1, s[100:101] sc1
	s_add_i32 s3, s3, 1
	s_mov_b64 s[18:19], -1
	s_waitcnt vmcnt(0)
	v_cmp_ge_u32_e32 vcc, v3, v18
	s_orn2_b64 s[16:17], vcc, exec
	s_branch .LBB0_3427

.LBB0_3438:
	s_andn2_saveexec_b64 s[8:9], s[8:9]
	s_cbranch_execz .LBB0_3458
	s_mov_b64 s[8:9], exec
	buffer_wbl2 sc1
	s_waitcnt lgkmcnt(0)
	v_mul_u32_u24_e32 v18, 39, v1
	s_waitcnt vmcnt(0)
	v_mbcnt_lo_u32_b32 v2, s8, 0
	v_mbcnt_hi_u32_b32 v2, s9, v2
	v_cmp_eq_u32_e32 vcc, 0, v2
	s_and_saveexec_b64 s[10:11], vcc
	s_cbranch_execz .LBB0_3441
	s_bcnt1_i32_b64 s3, s[8:9]
	v_mov_b32_e32 v3, 0x7000
	v_mov_b32_e32 v4, s3
	global_atomic_add v3, v3, v4, s[94:95] offset:1024 sc0
.LBB0_3441:
	s_or_b64 exec, exec, s[10:11]
	v_cvt_f32_u32_e32 v4, v1
	s_waitcnt vmcnt(0)
	v_readfirstlane_b32 s3, v3
	s_add_u32 s8, s94, 0x7500
	s_addc_u32 s9, s95, 0
	v_rcp_iflag_f32_e32 v4, v4
	v_add_u32_e32 v2, s3, v2
	s_mov_b64 s[12:13], -1
	v_mul_f32_e32 v3, 0x4f7ffffe, v4
	v_cvt_u32_f32_e32 v3, v3
	v_sub_u32_e32 v4, 0, v1
	v_mul_lo_u32 v4, v4, v3
	v_mul_hi_u32 v4, v3, v4
	v_add_u32_e32 v3, v3, v4
	v_mul_hi_u32 v3, v2, v3
	v_mul_lo_u32 v4, v3, v1
	v_sub_u32_e32 v4, v2, v4
	v_add_u32_e32 v5, 1, v3
	v_cmp_ge_u32_e32 vcc, v4, v1
	v_add_u32_e32 v2, 1, v2
	s_nop 0
	v_cndmask_b32_e32 v3, v3, v5, vcc
	v_sub_u32_e32 v5, v4, v1
	v_cndmask_b32_e32 v4, v4, v5, vcc
	v_add_u32_e32 v5, 1, v3
	v_cmp_ge_u32_e32 vcc, v4, v1
	s_nop 1
	v_cndmask_b32_e32 v4, v3, v5, vcc
	v_mul_lo_u32 v3, v1, v4
	v_add_u32_e32 v1, v3, v1
	v_cmp_ne_u32_e32 vcc, v2, v1
	v_mov_b64_e32 v[2:3], s[8:9]
	s_and_saveexec_b64 s[10:11], vcc
	s_cbranch_execz .LBB0_3453
	v_mov_b32_e32 v1, 0
	global_load_dword v2, v1, s[100:101] sc1
	s_mov_b64 s[14:15], 0
	s_waitcnt vmcnt(0)
	v_cmp_lt_u32_e32 vcc, v2, v18
	s_and_saveexec_b64 s[12:13], vcc
	s_cbranch_execz .LBB0_3452
	s_mov_b32 s3, 1
	s_branch .LBB0_3445

.LBB0_3447:
	global_load_dword v2, v1, s[100:101] sc1
	s_add_i32 s3, s3, 1
	s_mov_b64 s[18:19], -1
	s_waitcnt vmcnt(0)
	v_cmp_ge_u32_e32 vcc, v2, v18
	s_orn2_b64 s[22:23], vcc, exec
	s_branch .LBB0_3444

.LBB0_3503:
	s_waitcnt vmcnt(0)
	s_waitcnt vmcnt(0)
	s_barrier
	s_mov_b64 s[0:1], exec
	v_readlane_b32 s2, v254, 36
	v_readlane_b32 s3, v254, 37
	s_and_b64 s[2:3], s[0:1], s[2:3]
	s_mov_b64 exec, s[2:3]
	s_cbranch_execz .LBB0_3556
	s_add_u32 s100, s94, 0x7400
	s_addc_u32 s101, s95, 0
	s_add_u32 s2, s94, 0x4200
	s_addc_u32 s3, s95, 0
	s_add_i32 s4, 0, 0x20160
	v_mov_b32_e32 v1, s4
	s_waitcnt vmcnt(0) expcnt(0) lgkmcnt(0)
	ds_read_b32 v3, v1
	s_add_i32 s4, 0, 0x20164
	v_mov_b32_e32 v1, s4
	ds_read_b32 v1, v1
	s_waitcnt lgkmcnt(1)
	v_cmp_ne_u32_e32 vcc, 0, v3
	s_cbranch_vccnz .LBB0_3520
	s_add_u32 s4, s94, 0x4400
	s_addc_u32 s5, s95, 0
	s_add_u32 s6, s94, 0x4500
	s_addc_u32 s7, s95, 0
	s_add_u32 s8, s94, 0x4600
	s_addc_u32 s9, s95, 0
	s_add_u32 s10, s94, 0x4700
	s_addc_u32 s11, s95, 0
	s_add_u32 s12, s94, 0x4800
	s_addc_u32 s13, s95, 0
	s_add_u32 s14, s94, 0x4900
	s_addc_u32 s15, s95, 0
	s_add_u32 s16, s94, 0x4a00
	s_addc_u32 s17, s95, 0
	s_add_u32 s18, s94, 0x4b00
	s_addc_u32 s19, s95, 0
	s_add_u32 s20, s94, 0x4c00
	s_addc_u32 s21, s95, 0
	s_add_u32 s22, s94, 0x4d00
	s_addc_u32 s23, s95, 0
	s_add_u32 s24, s94, 0x4e00
	s_addc_u32 s25, s95, 0
	s_add_u32 s26, s94, 0x4f00
	s_addc_u32 s27, s95, 0
	v_readlane_b32 s34, v254, 0
	s_add_u32 s28, s94, 0x5000
	v_readlane_b32 s35, v254, 1
	s_addc_u32 s29, s95, 0
	s_load_dwordx2 s[38:39], s[34:35], 0x4
	s_add_u32 s30, s94, 0x5100
	s_addc_u32 s31, s95, 0
	s_add_u32 s34, s94, 0x5200
	s_addc_u32 s35, s95, 0
	s_add_u32 s36, s94, 0x5300
	s_waitcnt lgkmcnt(0)
	s_mul_i32 s44, s38, s90
	s_addc_u32 s37, s95, 0
	s_mul_i32 s44, s44, s39
	s_mov_b32 s45, 1
	v_mov_b32_e32 v17, 0
	s_branch .LBB0_3508

.LBB0_3522:
	s_or_b64 exec, exec, s[8:9]
	v_cvt_f32_u32_e32 v5, v3
	s_waitcnt vmcnt(0)
	v_readfirstlane_b32 s6, v4
	s_add_u32 s4, s4, 0x2400
	s_addc_u32 s5, s5, 0
	v_rcp_iflag_f32_e32 v5, v5
	v_add_u32_e32 v6, s6, v2
	v_mul_f32_e32 v4, 0x4f7ffffe, v5
	v_cvt_u32_f32_e32 v4, v4
	v_sub_u32_e32 v5, 0, v3
	v_mul_lo_u32 v2, v5, v4
	v_mul_hi_u32 v2, v4, v2
	v_add_u32_e32 v2, v4, v2
	v_mul_hi_u32 v2, v6, v2
	v_mul_lo_u32 v4, v2, v3
	v_sub_u32_e32 v4, v6, v4
	v_add_u32_e32 v5, 1, v2
	v_cmp_ge_u32_e32 vcc, v4, v3
	s_nop 1
	v_cndmask_b32_e32 v2, v2, v5, vcc
	v_sub_u32_e32 v5, v4, v3
	v_cndmask_b32_e32 v4, v4, v5, vcc
	v_add_u32_e32 v5, 1, v2
	v_cmp_ge_u32_e32 vcc, v4, v3
	v_add_u32_e32 v4, 1, v6
	s_nop 0
	v_cndmask_b32_e32 v2, v2, v5, vcc
	v_mul_lo_u32 v5, v3, v2
	v_add_u32_e32 v3, v5, v3
	v_cmp_ne_u32_e32 vcc, v4, v3
	s_and_saveexec_b64 s[6:7], vcc
	s_xor_b64 s[6:7], exec, s[6:7]
	s_cbranch_execz .LBB0_3536
	s_waitcnt lgkmcnt(0)
	v_mul_u32_u24_e32 v18, 40, v1
	v_mov_b32_e32 v1, 0
	global_load_dword v3, v1, s[100:101] sc1
	s_waitcnt vmcnt(0)
	v_cmp_lt_u32_e32 vcc, v3, v18
	s_and_saveexec_b64 s[8:9], vcc
	s_cbranch_execz .LBB0_3535
	s_mov_b32 s20, 1
	s_mov_b64 s[10:11], 0
	s_branch .LBB0_3526

.LBB0_3528:
	global_load_dword v3, v1, s[100:101] sc1
	s_add_i32 s20, s20, 1
	s_mov_b64 s[16:17], -1
	s_waitcnt vmcnt(0)
	v_cmp_ge_u32_e32 vcc, v3, v18
	s_orn2_b64 s[14:15], vcc, exec
	s_branch .LBB0_3525

.LBB0_3536:
	s_andn2_saveexec_b64 s[6:7], s[6:7]
	s_cbranch_execz .LBB0_3556
	s_mov_b64 s[6:7], exec
	buffer_wbl2 sc1
	s_waitcnt lgkmcnt(0)
	v_mul_u32_u24_e32 v18, 40, v1
	s_waitcnt vmcnt(0)
	v_mbcnt_lo_u32_b32 v2, s6, 0
	v_mbcnt_hi_u32_b32 v2, s7, v2
	v_cmp_eq_u32_e32 vcc, 0, v2
	s_and_saveexec_b64 s[8:9], vcc
	s_cbranch_execz .LBB0_3539
	s_bcnt1_i32_b64 s6, s[6:7]
	v_mov_b32_e32 v3, 0x7000
	v_mov_b32_e32 v4, s6
	global_atomic_add v3, v3, v4, s[94:95] offset:1024 sc0
.LBB0_3539:
	s_or_b64 exec, exec, s[8:9]
	v_cvt_f32_u32_e32 v4, v1
	s_waitcnt vmcnt(0)
	v_readfirstlane_b32 s8, v3
	s_add_u32 s6, s94, 0x7500
	s_addc_u32 s7, s95, 0
	v_rcp_iflag_f32_e32 v4, v4
	v_add_u32_e32 v2, s8, v2
	s_mov_b64 s[10:11], -1
	v_mul_f32_e32 v3, 0x4f7ffffe, v4
	v_cvt_u32_f32_e32 v3, v3
	v_sub_u32_e32 v4, 0, v1
	v_mul_lo_u32 v4, v4, v3
	v_mul_hi_u32 v4, v3, v4
	v_add_u32_e32 v3, v3, v4
	v_mul_hi_u32 v3, v2, v3
	v_mul_lo_u32 v4, v3, v1
	v_sub_u32_e32 v4, v2, v4
	v_add_u32_e32 v5, 1, v3
	v_cmp_ge_u32_e32 vcc, v4, v1
	v_add_u32_e32 v2, 1, v2
	s_nop 0
	v_cndmask_b32_e32 v3, v3, v5, vcc
	v_sub_u32_e32 v5, v4, v1
	v_cndmask_b32_e32 v4, v4, v5, vcc
	v_add_u32_e32 v5, 1, v3
	v_cmp_ge_u32_e32 vcc, v4, v1
	s_nop 1
	v_cndmask_b32_e32 v4, v3, v5, vcc
	v_mul_lo_u32 v3, v1, v4
	v_add_u32_e32 v1, v3, v1
	v_cmp_ne_u32_e32 vcc, v2, v1
	v_mov_b64_e32 v[2:3], s[6:7]
	s_and_saveexec_b64 s[8:9], vcc
	s_cbranch_execz .LBB0_3551
	v_mov_b32_e32 v1, 0
	global_load_dword v2, v1, s[100:101] sc1
	s_mov_b64 s[12:13], 0
	s_waitcnt vmcnt(0)
	v_cmp_lt_u32_e32 vcc, v2, v18
	s_and_saveexec_b64 s[10:11], vcc
	s_cbranch_execz .LBB0_3550
	s_mov_b32 s22, 1
	s_branch .LBB0_3543

.LBB0_3545:
	global_load_dword v2, v1, s[100:101] sc1
	s_add_i32 s22, s22, 1
	s_mov_b64 s[16:17], -1
	s_waitcnt vmcnt(0)
	v_cmp_ge_u32_e32 vcc, v2, v18
	s_orn2_b64 s[20:21], vcc, exec
	s_branch .LBB0_3542

.LBB0_3574:
	s_branch .LBB0_3627
	s_waitcnt vmcnt(0)
	s_waitcnt vmcnt(0)
	s_barrier
	s_mov_b64 s[0:1], exec
	v_readlane_b32 s2, v254, 36
	v_readlane_b32 s3, v254, 37
	s_and_b64 s[2:3], s[0:1], s[2:3]
	s_mov_b64 exec, s[2:3]
	s_cbranch_execz .LBB0_3626
	s_add_u32 s100, s94, 0x7400
	s_addc_u32 s101, s95, 0
	s_add_u32 s2, s94, 0x4200
	s_addc_u32 s3, s95, 0
	s_add_i32 s4, 0, 0x20160
	v_mov_b32_e32 v0, s4
	s_waitcnt vmcnt(0) expcnt(0) lgkmcnt(0)
	ds_read_b32 v2, v0
	s_add_i32 s4, 0, 0x20164
	v_mov_b32_e32 v0, s4
	ds_read_b32 v0, v0
	s_waitcnt lgkmcnt(1)
	v_cmp_ne_u32_e32 vcc, 0, v2
	s_cbranch_vccnz .LBB0_3590
	s_add_u32 s4, s94, 0x4400
	s_addc_u32 s5, s95, 0
	s_add_u32 s6, s94, 0x4500
	s_addc_u32 s7, s95, 0
	s_add_u32 s8, s94, 0x4600
	s_addc_u32 s9, s95, 0
	s_add_u32 s10, s94, 0x4700
	s_addc_u32 s11, s95, 0
	s_add_u32 s12, s94, 0x4800
	s_addc_u32 s13, s95, 0
	s_add_u32 s14, s94, 0x4900
	s_addc_u32 s15, s95, 0
	s_add_u32 s16, s94, 0x4a00
	s_addc_u32 s17, s95, 0
	s_add_u32 s18, s94, 0x4b00
	s_addc_u32 s19, s95, 0
	s_add_u32 s20, s94, 0x4c00
	s_addc_u32 s21, s95, 0
	s_add_u32 s22, s94, 0x4d00
	s_addc_u32 s23, s95, 0
	s_add_u32 s24, s94, 0x4e00
	s_addc_u32 s25, s95, 0
	s_add_u32 s26, s94, 0x4f00
	s_addc_u32 s27, s95, 0
	v_readlane_b32 s34, v254, 0
	s_add_u32 s28, s94, 0x5000
	v_readlane_b32 s35, v254, 1
	s_addc_u32 s29, s95, 0
	s_load_dwordx2 s[38:39], s[34:35], 0x4
	s_add_u32 s30, s94, 0x5100
	s_addc_u32 s31, s95, 0
	s_add_u32 s34, s94, 0x5200
	s_addc_u32 s35, s95, 0
	s_add_u32 s36, s94, 0x5300
	s_waitcnt lgkmcnt(0)
	s_mul_i32 s44, s38, s90
	s_addc_u32 s37, s95, 0
	s_mul_i32 s44, s44, s39
	s_mov_b32 s45, 1
	v_mov_b32_e32 v16, 0
	s_branch .LBB0_3578

.LBB0_3592:
	s_or_b64 exec, exec, s[8:9]
	v_cvt_f32_u32_e32 v4, v2
	s_waitcnt vmcnt(0)
	v_readfirstlane_b32 s6, v3
	s_add_u32 s4, s4, 0x2400
	s_addc_u32 s5, s5, 0
	v_rcp_iflag_f32_e32 v4, v4
	v_add_u32_e32 v5, s6, v1
	v_mul_f32_e32 v3, 0x4f7ffffe, v4
	v_cvt_u32_f32_e32 v3, v3
	v_sub_u32_e32 v4, 0, v2
	v_mul_lo_u32 v1, v4, v3
	v_mul_hi_u32 v1, v3, v1
	v_add_u32_e32 v1, v3, v1
	v_mul_hi_u32 v1, v5, v1
	v_mul_lo_u32 v3, v1, v2
	v_sub_u32_e32 v3, v5, v3
	v_add_u32_e32 v4, 1, v1
	v_cmp_ge_u32_e32 vcc, v3, v2
	s_nop 1
	v_cndmask_b32_e32 v1, v1, v4, vcc
	v_sub_u32_e32 v4, v3, v2
	v_cndmask_b32_e32 v3, v3, v4, vcc
	v_add_u32_e32 v4, 1, v1
	v_cmp_ge_u32_e32 vcc, v3, v2
	v_add_u32_e32 v3, 1, v5
	s_nop 0
	v_cndmask_b32_e32 v1, v1, v4, vcc
	v_mul_lo_u32 v4, v2, v1
	v_add_u32_e32 v2, v4, v2
	v_cmp_ne_u32_e32 vcc, v3, v2
	s_and_saveexec_b64 s[6:7], vcc
	s_xor_b64 s[6:7], exec, s[6:7]
	s_cbranch_execz .LBB0_3606
	s_waitcnt lgkmcnt(0)
	v_mul_u32_u24_e32 v18, 41, v0
	v_mov_b32_e32 v0, 0
	global_load_dword v2, v0, s[100:101] sc1
	s_waitcnt vmcnt(0)
	v_cmp_lt_u32_e32 vcc, v2, v18
	s_and_saveexec_b64 s[8:9], vcc
	s_cbranch_execz .LBB0_3605
	s_mov_b32 s20, 1
	s_mov_b64 s[10:11], 0
	s_branch .LBB0_3596

.LBB0_3598:
	global_load_dword v2, v0, s[100:101] sc1
	s_add_i32 s20, s20, 1
	s_mov_b64 s[16:17], -1
	s_waitcnt vmcnt(0)
	v_cmp_ge_u32_e32 vcc, v2, v18
	s_orn2_b64 s[14:15], vcc, exec
	s_branch .LBB0_3595

.LBB0_3606:
	s_andn2_saveexec_b64 s[6:7], s[6:7]
	s_cbranch_execz .LBB0_3626
	s_mov_b64 s[6:7], exec
	buffer_wbl2 sc1
	s_waitcnt lgkmcnt(0)
	v_mul_u32_u24_e32 v18, 41, v0
	s_waitcnt vmcnt(0)
	v_mbcnt_lo_u32_b32 v1, s6, 0
	v_mbcnt_hi_u32_b32 v1, s7, v1
	v_cmp_eq_u32_e32 vcc, 0, v1
	s_and_saveexec_b64 s[8:9], vcc
	s_cbranch_execz .LBB0_3609
	s_bcnt1_i32_b64 s6, s[6:7]
	v_mov_b32_e32 v2, 0x7000
	v_mov_b32_e32 v3, s6
	global_atomic_add v2, v2, v3, s[94:95] offset:1024 sc0
.LBB0_3609:
	s_or_b64 exec, exec, s[8:9]
	v_cvt_f32_u32_e32 v3, v0
	s_waitcnt vmcnt(0)
	v_readfirstlane_b32 s8, v2
	s_add_u32 s6, s94, 0x7500
	s_addc_u32 s7, s95, 0
	v_rcp_iflag_f32_e32 v3, v3
	v_add_u32_e32 v1, s8, v1
	s_mov_b64 s[10:11], -1
	v_mul_f32_e32 v2, 0x4f7ffffe, v3
	v_cvt_u32_f32_e32 v2, v2
	v_sub_u32_e32 v3, 0, v0
	v_mul_lo_u32 v3, v3, v2
	v_mul_hi_u32 v3, v2, v3
	v_add_u32_e32 v2, v2, v3
	v_mul_hi_u32 v2, v1, v2
	v_mul_lo_u32 v3, v2, v0
	v_sub_u32_e32 v3, v1, v3
	v_add_u32_e32 v4, 1, v2
	v_cmp_ge_u32_e32 vcc, v3, v0
	v_add_u32_e32 v1, 1, v1
	s_nop 0
	v_cndmask_b32_e32 v2, v2, v4, vcc
	v_sub_u32_e32 v4, v3, v0
	v_cndmask_b32_e32 v3, v3, v4, vcc
	v_add_u32_e32 v4, 1, v2
	v_cmp_ge_u32_e32 vcc, v3, v0
	s_nop 1
	v_cndmask_b32_e32 v2, v2, v4, vcc
	v_mul_lo_u32 v3, v0, v2
	v_add_u32_e32 v0, v3, v0
	v_cmp_ne_u32_e32 vcc, v1, v0
	v_mov_b64_e32 v[0:1], s[6:7]
	s_and_saveexec_b64 s[8:9], vcc
	s_cbranch_execz .LBB0_3621
	v_mov_b32_e32 v0, 0
	global_load_dword v1, v0, s[100:101] sc1
	s_mov_b64 s[12:13], 0
	s_waitcnt vmcnt(0)
	v_cmp_lt_u32_e32 vcc, v1, v18
	s_and_saveexec_b64 s[10:11], vcc
	s_cbranch_execz .LBB0_3620
	s_mov_b32 s22, 1
	s_branch .LBB0_3613

.LBB0_3615:
	global_load_dword v1, v0, s[100:101] sc1
	s_add_i32 s22, s22, 1
	s_mov_b64 s[16:17], -1
	s_waitcnt vmcnt(0)
	v_cmp_ge_u32_e32 vcc, v1, v18
	s_orn2_b64 s[20:21], vcc, exec
	s_branch .LBB0_3612

	.amdhsa_kernel _Z10hybrid_fwd4Args
		.amdhsa_group_segment_fixed_size 0
		.amdhsa_private_segment_fixed_size 0
		.amdhsa_kernarg_size 536
		.amdhsa_user_sgpr_count 2
		.amdhsa_user_sgpr_dispatch_ptr 0
		.amdhsa_user_sgpr_queue_ptr 0
		.amdhsa_user_sgpr_kernarg_segment_ptr 1
		.amdhsa_user_sgpr_dispatch_id 0
		.amdhsa_user_sgpr_kernarg_preload_length 0
		.amdhsa_user_sgpr_kernarg_preload_offset 0
		.amdhsa_user_sgpr_private_segment_size 0
		.amdhsa_uses_dynamic_stack 0
		.amdhsa_enable_private_segment 0
		.amdhsa_system_sgpr_workgroup_id_x 1
		.amdhsa_system_sgpr_workgroup_id_y 0
		.amdhsa_system_sgpr_workgroup_id_z 0
		.amdhsa_system_sgpr_workgroup_info 0
		.amdhsa_system_vgpr_workitem_id 0
		.amdhsa_next_free_vgpr 255
		.amdhsa_next_free_sgpr 102
		.amdhsa_accum_offset 256
		.amdhsa_reserve_vcc 1
		.amdhsa_float_round_mode_32 0
		.amdhsa_float_round_mode_16_64 0
		.amdhsa_float_denorm_mode_32 3
		.amdhsa_float_denorm_mode_16_64 3
		.amdhsa_dx10_clamp 1
		.amdhsa_ieee_mode 1
		.amdhsa_fp16_overflow 0
		.amdhsa_tg_split 0
		.amdhsa_exception_fp_ieee_invalid_op 0
		.amdhsa_exception_fp_denorm_src 0
		.amdhsa_exception_fp_ieee_div_zero 0
		.amdhsa_exception_fp_ieee_overflow 0
		.amdhsa_exception_fp_ieee_underflow 0
		.amdhsa_exception_fp_ieee_inexact 0
		.amdhsa_exception_int_div_zero 0
	.end_amdhsa_kernel

amdhsa.kernels:
  - .agpr_count:     0
    .args:
      - .offset:         0
        .size:           280
        .value_kind:     by_value
      - .offset:         280
        .size:           4
        .value_kind:     hidden_block_count_x
      - .offset:         284
        .size:           4
        .value_kind:     hidden_block_count_y
      - .offset:         288
        .size:           4
        .value_kind:     hidden_block_count_z
      - .offset:         292
        .size:           2
        .value_kind:     hidden_group_size_x
      - .offset:         294
        .size:           2
        .value_kind:     hidden_group_size_y
      - .offset:         296
        .size:           2
        .value_kind:     hidden_group_size_z
      - .offset:         298
        .size:           2
        .value_kind:     hidden_remainder_x
      - .offset:         300
        .size:           2
        .value_kind:     hidden_remainder_y
      - .offset:         302
        .size:           2
        .value_kind:     hidden_remainder_z
      - .offset:         320
        .size:           8
        .value_kind:     hidden_global_offset_x
      - .offset:         328
        .size:           8
        .value_kind:     hidden_global_offset_y
      - .offset:         336
        .size:           8
        .value_kind:     hidden_global_offset_z
      - .offset:         344
        .size:           2
        .value_kind:     hidden_grid_dims
      - .offset:         400
        .size:           4
        .value_kind:     hidden_dynamic_lds_size
    .group_segment_fixed_size: 0
    .kernarg_segment_align: 8
    .kernarg_segment_size: 536
    .language:       OpenCL C
    .language_version:
      - 2
      - 0
    .max_flat_workgroup_size: 512
    .name:           _Z10hybrid_fwd4Args
    .private_segment_fixed_size: 0
    .sgpr_count:     108
    .sgpr_spill_count: 62
    .symbol:         _Z10hybrid_fwd4Args.kd
    .uniform_work_group_size: 1
    .uses_dynamic_stack: false
    .vgpr_count:     255
    .vgpr_spill_count: 0
    .wavefront_size: 64
